# every global store made write-through (sc1) and the L2 writeback (buffer_wbl2) removed from the grid barrier: publish = sc1 stores + drained vmcnt(0) + arrival atomic; consumers keep the agent-scope i
# speedup vs baseline: 1.0077x; 1.0060x over previous
.LBB0_22:
	global_load_dword v16, v[6:7], off
	v_lshl_add_u64 v[18:19], v[6:7], 0, s[20:21]
	s_add_i32 s23, s44, s22
	global_load_dword v58, v[18:19], off
	v_mov_b32_e32 v21, s23
	v_lshl_add_u64 v[18:19], v[18:19], 0, s[20:21]
	ds_read_b128 v[22:25], v21
	ds_read_b128 v[26:29], v21 offset:16
	ds_read_b128 v[30:33], v21 offset:32
	ds_read_b128 v[34:37], v21 offset:48
	global_load_dword v60, v[18:19], off
	v_lshl_add_u64 v[18:19], v[18:19], 0, s[20:21]
	ds_read_b128 v[38:41], v21 offset:64
	ds_read_b128 v[42:45], v21 offset:80
	ds_read_b128 v[46:49], v21 offset:96
	ds_read_b128 v[50:53], v21 offset:112
	ds_read_b128 v[54:57], v21 offset:128
	global_load_dword v62, v[18:19], off
	v_lshl_add_u64 v[18:19], v[18:19], 0, s[20:21]
	global_load_dword v64, v[18:19], off
	v_lshl_add_u64 v[18:19], v[18:19], 0, s[20:21]
	global_load_dword v68, v[18:19], off
	v_lshl_add_u64 v[18:19], v[18:19], 0, s[20:21]
	global_load_dword v70, v[18:19], off
	v_lshl_add_u64 v[18:19], v[18:19], 0, s[20:21]
	s_addk_i32 s22, 0x400
	v_lshl_add_u64 v[6:7], v[6:7], 0, s[12:13]
	s_cmpk_eq_i32 s22, 0x1000
	s_waitcnt vmcnt(6) lgkmcnt(8)
	v_pk_fma_f32 v[10:11], v[16:17], v[22:23], v[10:11] op_sel_hi:[0,1,1]
	v_pk_fma_f32 v[14:15], v[16:17], v[24:25], v[14:15] op_sel_hi:[0,1,1]
	s_waitcnt lgkmcnt(7)
	v_pk_fma_f32 v[12:13], v[16:17], v[26:27], v[12:13] op_sel_hi:[0,1,1]
	v_pk_fma_f32 v[22:23], v[16:17], v[28:29], v[8:9] op_sel_hi:[0,1,1]
	global_load_dword v16, v[18:19], off
	v_lshl_add_u64 v[18:19], v[18:19], 0, s[20:21]
	s_waitcnt vmcnt(6) lgkmcnt(6)
	v_pk_fma_f32 v[26:27], v[58:59], v[30:31], v[10:11] op_sel_hi:[0,1,1]
	ds_read_b128 v[8:11], v21 offset:144
	global_load_dword v72, v[18:19], off
	v_pk_fma_f32 v[28:29], v[58:59], v[32:33], v[14:15] op_sel_hi:[0,1,1]
	s_waitcnt lgkmcnt(6)
	v_pk_fma_f32 v[30:31], v[58:59], v[34:35], v[12:13] op_sel_hi:[0,1,1]
	v_pk_fma_f32 v[32:33], v[58:59], v[36:37], v[22:23] op_sel_hi:[0,1,1]
	ds_read_b128 v[12:15], v21 offset:160
	ds_read_b128 v[22:25], v21 offset:176
	s_waitcnt vmcnt(6) lgkmcnt(7)
	v_pk_fma_f32 v[34:35], v[60:61], v[38:39], v[26:27] op_sel_hi:[0,1,1]
	v_pk_fma_f32 v[36:37], v[60:61], v[40:41], v[28:29] op_sel_hi:[0,1,1]
	ds_read_b128 v[26:29], v21 offset:192
	s_waitcnt lgkmcnt(7)
	v_pk_fma_f32 v[38:39], v[60:61], v[42:43], v[30:31] op_sel_hi:[0,1,1]
	v_pk_fma_f32 v[40:41], v[60:61], v[44:45], v[32:33] op_sel_hi:[0,1,1]
	ds_read_b128 v[30:33], v21 offset:208
	s_waitcnt vmcnt(5) lgkmcnt(7)
	v_pk_fma_f32 v[46:47], v[62:63], v[46:47], v[34:35] op_sel_hi:[0,1,1]
	v_pk_fma_f32 v[48:49], v[62:63], v[48:49], v[36:37] op_sel_hi:[0,1,1]
	ds_read_b128 v[34:37], v21 offset:224
	s_waitcnt lgkmcnt(7)
	v_pk_fma_f32 v[50:51], v[62:63], v[50:51], v[38:39] op_sel_hi:[0,1,1]
	v_pk_fma_f32 v[52:53], v[62:63], v[52:53], v[40:41] op_sel_hi:[0,1,1]
	ds_read_b128 v[38:41], v21 offset:240
	ds_read_b128 v[42:45], v21 offset:256
	s_waitcnt vmcnt(4) lgkmcnt(8)
	v_pk_fma_f32 v[54:55], v[64:65], v[54:55], v[46:47] op_sel_hi:[0,1,1]
	v_pk_fma_f32 v[56:57], v[64:65], v[56:57], v[48:49] op_sel_hi:[0,1,1]
	s_waitcnt lgkmcnt(7)
	v_pk_fma_f32 v[50:51], v[64:65], v[8:9], v[50:51] op_sel_hi:[0,1,1]
	v_pk_fma_f32 v[52:53], v[64:65], v[10:11], v[52:53] op_sel_hi:[0,1,1]
	s_waitcnt vmcnt(3) lgkmcnt(6)
	v_pk_fma_f32 v[54:55], v[68:69], v[12:13], v[54:55] op_sel_hi:[0,1,1]
	v_pk_fma_f32 v[56:57], v[68:69], v[14:15], v[56:57] op_sel_hi:[0,1,1]
	s_waitcnt lgkmcnt(5)
	v_pk_fma_f32 v[58:59], v[68:69], v[22:23], v[50:51] op_sel_hi:[0,1,1]
	v_pk_fma_f32 v[60:61], v[68:69], v[24:25], v[52:53] op_sel_hi:[0,1,1]
	s_waitcnt vmcnt(2) lgkmcnt(4)
	v_pk_fma_f32 v[54:55], v[70:71], v[26:27], v[54:55] op_sel_hi:[0,1,1]
	v_pk_fma_f32 v[56:57], v[70:71], v[28:29], v[56:57] op_sel_hi:[0,1,1]
	s_waitcnt lgkmcnt(3)
	v_pk_fma_f32 v[58:59], v[70:71], v[30:31], v[58:59] op_sel_hi:[0,1,1]
	v_pk_fma_f32 v[60:61], v[70:71], v[32:33], v[60:61] op_sel_hi:[0,1,1]
	v_lshl_add_u64 v[18:19], v[18:19], 0, s[20:21]
	ds_read_b128 v[46:49], v21 offset:272
	ds_read_b128 v[8:11], v21 offset:288
	ds_read_b128 v[12:15], v21 offset:304
	ds_read_b128 v[22:25], v21 offset:320
	ds_read_b128 v[50:53], v21 offset:336
	ds_read_b128 v[26:29], v21 offset:352
	ds_read_b128 v[30:33], v21 offset:368
	s_waitcnt vmcnt(1) lgkmcnt(9)
	v_pk_fma_f32 v[62:63], v[16:17], v[34:35], v[54:55] op_sel_hi:[0,1,1]
	v_pk_fma_f32 v[64:65], v[16:17], v[36:37], v[56:57] op_sel_hi:[0,1,1]
	ds_read_b128 v[34:37], v21 offset:384
	s_waitcnt lgkmcnt(9)
	v_pk_fma_f32 v[58:59], v[16:17], v[38:39], v[58:59] op_sel_hi:[0,1,1]
	v_pk_fma_f32 v[60:61], v[16:17], v[40:41], v[60:61] op_sel_hi:[0,1,1]
	ds_read_b128 v[38:41], v21 offset:400
	ds_read_b128 v[54:57], v21 offset:416
	global_load_dword v16, v[18:19], off
	v_lshl_add_u64 v[18:19], v[18:19], 0, s[20:21]
	s_waitcnt vmcnt(1) lgkmcnt(10)
	v_pk_fma_f32 v[62:63], v[72:73], v[42:43], v[62:63] op_sel_hi:[0,1,1]
	v_pk_fma_f32 v[64:65], v[72:73], v[44:45], v[64:65] op_sel_hi:[0,1,1]
	s_waitcnt lgkmcnt(9)
	v_pk_fma_f32 v[46:47], v[72:73], v[46:47], v[58:59] op_sel_hi:[0,1,1]
	v_pk_fma_f32 v[48:49], v[72:73], v[48:49], v[60:61] op_sel_hi:[0,1,1]
	global_load_dword v58, v[18:19], off
	v_lshl_add_u64 v[18:19], v[18:19], 0, s[20:21]
	ds_read_b128 v[42:45], v21 offset:432
	s_waitcnt vmcnt(1) lgkmcnt(9)
	v_pk_fma_f32 v[60:61], v[16:17], v[8:9], v[62:63] op_sel_hi:[0,1,1]
	v_pk_fma_f32 v[62:63], v[16:17], v[10:11], v[64:65] op_sel_hi:[0,1,1]
	ds_read_b128 v[8:11], v21 offset:448
	s_waitcnt lgkmcnt(9)
	v_pk_fma_f32 v[64:65], v[16:17], v[12:13], v[46:47] op_sel_hi:[0,1,1]
	v_pk_fma_f32 v[68:69], v[16:17], v[14:15], v[48:49] op_sel_hi:[0,1,1]
	ds_read_b128 v[12:15], v21 offset:464
	ds_read_b128 v[46:49], v21 offset:480
	global_load_dword v16, v[18:19], off
	s_waitcnt vmcnt(1) lgkmcnt(10)
	v_pk_fma_f32 v[60:61], v[58:59], v[22:23], v[60:61] op_sel_hi:[0,1,1]
	v_pk_fma_f32 v[62:63], v[58:59], v[24:25], v[62:63] op_sel_hi:[0,1,1]
	s_waitcnt lgkmcnt(9)
	v_pk_fma_f32 v[64:65], v[58:59], v[50:51], v[64:65] op_sel_hi:[0,1,1]
	v_pk_fma_f32 v[58:59], v[58:59], v[52:53], v[68:69] op_sel_hi:[0,1,1]
	v_lshl_add_u64 v[18:19], v[18:19], 0, s[20:21]
	ds_read_b128 v[22:25], v21 offset:496
	ds_read_b128 v[50:53], v21 offset:512
	s_waitcnt vmcnt(0) lgkmcnt(10)
	v_pk_fma_f32 v[60:61], v[16:17], v[26:27], v[60:61] op_sel_hi:[0,1,1]
	v_pk_fma_f32 v[62:63], v[16:17], v[28:29], v[62:63] op_sel_hi:[0,1,1]
	s_waitcnt lgkmcnt(9)
	v_pk_fma_f32 v[64:65], v[16:17], v[30:31], v[64:65] op_sel_hi:[0,1,1]
	v_pk_fma_f32 v[58:59], v[16:17], v[32:33], v[58:59] op_sel_hi:[0,1,1]
	global_load_dword v16, v[18:19], off
	v_lshl_add_u64 v[18:19], v[18:19], 0, s[20:21]
	ds_read_b128 v[26:29], v21 offset:528
	ds_read_b128 v[30:33], v21 offset:544
	s_waitcnt vmcnt(0) lgkmcnt(10)
	v_pk_fma_f32 v[60:61], v[16:17], v[34:35], v[60:61] op_sel_hi:[0,1,1]
	v_pk_fma_f32 v[62:63], v[16:17], v[36:37], v[62:63] op_sel_hi:[0,1,1]
	s_waitcnt lgkmcnt(9)
	v_pk_fma_f32 v[64:65], v[16:17], v[38:39], v[64:65] op_sel_hi:[0,1,1]
	v_pk_fma_f32 v[58:59], v[16:17], v[40:41], v[58:59] op_sel_hi:[0,1,1]
	global_load_dword v16, v[18:19], off
	v_lshl_add_u64 v[18:19], v[18:19], 0, s[20:21]
	ds_read_b128 v[34:37], v21 offset:560
	ds_read_b128 v[38:41], v21 offset:576
	s_waitcnt vmcnt(0) lgkmcnt(10)
	v_pk_fma_f32 v[60:61], v[16:17], v[54:55], v[60:61] op_sel_hi:[0,1,1]
	v_pk_fma_f32 v[62:63], v[16:17], v[56:57], v[62:63] op_sel_hi:[0,1,1]
	s_waitcnt lgkmcnt(9)
	v_pk_fma_f32 v[64:65], v[16:17], v[42:43], v[64:65] op_sel_hi:[0,1,1]
	v_pk_fma_f32 v[68:69], v[16:17], v[44:45], v[58:59] op_sel_hi:[0,1,1]
	global_load_dword v16, v[18:19], off
	v_lshl_add_u64 v[18:19], v[18:19], 0, s[20:21]
	ds_read_b128 v[54:57], v21 offset:592
	ds_read_b128 v[42:45], v21 offset:608
	s_waitcnt vmcnt(0) lgkmcnt(10)
	v_pk_fma_f32 v[8:9], v[16:17], v[8:9], v[60:61] op_sel_hi:[0,1,1]
	v_pk_fma_f32 v[10:11], v[16:17], v[10:11], v[62:63] op_sel_hi:[0,1,1]
	s_waitcnt lgkmcnt(9)
	v_pk_fma_f32 v[12:13], v[16:17], v[12:13], v[64:65] op_sel_hi:[0,1,1]
	v_pk_fma_f32 v[14:15], v[16:17], v[14:15], v[68:69] op_sel_hi:[0,1,1]
	global_load_dword v16, v[18:19], off
	v_lshl_add_u64 v[18:19], v[18:19], 0, s[20:21]
	global_load_dword v62, v[18:19], off
	v_lshl_add_u64 v[18:19], v[18:19], 0, s[20:21]
	global_load_dword v64, v[18:19], off
	v_lshl_add_u64 v[18:19], v[18:19], 0, s[20:21]
	ds_read_b128 v[58:61], v21 offset:624
	s_waitcnt vmcnt(2) lgkmcnt(9)
	v_pk_fma_f32 v[8:9], v[16:17], v[46:47], v[8:9] op_sel_hi:[0,1,1]
	global_load_dword v46, v[18:19], off
	v_lshl_add_u64 v[18:19], v[18:19], 0, s[20:21]
	v_pk_fma_f32 v[10:11], v[16:17], v[48:49], v[10:11] op_sel_hi:[0,1,1]
	global_load_dword v48, v[18:19], off
	v_lshl_add_u64 v[18:19], v[18:19], 0, s[20:21]
	global_load_dword v68, v[18:19], off
	v_lshl_add_u64 v[18:19], v[18:19], 0, s[20:21]
	global_load_dword v70, v[18:19], off
	v_lshl_add_u64 v[18:19], v[18:19], 0, s[20:21]
	global_load_dword v72, v[18:19], off
	v_lshl_add_u64 v[18:19], v[18:19], 0, s[20:21]
	s_waitcnt vmcnt(6) lgkmcnt(7)
	v_pk_fma_f32 v[8:9], v[62:63], v[50:51], v[8:9] op_sel_hi:[0,1,1]
	global_load_dword v50, v[18:19], off
	v_lshl_add_u64 v[18:19], v[18:19], 0, s[20:21]
	v_pk_fma_f32 v[12:13], v[16:17], v[22:23], v[12:13] op_sel_hi:[0,1,1]
	v_pk_fma_f32 v[14:15], v[16:17], v[24:25], v[14:15] op_sel_hi:[0,1,1]
	global_load_dword v74, v[18:19], off
	v_lshl_add_u64 v[18:19], v[18:19], 0, s[20:21]
	v_pk_fma_f32 v[10:11], v[62:63], v[52:53], v[10:11] op_sel_hi:[0,1,1]
	s_waitcnt lgkmcnt(6)
	v_pk_fma_f32 v[12:13], v[62:63], v[26:27], v[12:13] op_sel_hi:[0,1,1]
	v_pk_fma_f32 v[22:23], v[62:63], v[28:29], v[14:15] op_sel_hi:[0,1,1]
	global_load_dword v62, v[18:19], off
	v_lshl_add_u64 v[14:15], v[18:19], 0, s[20:21]
	global_load_dword v18, v[14:15], off
	v_lshl_add_u64 v[24:25], v[14:15], 0, s[20:21]
	global_load_dword v14, v[24:25], off
	v_lshl_add_u64 v[24:25], v[24:25], 0, s[20:21]
	s_waitcnt vmcnt(10) lgkmcnt(5)
	v_pk_fma_f32 v[26:27], v[64:65], v[30:31], v[8:9] op_sel_hi:[0,1,1]
	global_load_dword v16, v[24:25], off
	v_lshl_add_u64 v[8:9], v[24:25], 0, s[20:21]
	v_pk_fma_f32 v[28:29], v[64:65], v[32:33], v[10:11] op_sel_hi:[0,1,1]
	global_load_dword v10, v[8:9], off
	v_lshl_add_u64 v[8:9], v[8:9], 0, s[20:21]
	s_waitcnt lgkmcnt(4)
	v_pk_fma_f32 v[30:31], v[64:65], v[34:35], v[12:13] op_sel_hi:[0,1,1]
	global_load_dword v12, v[8:9], off
	v_lshl_add_u64 v[8:9], v[8:9], 0, s[20:21]
	global_load_dword v8, v[8:9], off
	v_pk_fma_f32 v[32:33], v[64:65], v[36:37], v[22:23] op_sel_hi:[0,1,1]
	ds_read_b128 v[22:25], v21 offset:640
	s_waitcnt vmcnt(13) lgkmcnt(4)
	v_pk_fma_f32 v[34:35], v[46:47], v[38:39], v[26:27] op_sel_hi:[0,1,1]
	v_pk_fma_f32 v[36:37], v[46:47], v[40:41], v[28:29] op_sel_hi:[0,1,1]
	ds_read_b128 v[26:29], v21 offset:656
	s_waitcnt lgkmcnt(4)
	v_pk_fma_f32 v[38:39], v[46:47], v[54:55], v[30:31] op_sel_hi:[0,1,1]
	v_pk_fma_f32 v[40:41], v[46:47], v[56:57], v[32:33] op_sel_hi:[0,1,1]
	ds_read_b128 v[30:33], v21 offset:672
	s_waitcnt vmcnt(12) lgkmcnt(4)
	v_pk_fma_f32 v[46:47], v[48:49], v[42:43], v[34:35] op_sel_hi:[0,1,1]
	v_pk_fma_f32 v[52:53], v[48:49], v[44:45], v[36:37] op_sel_hi:[0,1,1]
	ds_read_b128 v[34:37], v21 offset:688
	s_waitcnt lgkmcnt(4)
	v_pk_fma_f32 v[54:55], v[48:49], v[58:59], v[38:39] op_sel_hi:[0,1,1]
	v_pk_fma_f32 v[48:49], v[48:49], v[60:61], v[40:41] op_sel_hi:[0,1,1]
	ds_read_b128 v[38:41], v21 offset:704
	ds_read_b128 v[42:45], v21 offset:720
	s_waitcnt vmcnt(11) lgkmcnt(5)
	v_pk_fma_f32 v[46:47], v[68:69], v[22:23], v[46:47] op_sel_hi:[0,1,1]
	v_pk_fma_f32 v[52:53], v[68:69], v[24:25], v[52:53] op_sel_hi:[0,1,1]
	ds_read_b128 v[22:25], v21 offset:736
	s_waitcnt lgkmcnt(5)
	v_pk_fma_f32 v[54:55], v[68:69], v[26:27], v[54:55] op_sel_hi:[0,1,1]
	v_pk_fma_f32 v[48:49], v[68:69], v[28:29], v[48:49] op_sel_hi:[0,1,1]
	ds_read_b128 v[26:29], v21 offset:752
	s_waitcnt vmcnt(10) lgkmcnt(5)
	v_pk_fma_f32 v[56:57], v[70:71], v[30:31], v[46:47] op_sel_hi:[0,1,1]
	v_pk_fma_f32 v[52:53], v[70:71], v[32:33], v[52:53] op_sel_hi:[0,1,1]
	ds_read_b128 v[30:33], v21 offset:768
	s_waitcnt lgkmcnt(5)
	v_pk_fma_f32 v[54:55], v[70:71], v[34:35], v[54:55] op_sel_hi:[0,1,1]
	v_pk_fma_f32 v[58:59], v[70:71], v[36:37], v[48:49] op_sel_hi:[0,1,1]
	ds_read_b128 v[34:37], v21 offset:784
	ds_read_b128 v[46:49], v21 offset:800
	s_waitcnt vmcnt(9) lgkmcnt(6)
	v_pk_fma_f32 v[56:57], v[72:73], v[38:39], v[56:57] op_sel_hi:[0,1,1]
	v_pk_fma_f32 v[52:53], v[72:73], v[40:41], v[52:53] op_sel_hi:[0,1,1]
	ds_read_b128 v[38:41], v21 offset:816
	s_waitcnt lgkmcnt(6)
	v_pk_fma_f32 v[54:55], v[72:73], v[42:43], v[54:55] op_sel_hi:[0,1,1]
	v_pk_fma_f32 v[58:59], v[72:73], v[44:45], v[58:59] op_sel_hi:[0,1,1]
	ds_read_b128 v[42:45], v21 offset:832
	s_waitcnt vmcnt(8) lgkmcnt(6)
	v_pk_fma_f32 v[56:57], v[50:51], v[22:23], v[56:57] op_sel_hi:[0,1,1]
	v_pk_fma_f32 v[60:61], v[50:51], v[24:25], v[52:53] op_sel_hi:[0,1,1]
	ds_read_b128 v[22:25], v21 offset:848
	s_waitcnt lgkmcnt(6)
	v_pk_fma_f32 v[54:55], v[50:51], v[26:27], v[54:55] op_sel_hi:[0,1,1]
	v_pk_fma_f32 v[58:59], v[50:51], v[28:29], v[58:59] op_sel_hi:[0,1,1]
	ds_read_b128 v[26:29], v21 offset:864
	ds_read_b128 v[50:53], v21 offset:880
	s_waitcnt vmcnt(7) lgkmcnt(7)
	v_pk_fma_f32 v[56:57], v[74:75], v[30:31], v[56:57] op_sel_hi:[0,1,1]
	v_pk_fma_f32 v[60:61], v[74:75], v[32:33], v[60:61] op_sel_hi:[0,1,1]
	ds_read_b128 v[30:33], v21 offset:896
	s_waitcnt lgkmcnt(7)
	v_pk_fma_f32 v[54:55], v[74:75], v[34:35], v[54:55] op_sel_hi:[0,1,1]
	v_pk_fma_f32 v[58:59], v[74:75], v[36:37], v[58:59] op_sel_hi:[0,1,1]
	ds_read_b128 v[34:37], v21 offset:912
	s_waitcnt vmcnt(6) lgkmcnt(7)
	v_pk_fma_f32 v[64:65], v[62:63], v[46:47], v[56:57] op_sel_hi:[0,1,1]
	v_pk_fma_f32 v[60:61], v[62:63], v[48:49], v[60:61] op_sel_hi:[0,1,1]
	ds_read_b128 v[46:49], v21 offset:928
	s_waitcnt lgkmcnt(7)
	v_pk_fma_f32 v[68:69], v[62:63], v[38:39], v[54:55] op_sel_hi:[0,1,1]
	v_pk_fma_f32 v[58:59], v[62:63], v[40:41], v[58:59] op_sel_hi:[0,1,1]
	ds_read_b128 v[38:41], v21 offset:944
	ds_read_b128 v[54:57], v21 offset:960
	s_waitcnt vmcnt(5) lgkmcnt(8)
	v_pk_fma_f32 v[62:63], v[18:19], v[42:43], v[64:65] op_sel_hi:[0,1,1]
	v_pk_fma_f32 v[64:65], v[18:19], v[44:45], v[60:61] op_sel_hi:[0,1,1]
	ds_read_b128 v[42:45], v21 offset:976
	s_waitcnt lgkmcnt(8)
	v_pk_fma_f32 v[68:69], v[18:19], v[22:23], v[68:69] op_sel_hi:[0,1,1]
	v_pk_fma_f32 v[18:19], v[18:19], v[24:25], v[58:59] op_sel_hi:[0,1,1]
	ds_read_b128 v[22:25], v21 offset:992
	ds_read_b128 v[58:61], v21 offset:1008
	s_waitcnt vmcnt(4) lgkmcnt(9)
	v_pk_fma_f32 v[26:27], v[14:15], v[26:27], v[62:63] op_sel_hi:[0,1,1]
	v_pk_fma_f32 v[28:29], v[14:15], v[28:29], v[64:65] op_sel_hi:[0,1,1]
	s_waitcnt lgkmcnt(8)
	v_pk_fma_f32 v[50:51], v[14:15], v[50:51], v[68:69] op_sel_hi:[0,1,1]
	v_pk_fma_f32 v[14:15], v[14:15], v[52:53], v[18:19] op_sel_hi:[0,1,1]
	s_waitcnt vmcnt(3) lgkmcnt(7)
	v_pk_fma_f32 v[18:19], v[16:17], v[30:31], v[26:27] op_sel_hi:[0,1,1]
	v_pk_fma_f32 v[26:27], v[16:17], v[32:33], v[28:29] op_sel_hi:[0,1,1]
	s_waitcnt lgkmcnt(6)
	v_pk_fma_f32 v[28:29], v[16:17], v[34:35], v[50:51] op_sel_hi:[0,1,1]
	v_pk_fma_f32 v[14:15], v[16:17], v[36:37], v[14:15] op_sel_hi:[0,1,1]
	s_waitcnt vmcnt(2) lgkmcnt(5)
	v_pk_fma_f32 v[18:19], v[10:11], v[46:47], v[18:19] op_sel_hi:[0,1,1]
	v_pk_fma_f32 v[26:27], v[10:11], v[48:49], v[26:27] op_sel_hi:[0,1,1]
	s_waitcnt lgkmcnt(4)
	v_pk_fma_f32 v[28:29], v[10:11], v[38:39], v[28:29] op_sel_hi:[0,1,1]
	v_pk_fma_f32 v[10:11], v[10:11], v[40:41], v[14:15] op_sel_hi:[0,1,1]
	s_waitcnt vmcnt(1) lgkmcnt(3)
	v_pk_fma_f32 v[14:15], v[12:13], v[54:55], v[18:19] op_sel_hi:[0,1,1]
	v_pk_fma_f32 v[18:19], v[12:13], v[56:57], v[26:27] op_sel_hi:[0,1,1]
	s_waitcnt lgkmcnt(2)
	v_pk_fma_f32 v[26:27], v[12:13], v[42:43], v[28:29] op_sel_hi:[0,1,1]
	v_pk_fma_f32 v[28:29], v[12:13], v[44:45], v[10:11] op_sel_hi:[0,1,1]
	s_waitcnt vmcnt(0) lgkmcnt(1)
	v_pk_fma_f32 v[10:11], v[8:9], v[22:23], v[14:15] op_sel_hi:[0,1,1]
	v_pk_fma_f32 v[14:15], v[8:9], v[24:25], v[18:19] op_sel_hi:[0,1,1]
	s_waitcnt lgkmcnt(0)
	v_pk_fma_f32 v[12:13], v[8:9], v[58:59], v[26:27] op_sel_hi:[0,1,1]
	v_pk_fma_f32 v[8:9], v[8:9], v[60:61], v[28:29] op_sel_hi:[0,1,1]
	s_cbranch_scc0 .LBB0_22
	v_add_u32_e32 v6, s43, v17
	ds_write2st64_b32 v6, v10, v11 offset0:128 offset1:129
	ds_write2st64_b32 v6, v14, v15 offset0:130 offset1:131
	ds_write2st64_b32 v6, v12, v13 offset0:132 offset1:133
	ds_write2st64_b32 v6, v8, v9 offset0:134 offset1:135
	v_add_u32_e32 v6, s14, v66
	v_ashrrev_i32_e32 v7, 31, v6
	v_lshl_add_u64 v[6:7], v[6:7], 2, s[16:17]
	s_waitcnt lgkmcnt(0)
	s_barrier
	global_load_dword v16, v[6:7], off
	ds_read2st64_b32 v[8:9], v20 offset0:128 offset1:136
	ds_read2st64_b32 v[10:11], v20 offset0:144 offset1:152
	ds_read2st64_b32 v[12:13], v20 offset0:160 offset1:168
	ds_read2st64_b32 v[14:15], v20 offset0:176 offset1:184
	v_lshl_add_u64 v[6:7], v[4:5], 0, s[18:19]
	s_add_i32 s45, s45, s76
	v_lshl_add_u64 v[6:7], s[14:15], 2, v[6:7]
	s_cmpk_gt_i32 s45, 0x19f
	v_lshl_add_u64 v[6:7], v[6:7], 0, v[2:3]
	s_waitcnt vmcnt(0) lgkmcnt(3)
	v_add_f32_e32 v8, v16, v8
	v_add_f32_e32 v8, v8, v9
	s_waitcnt lgkmcnt(2)
	v_add_f32_e32 v8, v8, v10
	v_add_f32_e32 v8, v8, v11
	s_waitcnt lgkmcnt(1)
	v_add_f32_e32 v8, v8, v12
	v_add_f32_e32 v8, v8, v13
	s_waitcnt lgkmcnt(0)
	v_add_f32_e32 v8, v8, v14
	v_add_f32_e32 v8, v8, v15
	global_store_dword v[6:7], v8, off sc1
	s_barrier
	s_cbranch_scc0 .LBB0_16

.LBB0_37:
	s_lshr_b32 s24, s12, 6
	s_ff1_i32_b32 s25, s24
	s_lshr_b32 s25, s49, s25
	s_and_b32 s25, s25, 0xffff
	s_add_i32 s24, s24, -1
	v_lshl_or_b32 v66, s25, 6, v136
	s_and_b32 s24, s24, s49
	v_mul_hi_u32_u24_e32 v67, s12, v66
	v_mul_u32_u24_e32 v66, s12, v66
	v_lshl_add_u64 v[66:67], v[66:67], 2, s[22:23]
	s_lshl_b32 s22, s24, 8
	s_and_b32 s22, s22, 0xffff00
	s_mov_b32 s23, s13
	v_lshl_add_u64 v[66:67], v[66:67], 0, s[22:23]
	v_lshl_add_u64 v[66:67], v[66:67], 0, v[132:133]
	s_lshl_b64 s[22:23], s[12:13], 4
	v_lshl_add_u64 v[74:75], v[66:67], 0, s[22:23]
	global_load_dwordx4 v[66:69], v[66:67], off
	s_nop 0
	global_load_dwordx4 v[70:73], v[74:75], off
	v_lshl_add_u64 v[74:75], v[74:75], 0, s[22:23]
	v_lshl_add_u64 v[82:83], v[74:75], 0, s[22:23]
	global_load_dwordx4 v[74:77], v[74:75], off
	s_nop 0
	global_load_dwordx4 v[78:81], v[82:83], off
	v_lshl_add_u64 v[82:83], v[82:83], 0, s[22:23]
	v_lshl_add_u64 v[90:91], v[82:83], 0, s[22:23]
	global_load_dwordx4 v[82:85], v[82:83], off
	s_nop 0
	global_load_dwordx4 v[86:89], v[90:91], off
	v_lshl_add_u64 v[90:91], v[90:91], 0, s[22:23]
	v_lshl_add_u64 v[98:99], v[90:91], 0, s[22:23]
	v_lshl_add_u64 v[102:103], v[98:99], 0, s[22:23]
	v_lshl_add_u64 v[106:107], v[102:103], 0, s[22:23]
	v_lshl_add_u64 v[110:111], v[106:107], 0, s[22:23]
	v_lshl_add_u64 v[114:115], v[110:111], 0, s[22:23]
	v_lshl_add_u64 v[118:119], v[114:115], 0, s[22:23]
	v_lshl_add_u64 v[122:123], v[118:119], 0, s[22:23]
	v_lshl_add_u64 v[126:127], v[122:123], 0, s[22:23]
	global_load_dwordx4 v[90:93], v[90:91], off
	s_nop 0
	global_load_dwordx4 v[94:97], v[98:99], off
	s_nop 0
	global_load_dwordx4 v[98:101], v[102:103], off
	s_nop 0
	global_load_dwordx4 v[102:105], v[106:107], off
	s_nop 0
	global_load_dwordx4 v[106:109], v[110:111], off
	s_nop 0
	global_load_dwordx4 v[110:113], v[114:115], off
	s_nop 0
	global_load_dwordx4 v[114:117], v[118:119], off
	s_nop 0
	global_load_dwordx4 v[118:121], v[122:123], off
	s_nop 0
	global_load_dwordx4 v[122:125], v[126:127], off
	v_lshl_add_u64 v[126:127], v[126:127], 0, s[22:23]
	global_load_dwordx4 v[126:129], v[126:127], off
	v_add_u32_e32 v135, 0x410, v145
	s_waitcnt vmcnt(18)
	ds_write2_b32 v135, v62, v63 offset1:1
	v_add_u32_e32 v62, 0x418, v145
	ds_write2_b32 v62, v64, v65 offset1:1
	v_add_u32_e32 v62, 0x820, v145
	ds_write2_b32 v62, v58, v59 offset1:1
	v_add_u32_e32 v58, 0x828, v145
	ds_write2_b32 v58, v60, v61 offset1:1
	v_add_u32_e32 v58, 0xc30, v145
	ds_write2_b32 v58, v54, v55 offset1:1
	v_add_u32_e32 v54, 0xc38, v145
	ds_write2_b32 v54, v56, v57 offset1:1
	v_add_u32_e32 v54, 0x1040, v145
	ds_write2_b32 v54, v50, v51 offset1:1
	v_add_u32_e32 v50, 0x1048, v145
	ds_write2_b32 v50, v52, v53 offset1:1
	v_add_u32_e32 v50, 0x1450, v145
	ds_write2_b32 v50, v46, v47 offset1:1
	v_add_u32_e32 v46, 0x1458, v145
	ds_write2_b32 v46, v48, v49 offset1:1
	v_add_u32_e32 v46, 0x1860, v145
	ds_write2_b32 v46, v42, v43 offset1:1
	v_add_u32_e32 v42, 0x1868, v145
	ds_write2_b32 v42, v44, v45 offset1:1
	v_add_u32_e32 v42, 0x1c70, v145
	ds_write2_b32 v42, v38, v39 offset1:1
	v_add_u32_e32 v38, 0x1c78, v145
	ds_write2_b32 v38, v40, v41 offset1:1
	v_add_u32_e32 v38, 0x2080, v145
	ds_write2_b32 v38, v30, v31 offset1:1
	v_add_u32_e32 v30, 0x2088, v145
	ds_write2_b32 v30, v32, v33 offset1:1
	v_add_u32_e32 v30, 0x2490, v145
	ds_write2_b32 v30, v22, v23 offset1:1
	v_add_u32_e32 v22, 0x2498, v145
	ds_write2_b32 v22, v24, v25 offset1:1
	v_add_u32_e32 v22, 0x28a0, v145
	ds_write2_b32 v22, v18, v19 offset1:1
	v_add_u32_e32 v18, 0x28a8, v145
	ds_write2_b32 v18, v20, v21 offset1:1
	v_add_u32_e32 v18, 0x2cb0, v145
	ds_write2_b32 v18, v14, v15 offset1:1
	v_add_u32_e32 v14, 0x2cb8, v145
	ds_write2_b32 v14, v16, v17 offset1:1
	v_add_u32_e32 v14, 0x30c0, v145
	ds_write2_b32 v14, v10, v11 offset1:1
	v_add_u32_e32 v10, 0x30c8, v145
	ds_write2_b32 v10, v12, v13 offset1:1
	v_add_u32_e32 v10, 0x34d0, v145
	ds_write2_b32 v10, v6, v7 offset1:1
	v_add_u32_e32 v6, 0x34d8, v145
	s_lshr_b32 s25, s48, 6
	ds_write2_b32 v6, v8, v9 offset1:1
	v_add_u32_e32 v6, 0x38e0, v145
	s_add_i32 s22, s25, -1
	s_waitcnt vmcnt(16)
	ds_write2_b32 v145, v26, v27 offset1:1
	ds_write2_b32 v145, v28, v29 offset0:2 offset1:3
	ds_write2_b32 v6, v2, v3 offset1:1
	v_add_u32_e32 v2, 0x38e8, v145
	s_and_b32 s22, s22, s47
	ds_write2_b32 v2, v4, v5 offset1:1
	v_add_u32_e32 v2, 0x3cf0, v145
	s_lshl_b32 s24, s22, 6
	ds_write2_b32 v2, v34, v35 offset1:1
	v_add_u32_e32 v2, 0x3cf8, v145
	v_or_b32_e32 v3, s24, v1
	ds_write2_b32 v2, v36, v37 offset1:1
	v_mad_u64_u32 v[12:13], s[22:23], s14, v3, 0
	s_waitcnt lgkmcnt(0)
	v_mov_b32_e32 v2, v13
	v_add_u32_e32 v24, 0x400, v137
	ds_read2_b32 v[6:7], v137 offset0:65 offset1:73
	ds_read2_b32 v[8:9], v137 offset1:8
	ds_read2_b32 v[10:11], v137 offset0:130 offset1:138
	v_mad_u64_u32 v[2:3], s[22:23], s15, v3, v[2:3]
	ds_read2_b32 v[14:15], v137 offset0:195 offset1:203
	ds_read2_b32 v[16:17], v24 offset0:4 offset1:12
	ds_read2_b32 v[18:19], v24 offset0:69 offset1:77
	ds_read2_b32 v[20:21], v24 offset0:134 offset1:142
	ds_read2_b32 v[22:23], v24 offset0:199 offset1:207
	s_ff1_i32_b32 s22, s25
	s_lshr_b32 s22, s47, s22
	v_mov_b32_e32 v13, v2
	v_lshl_add_u64 v[12:13], v[12:13], 1, v[130:131]
	s_lshl_b32 s22, s22, 7
	s_mov_b32 s23, s13
	v_lshl_add_u64 v[12:13], v[12:13], 0, s[22:23]
	v_mov_b32_e32 v135, v133
	s_waitcnt lgkmcnt(6)
	v_cvt_pk_bf16_f32 v2, v8, v6
	s_waitcnt lgkmcnt(4)
	v_cvt_pk_bf16_f32 v3, v10, v14
	s_waitcnt lgkmcnt(2)
	v_cvt_pk_bf16_f32 v4, v16, v18
	s_waitcnt lgkmcnt(0)
	v_cvt_pk_bf16_f32 v5, v20, v22
	v_lshl_add_u64 v[12:13], v[12:13], 0, v[134:135]
	global_store_dwordx4 v[12:13], v[2:5], off sc1
	s_waitcnt vmcnt(16)
	v_mov_b64_e32 v[26:27], v[66:67]
	s_waitcnt vmcnt(15)
	v_mov_b64_e32 v[62:63], v[70:71]
	v_cvt_pk_bf16_f32 v2, v9, v7
	v_or_b32_e32 v9, s24, v138
	v_mad_u64_u32 v[6:7], s[50:51], s14, v9, 0
	v_mov_b32_e32 v8, v7
	v_mad_u64_u32 v[8:9], s[50:51], s15, v9, v[8:9]
	v_mov_b32_e32 v7, v8
	v_lshl_add_u64 v[6:7], v[6:7], 1, v[130:131]
	v_lshl_add_u64 v[6:7], v[6:7], 0, s[22:23]
	v_cvt_pk_bf16_f32 v3, v11, v15
	v_cvt_pk_bf16_f32 v4, v17, v19
	v_cvt_pk_bf16_f32 v5, v21, v23
	v_lshl_add_u64 v[6:7], v[6:7], 0, v[134:135]
	global_store_dwordx4 v[6:7], v[2:5], off sc1
	ds_read2_b32 v[6:7], v137 offset0:16 offset1:24
	ds_read2_b32 v[8:9], v137 offset0:81 offset1:89
	ds_read2_b32 v[10:11], v137 offset0:146 offset1:154
	v_or_b32_e32 v3, s24, v139
	v_mad_u64_u32 v[12:13], s[50:51], s14, v3, 0
	v_mov_b32_e32 v2, v13
	ds_read2_b32 v[14:15], v137 offset0:211 offset1:219
	ds_read2_b32 v[16:17], v24 offset0:20 offset1:28
	ds_read2_b32 v[18:19], v24 offset0:85 offset1:93
	ds_read2_b32 v[20:21], v24 offset0:150 offset1:158
	ds_read2_b32 v[22:23], v24 offset0:215 offset1:223
	v_mad_u64_u32 v[2:3], s[50:51], s15, v3, v[2:3]
	v_mov_b32_e32 v13, v2
	v_lshl_add_u64 v[12:13], v[12:13], 1, v[130:131]
	v_lshl_add_u64 v[12:13], v[12:13], 0, s[22:23]
	s_waitcnt lgkmcnt(6)
	v_cvt_pk_bf16_f32 v2, v6, v8
	s_waitcnt lgkmcnt(4)
	v_cvt_pk_bf16_f32 v3, v10, v14
	s_waitcnt lgkmcnt(2)
	v_cvt_pk_bf16_f32 v4, v16, v18
	s_waitcnt lgkmcnt(0)
	v_cvt_pk_bf16_f32 v5, v20, v22
	v_lshl_add_u64 v[12:13], v[12:13], 0, v[134:135]
	global_store_dwordx4 v[12:13], v[2:5], off sc1
	s_waitcnt vmcnt(16)
	v_mov_b64_e32 v[58:59], v[74:75]
	s_waitcnt vmcnt(15)
	v_mov_b64_e32 v[54:55], v[78:79]
	v_cvt_pk_bf16_f32 v2, v7, v9
	v_or_b32_e32 v9, s24, v140
	v_mad_u64_u32 v[6:7], s[50:51], s14, v9, 0
	v_mov_b32_e32 v8, v7
	v_mad_u64_u32 v[8:9], s[50:51], s15, v9, v[8:9]
	v_mov_b32_e32 v7, v8
	v_lshl_add_u64 v[6:7], v[6:7], 1, v[130:131]
	v_lshl_add_u64 v[6:7], v[6:7], 0, s[22:23]
	v_cvt_pk_bf16_f32 v3, v11, v15
	v_cvt_pk_bf16_f32 v4, v17, v19
	v_cvt_pk_bf16_f32 v5, v21, v23
	v_lshl_add_u64 v[6:7], v[6:7], 0, v[134:135]
	global_store_dwordx4 v[6:7], v[2:5], off sc1
	ds_read2_b32 v[6:7], v137 offset0:32 offset1:40
	ds_read2_b32 v[8:9], v137 offset0:97 offset1:105
	ds_read2_b32 v[10:11], v137 offset0:162 offset1:170
	v_or_b32_e32 v3, s24, v141
	v_mad_u64_u32 v[12:13], s[50:51], s14, v3, 0
	v_mov_b32_e32 v2, v13
	ds_read2_b32 v[14:15], v137 offset0:227 offset1:235
	ds_read2_b32 v[16:17], v24 offset0:36 offset1:44
	ds_read2_b32 v[18:19], v24 offset0:101 offset1:109
	ds_read2_b32 v[20:21], v24 offset0:166 offset1:174
	ds_read2_b32 v[22:23], v24 offset0:231 offset1:239
	v_mad_u64_u32 v[2:3], s[50:51], s15, v3, v[2:3]
	v_mov_b32_e32 v13, v2
	v_lshl_add_u64 v[12:13], v[12:13], 1, v[130:131]
	v_lshl_add_u64 v[12:13], v[12:13], 0, s[22:23]
	s_waitcnt lgkmcnt(6)
	v_cvt_pk_bf16_f32 v2, v6, v8
	s_waitcnt lgkmcnt(4)
	v_cvt_pk_bf16_f32 v3, v10, v14
	s_waitcnt lgkmcnt(2)
	v_cvt_pk_bf16_f32 v4, v16, v18
	s_waitcnt lgkmcnt(0)
	v_cvt_pk_bf16_f32 v5, v20, v22
	v_lshl_add_u64 v[12:13], v[12:13], 0, v[134:135]
	global_store_dwordx4 v[12:13], v[2:5], off sc1
	s_waitcnt vmcnt(16)
	v_mov_b64_e32 v[50:51], v[82:83]
	s_waitcnt vmcnt(15)
	v_mov_b64_e32 v[46:47], v[86:87]
	v_cvt_pk_bf16_f32 v2, v7, v9
	v_or_b32_e32 v9, s24, v142
	v_mad_u64_u32 v[6:7], s[50:51], s14, v9, 0
	v_mov_b32_e32 v8, v7
	v_mad_u64_u32 v[8:9], s[50:51], s15, v9, v[8:9]
	v_mov_b32_e32 v7, v8
	v_lshl_add_u64 v[6:7], v[6:7], 1, v[130:131]
	v_lshl_add_u64 v[6:7], v[6:7], 0, s[22:23]
	v_cvt_pk_bf16_f32 v3, v11, v15
	v_cvt_pk_bf16_f32 v4, v17, v19
	v_cvt_pk_bf16_f32 v5, v21, v23
	v_lshl_add_u64 v[6:7], v[6:7], 0, v[134:135]
	global_store_dwordx4 v[6:7], v[2:5], off sc1
	ds_read2_b32 v[6:7], v137 offset0:48 offset1:56
	ds_read2_b32 v[8:9], v137 offset0:113 offset1:121
	ds_read2_b32 v[10:11], v137 offset0:178 offset1:186
	v_or_b32_e32 v3, s24, v143
	v_mad_u64_u32 v[12:13], s[50:51], s14, v3, 0
	v_mov_b32_e32 v2, v13
	ds_read2_b32 v[14:15], v137 offset0:243 offset1:251
	ds_read2_b32 v[16:17], v24 offset0:52 offset1:60
	ds_read2_b32 v[18:19], v24 offset0:117 offset1:125
	ds_read2_b32 v[20:21], v24 offset0:182 offset1:190
	ds_read2_b32 v[22:23], v24 offset0:247 offset1:255
	v_mad_u64_u32 v[2:3], s[50:51], s15, v3, v[2:3]
	v_mov_b32_e32 v13, v2
	v_lshl_add_u64 v[12:13], v[12:13], 1, v[130:131]
	v_lshl_add_u64 v[12:13], v[12:13], 0, s[22:23]
	s_waitcnt lgkmcnt(6)
	v_cvt_pk_bf16_f32 v2, v6, v8
	s_waitcnt lgkmcnt(4)
	v_cvt_pk_bf16_f32 v3, v10, v14
	s_waitcnt lgkmcnt(2)
	v_cvt_pk_bf16_f32 v4, v16, v18
	s_waitcnt lgkmcnt(0)
	v_cvt_pk_bf16_f32 v5, v20, v22
	v_lshl_add_u64 v[12:13], v[12:13], 0, v[134:135]
	global_store_dwordx4 v[12:13], v[2:5], off sc1
	s_waitcnt vmcnt(16)
	v_mov_b64_e32 v[42:43], v[90:91]
	s_waitcnt vmcnt(15)
	v_mov_b64_e32 v[38:39], v[94:95]
	v_cvt_pk_bf16_f32 v2, v7, v9
	v_or_b32_e32 v9, s24, v144
	v_mad_u64_u32 v[6:7], s[24:25], s14, v9, 0
	v_mov_b32_e32 v8, v7
	v_mad_u64_u32 v[8:9], s[14:15], s15, v9, v[8:9]
	v_mov_b32_e32 v7, v8
	v_lshl_add_u64 v[6:7], v[6:7], 1, v[130:131]
	v_lshl_add_u64 v[6:7], v[6:7], 0, s[22:23]
	v_cvt_pk_bf16_f32 v3, v11, v15
	v_cvt_pk_bf16_f32 v4, v17, v19
	v_cvt_pk_bf16_f32 v5, v21, v23
	v_lshl_add_u64 v[6:7], v[6:7], 0, v[134:135]
	global_store_dwordx4 v[6:7], v[2:5], off sc1
	s_waitcnt lgkmcnt(0)
	s_waitcnt vmcnt(15)
	v_mov_b64_e32 v[30:31], v[98:99]
	s_waitcnt vmcnt(14)
	v_mov_b64_e32 v[22:23], v[102:103]
	s_waitcnt vmcnt(13)
	v_mov_b64_e32 v[18:19], v[106:107]
	s_waitcnt vmcnt(12)
	v_mov_b64_e32 v[14:15], v[110:111]
	s_waitcnt vmcnt(11)
	v_mov_b64_e32 v[10:11], v[114:115]
	s_waitcnt vmcnt(10)
	v_mov_b64_e32 v[6:7], v[118:119]
	s_waitcnt vmcnt(9)
	v_mov_b64_e32 v[2:3], v[122:123]
	s_waitcnt vmcnt(8)
	v_mov_b64_e32 v[34:35], v[126:127]
	s_andn2_b64 vcc, exec, s[16:17]
	v_mov_b64_e32 v[130:131], s[18:19]
	v_mov_b64_e32 v[28:29], v[68:69]
	v_mov_b64_e32 v[64:65], v[72:73]
	v_mov_b64_e32 v[60:61], v[76:77]
	v_mov_b64_e32 v[56:57], v[80:81]
	v_mov_b64_e32 v[52:53], v[84:85]
	v_mov_b64_e32 v[48:49], v[88:89]
	v_mov_b64_e32 v[44:45], v[92:93]
	v_mov_b64_e32 v[40:41], v[96:97]
	v_mov_b64_e32 v[32:33], v[100:101]
	v_mov_b64_e32 v[24:25], v[104:105]
	v_mov_b64_e32 v[20:21], v[108:109]
	v_mov_b64_e32 v[16:17], v[112:113]
	v_mov_b64_e32 v[12:13], v[116:117]
	v_mov_b64_e32 v[8:9], v[120:121]
	v_mov_b64_e32 v[4:5], v[124:125]
	v_mov_b64_e32 v[36:37], v[128:129]
	s_mov_b32 s47, s49
	s_mov_b32 s48, s12
	s_mov_b64 s[14:15], s[20:21]
	s_cbranch_vccz .LBB0_62

.LBB0_102:
	s_andn2_saveexec_b64 s[0:1], s[0:1]
	s_cbranch_execz .LBB0_118
	v_mov_b32_e32 v1, s34
	v_add_co_u32_e32 v2, vcc, 0x3000, v1
	v_mov_b32_e32 v1, s35
	s_waitcnt vmcnt(0)
	v_addc_co_u32_e32 v3, vcc, 0, v1, vcc
	v_mov_b32_e32 v1, 1
	flat_atomic_add v1, v[2:3], v1 offset:1024 sc0
	v_cvt_f32_u32_e32 v2, v0
	v_sub_u32_e32 v3, 0, v0
	s_add_u32 s0, s34, 0x3500
	s_addc_u32 s1, s35, 0
	v_rcp_iflag_f32_e32 v2, v2
	s_mov_b64 s[6:7], -1
	v_mul_f32_e32 v2, 0x4f7ffffe, v2
	v_cvt_u32_f32_e32 v2, v2
	v_mul_lo_u32 v3, v3, v2
	v_mul_hi_u32 v3, v2, v3
	v_add_u32_e32 v2, v2, v3
	s_waitcnt vmcnt(0) lgkmcnt(0)
	v_mul_hi_u32 v2, v1, v2
	v_mul_lo_u32 v4, v2, v0
	v_add_u32_e32 v3, 1, v1
	v_sub_u32_e32 v1, v1, v4
	v_add_u32_e32 v5, 1, v2
	v_cmp_ge_u32_e32 vcc, v1, v0
	v_sub_u32_e32 v4, v1, v0
	s_nop 0
	v_cndmask_b32_e32 v2, v2, v5, vcc
	v_cndmask_b32_e32 v1, v1, v4, vcc
	v_add_u32_e32 v4, 1, v2
	v_cmp_ge_u32_e32 vcc, v1, v0
	s_nop 1
	v_cndmask_b32_e32 v2, v2, v4, vcc
	v_mad_u64_u32 v[0:1], s[4:5], v0, v2, v[0:1]
	v_cmp_ne_u32_e32 vcc, v3, v0
	v_mov_b64_e32 v[0:1], s[0:1]
	s_and_saveexec_b64 s[4:5], vcc
	s_cbranch_execz .LBB0_115
	v_mov_b64_e32 v[0:1], s[0:1]
	flat_load_dword v0, v[0:1] sc1
	s_mov_b64 s[10:11], 0
	s_waitcnt vmcnt(0) lgkmcnt(0)
	v_cmp_eq_u32_e32 vcc, v0, v2
	s_and_saveexec_b64 s[8:9], vcc
	s_cbranch_execz .LBB0_114
	s_add_u32 s6, s34, 0x200
	s_addc_u32 s7, s35, 0
	s_mov_b32 s24, 1
	s_branch .LBB0_107

.LBB0_186:
	s_mov_b32 s2, 1
	v_writelane_b32 v246, s2, 43
	s_ashr_i32 s2, s55, 4
	v_lshl_or_b32 v242, s56, 8, v193
	s_mul_hi_i32 s3, s2, 0x6000
	s_mulk_i32 s2, 0x6000
	s_add_u32 s2, s37, s2
	v_ashrrev_i32_e32 v243, 31, v242
	s_addc_u32 s3, s39, s3
	v_lshlrev_b64 v[144:145], 2, v[242:243]
	v_lshl_add_u64 v[104:105], s[2:3], 0, v[144:145]
	v_lshl_add_u32 v244, s55, 8, v183
	v_readlane_b32 s2, v247, 56
	v_readlane_b32 s3, v247, 57
	v_ashrrev_i32_e32 v245, 31, v244
	v_lshlrev_b64 v[146:147], 12, v[244:245]
	v_lshl_add_u64 v[144:145], s[2:3], 0, v[144:145]
	v_lshl_add_u64 v[190:191], v[144:145], 0, v[146:147]
	global_load_dwordx4 v[116:119], v[104:105], off
	global_load_dwordx4 v[112:115], v[104:105], off offset:64
	global_load_dwordx4 v[108:111], v[104:105], off offset:512
	s_nop 0
	global_load_dwordx4 v[104:107], v[104:105], off offset:576
	v_lshlrev_b32_e32 v195, 2, v242
	v_lshl_add_u32 v195, v244, 12, v195
	s_mov_b64 s[22:23], -1
	global_load_dwordx4 v[196:199], v[190:191], off
	global_load_dwordx4 v[200:203], v[190:191], off offset:64
	global_load_dwordx4 v[210:213], v[190:191], off offset:512
	global_load_dwordx4 v[214:217], v[190:191], off offset:576
	s_mov_b64 s[2:3], 0x10000
	v_lshl_add_u64 v[244:245], v[190:191], 0, s[2:3]
	global_load_dwordx4 v[218:221], v[244:245], off
	global_load_dwordx4 v[222:225], v[244:245], off offset:64
	global_load_dwordx4 v[226:229], v[244:245], off offset:512
	global_load_dwordx4 v[230:233], v[244:245], off offset:576
	s_mov_b64 s[2:3], 0x20000
	v_lshl_add_u64 v[242:243], v[190:191], 0, s[2:3]
	global_load_dwordx4 v[234:237], v[242:243], off
	global_load_dwordx4 v[238:241], v[242:243], off offset:64
	global_load_dwordx4 v[164:167], v[242:243], off offset:512
	global_load_dwordx4 v[160:163], v[242:243], off offset:576
	s_mov_b64 s[2:3], 0x30000
	v_lshl_add_u64 v[244:245], v[190:191], 0, s[2:3]
	global_load_dwordx4 v[156:159], v[244:245], off
	global_load_dwordx4 v[152:155], v[244:245], off offset:64
	global_load_dwordx4 v[148:151], v[244:245], off offset:512
	global_load_dwordx4 v[144:147], v[244:245], off offset:576
	s_waitcnt vmcnt(12)
	v_pk_fma_f32 v[142:143], v[142:143], v[118:119], v[198:199]
	v_pk_fma_f32 v[140:141], v[140:141], v[116:117], v[196:197]
	v_pk_fma_f32 v[138:139], v[138:139], v[114:115], v[202:203]
	v_pk_fma_f32 v[136:137], v[136:137], v[112:113], v[200:201]
	v_pk_fma_f32 v[134:135], v[134:135], v[110:111], v[212:213]
	v_pk_fma_f32 v[132:133], v[132:133], v[108:109], v[210:211]
	v_pk_fma_f32 v[130:131], v[130:131], v[106:107], v[216:217]
	v_pk_fma_f32 v[128:129], v[128:129], v[104:105], v[214:215]
	buffer_store_dwordx4 v[140:143], v195, s[72:75], 0 offen sc1
	buffer_store_dwordx4 v[136:139], v195, s[72:75], 0 offen offset:64 sc1
	buffer_store_dwordx4 v[132:135], v195, s[72:75], 0 offen offset:512 sc1
	buffer_store_dwordx4 v[128:131], v195, s[72:75], 0 offen offset:576 sc1
	s_mov_b64 s[2:3], 0x80000
	v_lshl_add_u64 v[242:243], v[190:191], 0, s[2:3]
	global_load_dwordx4 v[196:199], v[242:243], off
	global_load_dwordx4 v[200:203], v[242:243], off offset:64
	global_load_dwordx4 v[210:213], v[242:243], off offset:512
	global_load_dwordx4 v[214:217], v[242:243], off offset:576
	s_waitcnt vmcnt(16)
	v_pk_fma_f32 v[126:127], v[126:127], v[118:119], v[220:221]
	v_pk_fma_f32 v[124:125], v[124:125], v[116:117], v[218:219]
	v_pk_fma_f32 v[122:123], v[122:123], v[114:115], v[224:225]
	v_pk_fma_f32 v[120:121], v[120:121], v[112:113], v[222:223]
	v_pk_fma_f32 v[102:103], v[102:103], v[110:111], v[228:229]
	v_pk_fma_f32 v[100:101], v[100:101], v[108:109], v[226:227]
	v_pk_fma_f32 v[98:99], v[98:99], v[106:107], v[232:233]
	v_pk_fma_f32 v[96:97], v[96:97], v[104:105], v[230:231]
	s_mov_b32 s2, 0x10000
	buffer_store_dwordx4 v[124:127], v195, s[72:75], s2 offen sc1
	buffer_store_dwordx4 v[120:123], v195, s[72:75], s2 offen offset:64 sc1
	buffer_store_dwordx4 v[100:103], v195, s[72:75], s2 offen offset:512 sc1
	buffer_store_dwordx4 v[96:99], v195, s[72:75], s2 offen offset:576 sc1
	s_mov_b64 s[2:3], 0x90000
	v_lshl_add_u64 v[244:245], v[190:191], 0, s[2:3]
	global_load_dwordx4 v[218:221], v[244:245], off
	global_load_dwordx4 v[222:225], v[244:245], off offset:64
	global_load_dwordx4 v[226:229], v[244:245], off offset:512
	global_load_dwordx4 v[230:233], v[244:245], off offset:576
	s_waitcnt vmcnt(20)
	v_pk_fma_f32 v[94:95], v[94:95], v[118:119], v[236:237]
	v_pk_fma_f32 v[92:93], v[92:93], v[116:117], v[234:235]
	v_pk_fma_f32 v[90:91], v[90:91], v[114:115], v[240:241]
	v_pk_fma_f32 v[88:89], v[88:89], v[112:113], v[238:239]
	v_pk_fma_f32 v[86:87], v[86:87], v[110:111], v[166:167]
	v_pk_fma_f32 v[84:85], v[84:85], v[108:109], v[164:165]
	v_pk_fma_f32 v[74:75], v[74:75], v[106:107], v[162:163]
	v_pk_fma_f32 v[72:73], v[72:73], v[104:105], v[160:161]
	s_mov_b32 s2, 0x20000
	buffer_store_dwordx4 v[92:95], v195, s[72:75], s2 offen sc1
	buffer_store_dwordx4 v[88:91], v195, s[72:75], s2 offen offset:64 sc1
	buffer_store_dwordx4 v[84:87], v195, s[72:75], s2 offen offset:512 sc1
	buffer_store_dwordx4 v[72:75], v195, s[72:75], s2 offen offset:576 sc1
	s_mov_b64 s[2:3], 0xa0000
	v_lshl_add_u64 v[242:243], v[190:191], 0, s[2:3]
	global_load_dwordx4 v[234:237], v[242:243], off
	global_load_dwordx4 v[238:241], v[242:243], off offset:64
	global_load_dwordx4 v[164:167], v[242:243], off offset:512
	global_load_dwordx4 v[160:163], v[242:243], off offset:576
	s_waitcnt vmcnt(24)
	v_pk_fma_f32 v[82:83], v[82:83], v[118:119], v[158:159]
	v_pk_fma_f32 v[80:81], v[80:81], v[116:117], v[156:157]
	v_pk_fma_f32 v[78:79], v[78:79], v[114:115], v[154:155]
	v_pk_fma_f32 v[76:77], v[76:77], v[112:113], v[152:153]
	v_pk_fma_f32 v[70:71], v[70:71], v[110:111], v[150:151]
	v_pk_fma_f32 v[68:69], v[68:69], v[108:109], v[148:149]
	v_pk_fma_f32 v[66:67], v[66:67], v[106:107], v[146:147]
	v_pk_fma_f32 v[64:65], v[64:65], v[104:105], v[144:145]
	s_mov_b32 s2, 0x30000
	buffer_store_dwordx4 v[80:83], v195, s[72:75], s2 offen sc1
	buffer_store_dwordx4 v[76:79], v195, s[72:75], s2 offen offset:64 sc1
	buffer_store_dwordx4 v[68:71], v195, s[72:75], s2 offen offset:512 sc1
	buffer_store_dwordx4 v[64:67], v195, s[72:75], s2 offen offset:576 sc1
	s_mov_b64 s[2:3], 0xb0000
	v_lshl_add_u64 v[244:245], v[190:191], 0, s[2:3]
	global_load_dwordx4 v[156:159], v[244:245], off
	global_load_dwordx4 v[152:155], v[244:245], off offset:64
	global_load_dwordx4 v[148:151], v[244:245], off offset:512
	global_load_dwordx4 v[144:147], v[244:245], off offset:576
	s_waitcnt vmcnt(24)
	v_pk_fma_f32 v[62:63], v[62:63], v[118:119], v[198:199]
	v_pk_fma_f32 v[60:61], v[60:61], v[116:117], v[196:197]
	v_pk_fma_f32 v[58:59], v[58:59], v[114:115], v[202:203]
	v_pk_fma_f32 v[56:57], v[56:57], v[112:113], v[200:201]
	v_pk_fma_f32 v[54:55], v[54:55], v[110:111], v[212:213]
	v_pk_fma_f32 v[52:53], v[52:53], v[108:109], v[210:211]
	v_pk_fma_f32 v[50:51], v[50:51], v[106:107], v[216:217]
	v_pk_fma_f32 v[48:49], v[48:49], v[104:105], v[214:215]
	s_mov_b32 s2, 0x80000
	buffer_store_dwordx4 v[60:63], v195, s[72:75], s2 offen sc1
	buffer_store_dwordx4 v[56:59], v195, s[72:75], s2 offen offset:64 sc1
	buffer_store_dwordx4 v[52:55], v195, s[72:75], s2 offen offset:512 sc1
	buffer_store_dwordx4 v[48:51], v195, s[72:75], s2 offen offset:576 sc1
	s_waitcnt vmcnt(20)
	v_pk_fma_f32 v[46:47], v[46:47], v[118:119], v[220:221]
	v_pk_fma_f32 v[44:45], v[44:45], v[116:117], v[218:219]
	v_pk_fma_f32 v[42:43], v[42:43], v[114:115], v[224:225]
	v_pk_fma_f32 v[40:41], v[40:41], v[112:113], v[222:223]
	v_pk_fma_f32 v[34:35], v[34:35], v[110:111], v[228:229]
	v_pk_fma_f32 v[32:33], v[32:33], v[108:109], v[226:227]
	v_pk_fma_f32 v[26:27], v[26:27], v[106:107], v[232:233]
	v_pk_fma_f32 v[24:25], v[24:25], v[104:105], v[230:231]
	s_mov_b32 s2, 0x90000
	buffer_store_dwordx4 v[44:47], v195, s[72:75], s2 offen sc1
	buffer_store_dwordx4 v[40:43], v195, s[72:75], s2 offen offset:64 sc1
	buffer_store_dwordx4 v[32:35], v195, s[72:75], s2 offen offset:512 sc1
	buffer_store_dwordx4 v[24:27], v195, s[72:75], s2 offen offset:576 sc1
	s_waitcnt vmcnt(16)
	v_pk_fma_f32 v[38:39], v[38:39], v[118:119], v[236:237]
	v_pk_fma_f32 v[36:37], v[36:37], v[116:117], v[234:235]
	v_pk_fma_f32 v[30:31], v[30:31], v[114:115], v[240:241]
	v_pk_fma_f32 v[28:29], v[28:29], v[112:113], v[238:239]
	v_pk_fma_f32 v[18:19], v[18:19], v[110:111], v[166:167]
	v_pk_fma_f32 v[16:17], v[16:17], v[108:109], v[164:165]
	v_pk_fma_f32 v[10:11], v[10:11], v[106:107], v[162:163]
	v_pk_fma_f32 v[8:9], v[8:9], v[104:105], v[160:161]
	s_mov_b32 s2, 0xa0000
	buffer_store_dwordx4 v[36:39], v195, s[72:75], s2 offen sc1
	buffer_store_dwordx4 v[28:31], v195, s[72:75], s2 offen offset:64 sc1
	buffer_store_dwordx4 v[16:19], v195, s[72:75], s2 offen offset:512 sc1
	buffer_store_dwordx4 v[8:11], v195, s[72:75], s2 offen offset:576 sc1
	s_waitcnt vmcnt(12)
	v_pk_fma_f32 v[22:23], v[22:23], v[118:119], v[158:159]
	v_pk_fma_f32 v[20:21], v[20:21], v[116:117], v[156:157]
	v_pk_fma_f32 v[14:15], v[14:15], v[114:115], v[154:155]
	v_pk_fma_f32 v[12:13], v[12:13], v[112:113], v[152:153]
	v_pk_fma_f32 v[6:7], v[6:7], v[110:111], v[150:151]
	v_pk_fma_f32 v[4:5], v[4:5], v[108:109], v[148:149]
	v_pk_fma_f32 v[2:3], v[2:3], v[106:107], v[146:147]
	v_pk_fma_f32 v[0:1], v[0:1], v[104:105], v[144:145]
	s_mov_b32 s2, 0xb0000
	buffer_store_dwordx4 v[20:23], v195, s[72:75], s2 offen sc1
	buffer_store_dwordx4 v[12:15], v195, s[72:75], s2 offen offset:64 sc1
	buffer_store_dwordx4 v[4:7], v195, s[72:75], s2 offen offset:512 sc1
	buffer_store_dwordx4 v[0:3], v195, s[72:75], s2 offen offset:576 sc1
	s_and_b64 vcc, exec, s[4:5]
	s_cbranch_vccnz .LBB0_171
	s_andn2_b64 vcc, exec, s[16:17]
	s_cbranch_vccnz .LBB0_170
	s_barrier
	s_branch .LBB0_170

.LBB0_198:
	s_ashr_i32 s2, s50, 11
	s_nop 7
	v_cvt_pk_bf16_f32 v0, v0, v1
	v_cvt_pk_bf16_f32 v1, v2, v3
	v_cvt_pk_bf16_f32 v4, v4, v5
	v_cvt_pk_bf16_f32 v5, v6, v7
	s_ashr_i32 s3, s2, 31
	v_cvt_pk_bf16_f32 v2, v16, v17
	v_cvt_pk_bf16_f32 v3, v18, v19
	ds_write2_b64 v183, v[0:1], v[4:5] offset1:2
	v_cvt_pk_bf16_f32 v0, v20, v21
	v_cvt_pk_bf16_f32 v1, v22, v23
	s_lshl_b64 s[2:3], s[2:3], 23
	ds_write2_b64 v183, v[2:3], v[0:1] offset0:8 offset1:10
	v_cvt_pk_bf16_f32 v0, v8, v9
	v_cvt_pk_bf16_f32 v1, v10, v11
	v_cvt_pk_bf16_f32 v4, v12, v13
	v_cvt_pk_bf16_f32 v5, v14, v15
	s_add_u32 s2, s39, s2
	v_cvt_pk_bf16_f32 v2, v24, v25
	v_cvt_pk_bf16_f32 v3, v26, v27
	ds_write2_b64 v183, v[0:1], v[4:5] offset0:4 offset1:6
	v_cvt_pk_bf16_f32 v0, v28, v29
	v_cvt_pk_bf16_f32 v1, v30, v31
	s_addc_u32 s3, s46, s3
	s_lshl_b32 s50, s59, 16
	ds_write2_b64 v183, v[2:3], v[0:1] offset0:12 offset1:14
	s_add_u32 s2, s2, s50
	s_waitcnt lgkmcnt(0)
	s_addc_u32 s3, s3, 0
	s_lshl_b32 s50, s54, 7
	s_and_b32 s50, s50, 0x780
	ds_read_b128 v[0:3], v211
	ds_read_b128 v[4:7], v211 offset:1152
	s_add_u32 s2, s2, s50
	s_addc_u32 s3, s3, 0
	v_mov_b32_e32 v191, v175
	v_lshl_add_u64 v[8:9], s[2:3], 0, v[190:191]
	v_mov_b32_e32 v193, v175
	v_lshl_add_u64 v[10:11], v[8:9], 0, v[192:193]
	v_mov_b32_e32 v195, v175
	s_waitcnt lgkmcnt(1)
	global_store_dwordx4 v[10:11], v[0:3], off sc1
	v_lshl_add_u64 v[10:11], v[8:9], 0, v[194:195]
	ds_read_b128 v[0:3], v211 offset:2304
	s_waitcnt lgkmcnt(1)
	global_store_dwordx4 v[10:11], v[4:7], off sc1
	ds_read_b128 v[4:7], v211 offset:3456
	v_mov_b32_e32 v197, v175
	v_lshl_add_u64 v[10:11], v[8:9], 0, v[196:197]
	v_mov_b32_e32 v199, v175
	s_waitcnt lgkmcnt(1)
	global_store_dwordx4 v[10:11], v[0:3], off sc1
	s_nop 1
	v_lshl_add_u64 v[0:1], v[8:9], 0, v[198:199]
	s_waitcnt lgkmcnt(0)
	global_store_dwordx4 v[0:1], v[4:7], off sc1
	s_waitcnt lgkmcnt(0)
	s_waitcnt vmcnt(10)
	s_waitcnt vmcnt(8)
	s_waitcnt vmcnt(4)
	s_add_i32 s47, s47, s62
	v_mov_b64_e32 v[36:37], v[92:93]
	v_mov_b64_e32 v[16:17], v[88:89]
	v_mov_b64_e32 v[40:41], v[84:85]
	v_mov_b64_e32 v[20:21], v[80:81]
	v_mov_b64_e32 v[24:25], v[76:77]
	s_andn2_b64 vcc, exec, s[52:53]
	v_mov_b64_e32 v[38:39], v[94:95]
	v_mov_b64_e32 v[18:19], v[90:91]
	v_mov_b64_e32 v[42:43], v[86:87]
	v_mov_b64_e32 v[22:23], v[82:83]
	s_mov_b32 s50, s51
	v_mov_b64_e32 v[26:27], v[78:79]
	v_mov_b32_e32 v0, v72
	v_mov_b32_e32 v1, v73
	v_mov_b32_e32 v2, v74
	v_mov_b32_e32 v3, v75
	v_mov_b32_e32 v44, v64
	v_mov_b32_e32 v45, v65
	v_mov_b32_e32 v46, v66
	v_mov_b32_e32 v47, v67
	v_mov_b32_e32 v28, v68
	v_mov_b32_e32 v29, v69
	v_mov_b32_e32 v30, v70
	v_mov_b32_e32 v31, v71
	v_mov_b32_e32 v4, v60
	v_mov_b32_e32 v5, v61
	v_mov_b32_e32 v6, v62
	v_mov_b32_e32 v7, v63
	v_mov_b32_e32 v8, v56
	v_mov_b32_e32 v9, v57
	v_mov_b32_e32 v10, v58
	v_mov_b32_e32 v11, v59
	v_mov_b32_e32 v12, v52
	v_mov_b32_e32 v13, v53
	v_mov_b32_e32 v14, v54
	v_mov_b32_e32 v15, v55
	v_mov_b32_e32 v112, v48
	v_mov_b32_e32 v113, v49
	v_mov_b32_e32 v114, v50
	v_mov_b32_e32 v115, v51
	s_cbranch_vccz .LBB0_205

.LBB0_209:
	s_or_b64 exec, exec, s[18:19]
	s_and_b32 s18, s39, 7
	s_lshl_b32 s78, s18, 7
	v_lshl_add_u64 v[0:1], s[78:79], 0, v[72:73]
	v_lshlrev_b64 v[0:1], 9, v[0:1]
	v_lshl_add_u64 v[4:5], v[80:81], 0, v[0:1]
	s_waitcnt lgkmcnt(0)
	s_barrier
	global_load_dwordx4 v[0:3], v[4:5], off offset:16
	s_nop 0
	global_load_dwordx4 v[4:7], v[4:5], off
	ds_read_b128 v[8:11], v113
	ds_read_b128 v[12:15], v113 offset:16
	v_readlane_b32 s2, v246, 27
	v_readlane_b32 s3, v246, 28
	v_readlane_b32 vcc_lo, v246, 15
	v_readlane_b32 vcc_hi, v246, 16
	s_movk_i32 s19, 0x2080
	s_add_i32 s39, s39, s76
	s_waitcnt vmcnt(0) lgkmcnt(0)
	v_mul_f32_e32 v4, v4, v8
	v_cndmask_b32_e64 v8, v4, 0, s[2:3]
	v_readlane_b32 s2, v246, 25
	v_mul_f32_e32 v5, v5, v9
	v_readlane_b32 s3, v246, 26
	s_nop 1
	v_cndmask_b32_e64 v9, 0, v5, s[2:3]
	v_pk_mul_f32 v[4:5], v[6:7], v[10:11]
	v_pk_mul_f32 v[6:7], v[2:3], v[14:15]
	v_pk_mul_f32 v[2:3], v[0:1], v[12:13]
	v_readlane_b32 s2, v246, 11
	v_cvt_pk_bf16_f32 v1, v4, v5
	v_readlane_b32 s3, v246, 12
	v_cvt_pk_bf16_f32 v2, v2, v3
	v_cndmask_b32_e64 v3, v2, 0, vcc
	v_cndmask_b32_e64 v4, v1, 0, s[2:3]
	v_readlane_b32 s2, v246, 23
	v_readlane_b32 vcc_lo, v246, 13
	v_lshrrev_b32_e32 v1, 16, v1
	v_readlane_b32 s3, v246, 24
	v_lshrrev_b32_e32 v2, 16, v2
	v_readlane_b32 vcc_hi, v246, 14
	v_cndmask_b32_e64 v1, v1, 0, s[2:3]
	s_mov_b32 s2, 0x5040100
	v_cndmask_b32_e64 v2, v2, 0, vcc
	v_readlane_b32 vcc_lo, v246, 19
	v_perm_b32 v2, v2, v3, s2
	v_cvt_pk_bf16_f32 v3, v6, v7
	v_readlane_b32 vcc_hi, v246, 20
	v_perm_b32 v1, v1, v4, s2
	v_cvt_pk_bf16_f32 v0, v8, v9
	v_cndmask_b32_e64 v4, v3, 0, vcc
	v_readlane_b32 vcc_lo, v246, 17
	v_lshrrev_b32_e32 v3, 16, v3
	v_readlane_b32 vcc_hi, v246, 18
	s_nop 1
	v_cndmask_b32_e64 v3, v3, 0, vcc
	v_perm_b32 v3, v3, v4, s2
	ds_write_b128 v69, v[0:3] offset:1024
	v_lshl_add_u64 v[0:1], s[78:79], 0, v[74:75]
	v_lshlrev_b64 v[0:1], 9, v[0:1]
	v_lshl_add_u64 v[4:5], v[80:81], 0, v[0:1]
	global_load_dwordx4 v[0:3], v[4:5], off offset:16
	s_nop 0
	global_load_dwordx4 v[4:7], v[4:5], off
	ds_read_b128 v[8:11], v113
	ds_read_b128 v[12:15], v113 offset:16
	v_readlane_b32 vcc_lo, v246, 21
	v_readlane_b32 vcc_hi, v246, 22
	s_waitcnt vmcnt(0) lgkmcnt(1)
	v_mul_f32_e32 v4, v4, v8
	v_mul_f32_e32 v5, v5, v9
	v_cndmask_b32_e64 v8, v4, 0, vcc
	v_cndmask_b32_e64 v9, 0, v5, s[22:23]
	v_pk_mul_f32 v[4:5], v[6:7], v[10:11]
	s_waitcnt lgkmcnt(0)
	v_pk_mul_f32 v[6:7], v[2:3], v[14:15]
	v_pk_mul_f32 v[2:3], v[0:1], v[12:13]
	v_cvt_pk_bf16_f32 v1, v4, v5
	v_cvt_pk_bf16_f32 v2, v2, v3
	v_cndmask_b32_e64 v3, v2, 0, s[30:31]
	v_lshrrev_b32_e32 v2, 16, v2
	v_cndmask_b32_e64 v4, v1, 0, s[26:27]
	v_lshrrev_b32_e32 v1, 16, v1
	v_cndmask_b32_e64 v2, v2, 0, s[28:29]
	v_cndmask_b32_e64 v1, v1, 0, s[24:25]
	v_perm_b32 v2, v2, v3, s2
	v_cvt_pk_bf16_f32 v3, v6, v7
	v_perm_b32 v1, v1, v4, s2
	v_cndmask_b32_e64 v4, v3, 0, s[36:37]
	v_lshrrev_b32_e32 v3, 16, v3
	v_cndmask_b32_e64 v3, v3, 0, s[34:35]
	v_cvt_pk_bf16_f32 v0, v8, v9
	v_perm_b32 v3, v3, v4, s2
	ds_write_b128 v114, v[0:3] offset:1024
	v_lshl_add_u64 v[0:1], s[78:79], 0, v[76:77]
	v_lshlrev_b64 v[0:1], 9, v[0:1]
	v_lshl_add_u64 v[4:5], v[80:81], 0, v[0:1]
	global_load_dwordx4 v[0:3], v[4:5], off offset:16
	s_nop 0
	global_load_dwordx4 v[4:7], v[4:5], off
	ds_read_b128 v[8:11], v113
	ds_read_b128 v[12:15], v113 offset:16
	s_lshl_b32 vcc_lo, s18, 9
	s_mov_b32 vcc_hi, s79
	s_waitcnt vmcnt(0) lgkmcnt(1)
	v_mul_f32_e32 v4, v4, v8
	v_mul_f32_e32 v5, v5, v9
	v_cndmask_b32_e64 v8, v4, 0, s[72:73]
	v_cndmask_b32_e64 v9, 0, v5, s[0:1]
	v_pk_mul_f32 v[4:5], v[6:7], v[10:11]
	s_waitcnt lgkmcnt(0)
	v_pk_mul_f32 v[6:7], v[2:3], v[14:15]
	v_pk_mul_f32 v[2:3], v[0:1], v[12:13]
	v_cvt_pk_bf16_f32 v1, v4, v5
	v_cvt_pk_bf16_f32 v2, v2, v3
	v_cndmask_b32_e64 v3, v2, 0, s[10:11]
	v_lshrrev_b32_e32 v2, 16, v2
	v_cndmask_b32_e64 v4, v1, 0, s[6:7]
	v_lshrrev_b32_e32 v1, 16, v1
	v_cndmask_b32_e64 v2, v2, 0, s[8:9]
	v_cndmask_b32_e64 v1, v1, 0, s[4:5]
	v_perm_b32 v2, v2, v3, s2
	v_cvt_pk_bf16_f32 v3, v6, v7
	v_perm_b32 v1, v1, v4, s2
	v_cndmask_b32_e64 v4, v3, 0, s[52:53]
	v_lshrrev_b32_e32 v3, 16, v3
	v_cndmask_b32_e64 v3, v3, 0, s[50:51]
	v_cvt_pk_bf16_f32 v0, v8, v9
	v_perm_b32 v3, v3, v4, s2
	ds_write_b128 v115, v[0:3] offset:1024
	v_lshl_add_u64 v[0:1], s[78:79], 0, v[78:79]
	v_lshlrev_b64 v[0:1], 9, v[0:1]
	v_lshl_add_u64 v[4:5], v[80:81], 0, v[0:1]
	global_load_dwordx4 v[0:3], v[4:5], off offset:16
	s_nop 0
	global_load_dwordx4 v[4:7], v[4:5], off
	ds_read_b128 v[8:11], v113
	ds_read_b128 v[12:15], v113 offset:16
	s_waitcnt vmcnt(0) lgkmcnt(1)
	v_mul_f32_e32 v4, v4, v8
	v_mul_f32_e32 v5, v5, v9
	v_cndmask_b32_e64 v8, v4, 0, s[54:55]
	v_cndmask_b32_e64 v9, 0, v5, s[56:57]
	v_pk_mul_f32 v[4:5], v[6:7], v[10:11]
	s_waitcnt lgkmcnt(0)
	v_pk_mul_f32 v[6:7], v[2:3], v[14:15]
	v_pk_mul_f32 v[2:3], v[0:1], v[12:13]
	v_cvt_pk_bf16_f32 v1, v4, v5
	v_cvt_pk_bf16_f32 v2, v2, v3
	v_cndmask_b32_e64 v3, v2, 0, s[64:65]
	v_lshrrev_b32_e32 v2, 16, v2
	v_cndmask_b32_e64 v4, v1, 0, s[60:61]
	v_lshrrev_b32_e32 v1, 16, v1
	v_cndmask_b32_e64 v2, v2, 0, s[62:63]
	v_cndmask_b32_e64 v1, v1, 0, s[20:21]
	v_perm_b32 v2, v2, v3, s2
	v_cvt_pk_bf16_f32 v3, v6, v7
	v_perm_b32 v1, v1, v4, s2
	v_cndmask_b32_e64 v4, v3, 0, s[68:69]
	v_lshrrev_b32_e32 v3, 16, v3
	v_cndmask_b32_e64 v3, v3, 0, s[66:67]
	v_cvt_pk_bf16_f32 v0, v8, v9
	v_perm_b32 v3, v3, v4, s2
	ds_write_b128 v116, v[0:3] offset:1024
	v_or_b32_e32 v2, s16, v66
	v_mov_b64_e32 v[0:1], s[12:13]
	v_mad_u64_u32 v[0:1], s[2:3], v2, s19, v[0:1]
	v_mad_i32_i24 v1, s17, v206, v1
	v_lshl_add_u64 v[0:1], v[0:1], 0, vcc
	s_mov_b64 s[2:3], 0x1000
	v_lshl_add_u64 v[0:1], v[0:1], 0, s[2:3]
	v_lshl_add_u64 v[10:11], v[82:83], 1, v[0:1]
	global_load_dwordx4 v[10:13], v[10:11], off
	v_lshl_add_u64 v[14:15], v[84:85], 1, v[0:1]
	s_waitcnt vmcnt(0)
	ds_write_b16 v117, v10 offset:35840
	ds_write_b16_d16_hi v117, v10 offset:36112
	ds_write_b16 v117, v11 offset:36384
	ds_write_b16_d16_hi v117, v11 offset:36656
	ds_write_b16 v117, v12 offset:36928
	ds_write_b16_d16_hi v117, v12 offset:37200
	ds_write_b16 v117, v13 offset:37472
	ds_write_b16_d16_hi v117, v13 offset:37744
	global_load_dwordx4 v[10:13], v[14:15], off
	v_lshl_add_u64 v[16:17], v[86:87], 1, v[0:1]
	s_waitcnt vmcnt(0)
	ds_write_b16 v118, v10 offset:35840
	ds_write_b16_d16_hi v118, v10 offset:36112
	ds_write_b16 v118, v11 offset:36384
	ds_write_b16_d16_hi v118, v11 offset:36656
	ds_write_b16 v118, v12 offset:36928
	ds_write_b16_d16_hi v118, v12 offset:37200
	ds_write_b16 v118, v13 offset:37472
	ds_write_b16_d16_hi v118, v13 offset:37744
	global_load_dwordx4 v[10:13], v[16:17], off
	v_lshl_add_u64 v[8:9], v[88:89], 1, v[0:1]
	s_waitcnt vmcnt(0)
	ds_write_b16 v119, v10 offset:35840
	ds_write_b16_d16_hi v119, v10 offset:36112
	ds_write_b16 v119, v11 offset:36384
	ds_write_b16_d16_hi v119, v11 offset:36656
	ds_write_b16 v119, v12 offset:36928
	ds_write_b16_d16_hi v119, v12 offset:37200
	ds_write_b16 v119, v13 offset:37472
	ds_write_b16_d16_hi v119, v13 offset:37744
	global_load_dwordx4 v[8:11], v[8:9], off
	v_lshl_add_u64 v[6:7], v[90:91], 1, v[0:1]
	s_waitcnt vmcnt(0)
	ds_write_b16 v120, v8 offset:35840
	ds_write_b16_d16_hi v120, v8 offset:36112
	ds_write_b16 v120, v9 offset:36384
	ds_write_b16_d16_hi v120, v9 offset:36656
	ds_write_b16 v120, v10 offset:36928
	ds_write_b16_d16_hi v120, v10 offset:37200
	ds_write_b16 v120, v11 offset:37472
	ds_write_b16_d16_hi v120, v11 offset:37744
	global_load_dwordx4 v[6:9], v[6:7], off
	v_lshl_add_u64 v[4:5], v[92:93], 1, v[0:1]
	s_waitcnt vmcnt(0)
	ds_write_b16 v121, v6 offset:35840
	ds_write_b16_d16_hi v121, v6 offset:36112
	ds_write_b16 v121, v7 offset:36384
	ds_write_b16_d16_hi v121, v7 offset:36656
	ds_write_b16 v121, v8 offset:36928
	ds_write_b16_d16_hi v121, v8 offset:37200
	ds_write_b16 v121, v9 offset:37472
	ds_write_b16_d16_hi v121, v9 offset:37744
	global_load_dwordx4 v[4:7], v[4:5], off
	v_lshl_add_u64 v[2:3], v[94:95], 1, v[0:1]
	s_waitcnt vmcnt(0)
	ds_write_b16 v122, v4 offset:35840
	ds_write_b16_d16_hi v122, v4 offset:36112
	ds_write_b16 v122, v5 offset:36384
	ds_write_b16_d16_hi v122, v5 offset:36656
	ds_write_b16 v122, v6 offset:36928
	ds_write_b16_d16_hi v122, v6 offset:37200
	ds_write_b16 v122, v7 offset:37472
	ds_write_b16_d16_hi v122, v7 offset:37744
	global_load_dwordx4 v[2:5], v[2:3], off
	v_lshl_add_u64 v[0:1], v[96:97], 1, v[0:1]
	s_waitcnt vmcnt(0)
	ds_write_b16 v123, v2 offset:35840
	ds_write_b16_d16_hi v123, v2 offset:36112
	ds_write_b16 v123, v3 offset:36384
	ds_write_b16_d16_hi v123, v3 offset:36656
	ds_write_b16 v123, v4 offset:36928
	ds_write_b16_d16_hi v123, v4 offset:37200
	ds_write_b16 v123, v5 offset:37472
	ds_write_b16_d16_hi v123, v5 offset:37744
	global_load_dwordx4 v[0:3], v[0:1], off
	s_waitcnt vmcnt(0)
	ds_write_b16 v124, v0 offset:35840
	ds_write_b16_d16_hi v124, v0 offset:36112
	ds_write_b16 v124, v1 offset:36384
	ds_write_b16_d16_hi v124, v1 offset:36656
	ds_write_b16 v124, v2 offset:36928
	ds_write_b16_d16_hi v124, v2 offset:37200
	ds_write_b16 v124, v3 offset:37472
	ds_write_b16_d16_hi v124, v3 offset:37744
	s_waitcnt lgkmcnt(0)
	s_barrier
	ds_read_b128 v[0:3], v68 offset:35840
	ds_read_b128 v[108:111], v68 offset:35872
	ds_read_b128 v[4:7], v125 offset:1024
	ds_read_b128 v[134:137], v125 offset:1056
	s_waitcnt lgkmcnt(1)
	v_mfma_f32_32x32x16_bf16 v[48:63], v[0:3], v[4:7], 0
	ds_read_b128 v[4:7], v126 offset:1024
	ds_read_b128 v[138:141], v126 offset:1056
	s_waitcnt lgkmcnt(1)
	v_mfma_f32_32x32x16_bf16 v[32:47], v[0:3], v[4:7], 0
	ds_read_b128 v[4:7], v125 offset:18432
	s_waitcnt lgkmcnt(0)
	v_mfma_f32_32x32x16_bf16 v[16:31], v[0:3], v[4:7], 0
	ds_read_b128 v[4:7], v127 offset:1024
	ds_read_b128 v[142:145], v127 offset:1056
	s_waitcnt lgkmcnt(1)
	v_mfma_f32_32x32x16_bf16 v[0:15], v[0:3], v[4:7], 0
	v_mfma_f32_32x32x16_bf16 v[48:63], v[108:111], v[134:137], v[48:63]
	ds_read_b128 v[134:137], v125 offset:18464
	v_mfma_f32_32x32x16_bf16 v[32:47], v[108:111], v[138:141], v[32:47]
	s_waitcnt lgkmcnt(0)
	v_mfma_f32_32x32x16_bf16 v[16:31], v[108:111], v[134:137], v[16:31]
	v_mfma_f32_32x32x16_bf16 v[0:15], v[108:111], v[142:145], v[0:15]
	ds_read_b128 v[108:111], v68 offset:35904
	ds_read_b128 v[134:137], v126 offset:1088
	s_waitcnt lgkmcnt(0)
	v_mfma_f32_32x32x16_bf16 v[32:47], v[108:111], v[134:137], v[32:47]
	ds_read_b128 v[134:137], v125 offset:18496
	s_waitcnt lgkmcnt(0)
	v_mfma_f32_32x32x16_bf16 v[16:31], v[108:111], v[134:137], v[16:31]
	ds_read_b128 v[134:137], v127 offset:1088
	s_waitcnt lgkmcnt(0)
	v_mfma_f32_32x32x16_bf16 v[0:15], v[108:111], v[134:137], v[0:15]
	ds_read_b128 v[108:111], v68 offset:35936
	ds_read_b128 v[134:137], v126 offset:1120
	s_waitcnt lgkmcnt(0)
	v_mfma_f32_32x32x16_bf16 v[32:47], v[108:111], v[134:137], v[32:47]
	ds_read_b128 v[134:137], v125 offset:18528
	s_waitcnt lgkmcnt(0)
	v_mfma_f32_32x32x16_bf16 v[16:31], v[108:111], v[134:137], v[16:31]
	ds_read_b128 v[134:137], v127 offset:1120
	s_waitcnt lgkmcnt(0)
	v_mfma_f32_32x32x16_bf16 v[0:15], v[108:111], v[134:137], v[0:15]
	ds_read_b128 v[108:111], v68 offset:35968
	ds_read_b128 v[134:137], v125 offset:18560
	s_waitcnt lgkmcnt(0)
	v_mfma_f32_32x32x16_bf16 v[16:31], v[108:111], v[134:137], v[16:31]
	ds_read_b128 v[134:137], v127 offset:1152
	s_waitcnt lgkmcnt(0)
	v_mfma_f32_32x32x16_bf16 v[0:15], v[108:111], v[134:137], v[0:15]
	ds_read_b128 v[108:111], v68 offset:36000
	ds_read_b128 v[134:137], v125 offset:18592
	s_waitcnt lgkmcnt(0)
	v_mfma_f32_32x32x16_bf16 v[16:31], v[108:111], v[134:137], v[16:31]
	ds_read_b128 v[134:137], v127 offset:1184
	s_waitcnt lgkmcnt(0)
	v_mfma_f32_32x32x16_bf16 v[0:15], v[108:111], v[134:137], v[0:15]
	ds_read_b128 v[108:111], v68 offset:36032
	ds_read_b128 v[134:137], v127 offset:1216
	s_waitcnt lgkmcnt(0)
	v_mfma_f32_32x32x16_bf16 v[0:15], v[108:111], v[134:137], v[0:15]
	ds_read_b128 v[108:111], v68 offset:36064
	ds_read_b128 v[134:137], v127 offset:1248
	s_waitcnt lgkmcnt(0)
	s_barrier
	v_mfma_f32_32x32x16_bf16 v[0:15], v[108:111], v[134:137], v[0:15]
	v_or_b32_e32 v134, s78, v67
	s_lshl_b32 s78, s18, 10
	v_lshlrev_b32_e32 v134, 2, v134
	v_lshl_add_u64 v[110:111], v[106:107], 0, s[78:79]
	global_load_dword v152, v134, s[14:15]
	global_load_dwordx4 v[136:139], v[110:111], off
	global_load_dwordx4 v[140:143], v[110:111], off offset:32
	global_load_dwordx4 v[144:147], v[110:111], off offset:64
	global_load_dwordx4 v[148:151], v[110:111], off offset:96
	v_lshl_add_u64 v[108:109], v[70:71], 0, vcc
	s_waitcnt vmcnt(3)
	v_pk_fma_f32 v[48:49], v[48:49], v[136:137], v[152:153] op_sel_hi:[1,1,0]
	v_pk_fma_f32 v[50:51], v[50:51], v[138:139], v[152:153] op_sel_hi:[1,1,0]
	ds_write_b128 v128, v[48:51]
	s_waitcnt vmcnt(2)
	v_pk_fma_f32 v[48:49], v[52:53], v[140:141], v[152:153] op_sel_hi:[1,1,0]
	v_pk_fma_f32 v[50:51], v[54:55], v[142:143], v[152:153] op_sel_hi:[1,1,0]
	ds_write_b128 v128, v[48:51] offset:32
	s_waitcnt vmcnt(1)
	v_pk_fma_f32 v[48:49], v[56:57], v[144:145], v[152:153] op_sel_hi:[1,1,0]
	v_pk_fma_f32 v[50:51], v[58:59], v[146:147], v[152:153] op_sel_hi:[1,1,0]
	ds_write_b128 v128, v[48:51] offset:64
	s_waitcnt vmcnt(0)
	v_pk_fma_f32 v[48:49], v[60:61], v[148:149], v[152:153] op_sel_hi:[1,1,0]
	v_pk_fma_f32 v[50:51], v[62:63], v[150:151], v[152:153] op_sel_hi:[1,1,0]
	ds_write_b128 v128, v[48:51] offset:96
	global_load_dword v48, v134, s[14:15] offset:128
	s_waitcnt vmcnt(0)
	v_pk_fma_f32 v[32:33], v[32:33], v[136:137], v[48:49] op_sel_hi:[1,1,0]
	v_pk_fma_f32 v[34:35], v[34:35], v[138:139], v[48:49] op_sel_hi:[1,1,0]
	ds_write_b128 v129, v[32:35]
	v_pk_fma_f32 v[32:33], v[36:37], v[140:141], v[48:49] op_sel_hi:[1,1,0]
	v_pk_fma_f32 v[34:35], v[38:39], v[142:143], v[48:49] op_sel_hi:[1,1,0]
	ds_write_b128 v129, v[32:35] offset:32
	v_pk_fma_f32 v[32:33], v[40:41], v[144:145], v[48:49] op_sel_hi:[1,1,0]
	v_pk_fma_f32 v[34:35], v[42:43], v[146:147], v[48:49] op_sel_hi:[1,1,0]
	ds_write_b128 v129, v[32:35] offset:64
	v_pk_fma_f32 v[32:33], v[44:45], v[148:149], v[48:49] op_sel_hi:[1,1,0]
	v_pk_fma_f32 v[34:35], v[46:47], v[150:151], v[48:49] op_sel_hi:[1,1,0]
	ds_write_b128 v129, v[32:35] offset:96
	v_lshl_add_u64 v[32:33], s[16:17], 0, v[98:99]
	v_mad_u64_u32 v[56:57], s[2:3], v32, s19, v[108:109]
	v_mad_i32_i24 v57, v33, s19, v57
	s_waitcnt lgkmcnt(0)
	s_barrier
	global_load_dwordx4 v[32:35], v[56:57], off
	v_lshl_add_u64 v[36:37], s[16:17], 0, v[100:101]
	v_mad_u64_u32 v[58:59], s[2:3], v36, s19, v[108:109]
	v_mad_i32_i24 v59, v37, s19, v59
	global_load_dwordx4 v[36:39], v[58:59], off
	v_lshl_add_u64 v[40:41], s[16:17], 0, v[102:103]
	v_mad_u64_u32 v[60:61], s[2:3], v40, s19, v[108:109]
	v_mad_i32_i24 v61, v41, s19, v61
	global_load_dwordx4 v[40:43], v[60:61], off
	v_lshl_add_u64 v[44:45], s[16:17], 0, v[104:105]
	v_mad_u64_u32 v[62:63], s[2:3], v44, s19, v[108:109]
	v_mad_i32_i24 v63, v45, s19, v63
	global_load_dwordx4 v[44:47], v[62:63], off
	ds_read_b128 v[48:51], v130
	ds_read_b128 v[52:55], v130 offset:16
	s_or_b32 s16, s16, 64
	s_cmpk_gt_i32 s39, 0x7ff
	s_waitcnt vmcnt(3)
	v_lshlrev_b32_e32 v136, 16, v32
	v_and_b32_e32 v137, 0xffff0000, v32
	s_waitcnt lgkmcnt(1)
	v_pk_mul_f32 v[48:49], v[48:49], v[136:137]
	s_nop 0
	v_cvt_pk_bf16_f32 v32, v48, v49
	v_lshlrev_b32_e32 v48, 16, v33
	v_and_b32_e32 v49, 0xffff0000, v33
	v_pk_mul_f32 v[48:49], v[50:51], v[48:49]
	s_nop 0
	v_cvt_pk_bf16_f32 v33, v48, v49
	v_lshlrev_b32_e32 v48, 16, v34
	v_and_b32_e32 v49, 0xffff0000, v34
	s_waitcnt lgkmcnt(0)
	v_pk_mul_f32 v[48:49], v[52:53], v[48:49]
	s_waitcnt vmcnt(2)
	v_lshlrev_b32_e32 v52, 16, v36
	v_cvt_pk_bf16_f32 v34, v48, v49
	v_lshlrev_b32_e32 v48, 16, v35
	v_and_b32_e32 v49, 0xffff0000, v35
	v_pk_mul_f32 v[48:49], v[54:55], v[48:49]
	v_and_b32_e32 v53, 0xffff0000, v36
	v_cvt_pk_bf16_f32 v35, v48, v49
	global_store_dwordx4 v[56:57], v[32:35], off sc1
	ds_read_b128 v[32:35], v131
	ds_read_b128 v[48:51], v131 offset:16
	v_lshlrev_b32_e32 v36, 16, v37
	v_and_b32_e32 v37, 0xffff0000, v37
	s_waitcnt lgkmcnt(1)
	v_pk_mul_f32 v[32:33], v[32:33], v[52:53]
	v_pk_mul_f32 v[34:35], v[34:35], v[36:37]
	v_cvt_pk_bf16_f32 v32, v32, v33
	v_cvt_pk_bf16_f32 v33, v34, v35
	v_lshlrev_b32_e32 v34, 16, v38
	v_and_b32_e32 v35, 0xffff0000, v38
	v_lshlrev_b32_e32 v36, 16, v39
	v_and_b32_e32 v37, 0xffff0000, v39
	s_waitcnt lgkmcnt(0)
	v_pk_mul_f32 v[34:35], v[48:49], v[34:35]
	v_pk_mul_f32 v[36:37], v[50:51], v[36:37]
	v_cvt_pk_bf16_f32 v34, v34, v35
	v_cvt_pk_bf16_f32 v35, v36, v37
	global_store_dwordx4 v[58:59], v[32:35], off sc1
	ds_read_b128 v[32:35], v132
	ds_read_b128 v[36:39], v132 offset:16
	s_waitcnt vmcnt(3)
	v_lshlrev_b32_e32 v48, 16, v40
	v_and_b32_e32 v49, 0xffff0000, v40
	v_lshlrev_b32_e32 v40, 16, v41
	v_and_b32_e32 v41, 0xffff0000, v41
	s_waitcnt lgkmcnt(1)
	v_pk_mul_f32 v[32:33], v[32:33], v[48:49]
	v_pk_mul_f32 v[34:35], v[34:35], v[40:41]
	v_cvt_pk_bf16_f32 v32, v32, v33
	v_cvt_pk_bf16_f32 v33, v34, v35
	v_lshlrev_b32_e32 v34, 16, v42
	v_and_b32_e32 v35, 0xffff0000, v42
	s_waitcnt lgkmcnt(0)
	v_pk_mul_f32 v[34:35], v[36:37], v[34:35]
	v_lshlrev_b32_e32 v36, 16, v43
	v_and_b32_e32 v37, 0xffff0000, v43
	v_pk_mul_f32 v[36:37], v[38:39], v[36:37]
	v_cvt_pk_bf16_f32 v34, v34, v35
	v_cvt_pk_bf16_f32 v35, v36, v37
	global_store_dwordx4 v[60:61], v[32:35], off sc1
	ds_read_b128 v[32:35], v133
	ds_read_b128 v[36:39], v133 offset:16
	s_waitcnt vmcnt(3)
	v_lshlrev_b32_e32 v40, 16, v44
	v_and_b32_e32 v41, 0xffff0000, v44
	s_waitcnt lgkmcnt(1)
	v_pk_mul_f32 v[32:33], v[32:33], v[40:41]
	v_lshlrev_b32_e32 v40, 16, v45
	v_and_b32_e32 v41, 0xffff0000, v45
	v_pk_mul_f32 v[34:35], v[34:35], v[40:41]
	v_cvt_pk_bf16_f32 v32, v32, v33
	v_cvt_pk_bf16_f32 v33, v34, v35
	v_lshlrev_b32_e32 v34, 16, v46
	v_and_b32_e32 v35, 0xffff0000, v46
	s_waitcnt lgkmcnt(0)
	v_pk_mul_f32 v[34:35], v[36:37], v[34:35]
	v_lshlrev_b32_e32 v36, 16, v47
	v_and_b32_e32 v37, 0xffff0000, v47
	v_pk_mul_f32 v[36:37], v[38:39], v[36:37]
	v_cvt_pk_bf16_f32 v34, v34, v35
	v_cvt_pk_bf16_f32 v35, v36, v37
	global_store_dwordx4 v[62:63], v[32:35], off sc1
	s_barrier
	global_load_dword v48, v134, s[14:15] offset:256
	global_load_dwordx4 v[32:35], v[110:111], off
	global_load_dwordx4 v[36:39], v[110:111], off offset:32
	global_load_dwordx4 v[40:43], v[110:111], off offset:64
	global_load_dwordx4 v[44:47], v[110:111], off offset:96
	s_waitcnt vmcnt(3)
	v_pk_fma_f32 v[16:17], v[16:17], v[32:33], v[48:49] op_sel_hi:[1,1,0]
	v_pk_fma_f32 v[18:19], v[18:19], v[34:35], v[48:49] op_sel_hi:[1,1,0]
	ds_write_b128 v128, v[16:19]
	s_waitcnt vmcnt(2)
	v_pk_fma_f32 v[16:17], v[20:21], v[36:37], v[48:49] op_sel_hi:[1,1,0]
	v_pk_fma_f32 v[18:19], v[22:23], v[38:39], v[48:49] op_sel_hi:[1,1,0]
	ds_write_b128 v128, v[16:19] offset:32
	s_waitcnt vmcnt(1)
	v_pk_fma_f32 v[16:17], v[24:25], v[40:41], v[48:49] op_sel_hi:[1,1,0]
	v_pk_fma_f32 v[18:19], v[26:27], v[42:43], v[48:49] op_sel_hi:[1,1,0]
	ds_write_b128 v128, v[16:19] offset:64
	s_waitcnt vmcnt(0)
	v_pk_fma_f32 v[16:17], v[28:29], v[44:45], v[48:49] op_sel_hi:[1,1,0]
	v_pk_fma_f32 v[18:19], v[30:31], v[46:47], v[48:49] op_sel_hi:[1,1,0]
	ds_write_b128 v128, v[16:19] offset:96
	global_load_dword v16, v134, s[14:15] offset:384
	s_waitcnt vmcnt(0)
	v_pk_fma_f32 v[0:1], v[0:1], v[32:33], v[16:17] op_sel_hi:[1,1,0]
	v_pk_fma_f32 v[2:3], v[2:3], v[34:35], v[16:17] op_sel_hi:[1,1,0]
	ds_write_b128 v129, v[0:3]
	v_pk_fma_f32 v[0:1], v[4:5], v[36:37], v[16:17] op_sel_hi:[1,1,0]
	v_pk_fma_f32 v[2:3], v[6:7], v[38:39], v[16:17] op_sel_hi:[1,1,0]
	ds_write_b128 v129, v[0:3] offset:32
	v_pk_fma_f32 v[0:1], v[8:9], v[40:41], v[16:17] op_sel_hi:[1,1,0]
	v_pk_fma_f32 v[2:3], v[10:11], v[42:43], v[16:17] op_sel_hi:[1,1,0]
	ds_write_b128 v129, v[0:3] offset:64
	v_pk_fma_f32 v[0:1], v[12:13], v[44:45], v[16:17] op_sel_hi:[1,1,0]
	v_pk_fma_f32 v[2:3], v[14:15], v[46:47], v[16:17] op_sel_hi:[1,1,0]
	ds_write_b128 v129, v[0:3] offset:96
	v_lshl_add_u64 v[0:1], s[16:17], 0, v[98:99]
	v_mad_u64_u32 v[24:25], s[2:3], v0, s19, v[108:109]
	v_mad_i32_i24 v25, v1, s19, v25
	s_waitcnt lgkmcnt(0)
	s_barrier
	global_load_dwordx4 v[0:3], v[24:25], off
	v_lshl_add_u64 v[4:5], s[16:17], 0, v[100:101]
	v_mad_u64_u32 v[26:27], s[2:3], v4, s19, v[108:109]
	v_mad_i32_i24 v27, v5, s19, v27
	global_load_dwordx4 v[4:7], v[26:27], off
	v_lshl_add_u64 v[8:9], s[16:17], 0, v[102:103]
	v_mad_u64_u32 v[28:29], s[2:3], v8, s19, v[108:109]
	v_mad_i32_i24 v29, v9, s19, v29
	global_load_dwordx4 v[8:11], v[28:29], off
	v_lshl_add_u64 v[12:13], s[16:17], 0, v[104:105]
	v_mad_u64_u32 v[30:31], s[2:3], v12, s19, v[108:109]
	v_mad_i32_i24 v31, v13, s19, v31
	global_load_dwordx4 v[12:15], v[30:31], off
	ds_read_b128 v[16:19], v130
	ds_read_b128 v[20:23], v130 offset:16
	s_waitcnt vmcnt(3)
	v_lshlrev_b32_e32 v32, 16, v0
	v_and_b32_e32 v33, 0xffff0000, v0
	s_waitcnt lgkmcnt(1)
	v_pk_mul_f32 v[16:17], v[16:17], v[32:33]
	s_nop 0
	v_cvt_pk_bf16_f32 v0, v16, v17
	v_lshlrev_b32_e32 v16, 16, v1
	v_and_b32_e32 v17, 0xffff0000, v1
	v_pk_mul_f32 v[16:17], v[18:19], v[16:17]
	s_nop 0
	v_cvt_pk_bf16_f32 v1, v16, v17
	v_lshlrev_b32_e32 v16, 16, v2
	v_and_b32_e32 v17, 0xffff0000, v2
	s_waitcnt lgkmcnt(0)
	v_pk_mul_f32 v[16:17], v[20:21], v[16:17]
	s_waitcnt vmcnt(2)
	v_lshlrev_b32_e32 v20, 16, v4
	v_cvt_pk_bf16_f32 v2, v16, v17
	v_lshlrev_b32_e32 v16, 16, v3
	v_and_b32_e32 v17, 0xffff0000, v3
	v_pk_mul_f32 v[16:17], v[22:23], v[16:17]
	v_and_b32_e32 v21, 0xffff0000, v4
	v_cvt_pk_bf16_f32 v3, v16, v17
	global_store_dwordx4 v[24:25], v[0:3], off sc1
	ds_read_b128 v[0:3], v131
	ds_read_b128 v[16:19], v131 offset:16
	v_lshlrev_b32_e32 v4, 16, v5
	v_and_b32_e32 v5, 0xffff0000, v5
	s_waitcnt lgkmcnt(1)
	v_pk_mul_f32 v[0:1], v[0:1], v[20:21]
	v_pk_mul_f32 v[2:3], v[2:3], v[4:5]
	v_cvt_pk_bf16_f32 v0, v0, v1
	v_cvt_pk_bf16_f32 v1, v2, v3
	v_lshlrev_b32_e32 v2, 16, v6
	v_and_b32_e32 v3, 0xffff0000, v6
	v_lshlrev_b32_e32 v4, 16, v7
	v_and_b32_e32 v5, 0xffff0000, v7
	s_waitcnt lgkmcnt(0)
	v_pk_mul_f32 v[2:3], v[16:17], v[2:3]
	v_pk_mul_f32 v[4:5], v[18:19], v[4:5]
	v_cvt_pk_bf16_f32 v2, v2, v3
	v_cvt_pk_bf16_f32 v3, v4, v5
	global_store_dwordx4 v[26:27], v[0:3], off sc1
	ds_read_b128 v[0:3], v132
	ds_read_b128 v[4:7], v132 offset:16
	s_waitcnt vmcnt(3)
	v_lshlrev_b32_e32 v16, 16, v8
	v_and_b32_e32 v17, 0xffff0000, v8
	v_lshlrev_b32_e32 v8, 16, v9
	v_and_b32_e32 v9, 0xffff0000, v9
	s_waitcnt lgkmcnt(1)
	v_pk_mul_f32 v[0:1], v[0:1], v[16:17]
	v_pk_mul_f32 v[2:3], v[2:3], v[8:9]
	v_cvt_pk_bf16_f32 v0, v0, v1
	v_cvt_pk_bf16_f32 v1, v2, v3
	v_lshlrev_b32_e32 v2, 16, v10
	v_and_b32_e32 v3, 0xffff0000, v10
	s_waitcnt lgkmcnt(0)
	v_pk_mul_f32 v[2:3], v[4:5], v[2:3]
	v_lshlrev_b32_e32 v4, 16, v11
	v_and_b32_e32 v5, 0xffff0000, v11
	v_pk_mul_f32 v[4:5], v[6:7], v[4:5]
	v_cvt_pk_bf16_f32 v2, v2, v3
	v_cvt_pk_bf16_f32 v3, v4, v5
	global_store_dwordx4 v[28:29], v[0:3], off sc1
	ds_read_b128 v[0:3], v133
	ds_read_b128 v[4:7], v133 offset:16
	s_waitcnt vmcnt(3)
	v_lshlrev_b32_e32 v8, 16, v12
	v_and_b32_e32 v9, 0xffff0000, v12
	s_waitcnt lgkmcnt(1)
	v_pk_mul_f32 v[0:1], v[0:1], v[8:9]
	v_lshlrev_b32_e32 v8, 16, v13
	v_and_b32_e32 v9, 0xffff0000, v13
	v_pk_mul_f32 v[2:3], v[2:3], v[8:9]
	v_cvt_pk_bf16_f32 v0, v0, v1
	v_cvt_pk_bf16_f32 v1, v2, v3
	v_lshlrev_b32_e32 v2, 16, v14
	v_and_b32_e32 v3, 0xffff0000, v14
	s_waitcnt lgkmcnt(0)
	v_pk_mul_f32 v[2:3], v[4:5], v[2:3]
	v_lshlrev_b32_e32 v4, 16, v15
	v_and_b32_e32 v5, 0xffff0000, v15
	v_pk_mul_f32 v[4:5], v[6:7], v[4:5]
	v_cvt_pk_bf16_f32 v2, v2, v3
	v_cvt_pk_bf16_f32 v3, v4, v5
	global_store_dwordx4 v[30:31], v[0:3], off sc1
	s_barrier
	s_cbranch_scc1 .LBB0_212

.LBB0_245:
	s_mov_b32 s2, 1
	v_writelane_b32 v246, s2, 42
	s_cmp_lg_u32 s95, 1
	s_cbranch_scc1 .Lepi_notgelu
	s_and_b64 vcc, exec, s[24:25]
	s_cbranch_vccnz .Lepi_notgelu
	s_and_b64 vcc, exec, s[26:27]
	s_cbranch_vccz .Lepi_notgelu
	v_mov_b32_e32 v196, 0x3e6d3388
	v_mov_b32_e32 v197, 0x3e6d3388
	v_mov_b32_e32 v198, 0x3f07dc22
	v_mov_b32_e32 v199, 0x3f07dc22
	v_mov_b32_e32 v200, 0xbf3a00e3
	v_mov_b32_e32 v201, 0xbf3a00e3
	v_mov_b32_e32 v202, 0x3f35f0e3
	v_mov_b32_e32 v203, 0x3f35f0e3
	v_mov_b32_e32 v210, 0xbe11a98e
	v_mov_b32_e32 v211, 0xbe11a98e
	v_mov_b32_e32 v212, 0x3e027906
	v_mov_b32_e32 v213, 0x3e027906
	v_mov_b32_e32 v214, 0xbf38aa3b
	v_mov_b32_e32 v215, 0xbf38aa3b
	v_lshl_add_u32 v216, s6, 8, v163
	s_lshl_b32 s2, s18, 8
	s_or_b32 s2, s2, s38
	v_or_b32_e32 v217, s2, v137
	v_mov_b32_e32 v236, v216
	v_mul_lo_u32 v216, v216, s33
	v_add_lshl_u32 v216, v216, v217, 1
	v_fma_f32 v144, |v124|, v196, 1.0
	v_fma_f32 v145, |v125|, v196, 1.0
	v_fma_f32 v152, |v126|, v196, 1.0
	v_fma_f32 v153, |v127|, v196, 1.0
	v_pk_mul_f32 v[146:147], v[124:125], v[124:125]
	v_pk_mul_f32 v[154:155], v[126:127], v[126:127]
	v_rcp_f32_e32 v144, v144
	v_rcp_f32_e32 v145, v145
	v_rcp_f32_e32 v152, v152
	v_rcp_f32_e32 v153, v153
	v_pk_mul_f32 v[146:147], v[146:147], v[214:215]
	v_pk_mul_f32 v[154:155], v[154:155], v[214:215]
	v_exp_f32_e32 v146, v146
	v_exp_f32_e32 v147, v147
	v_exp_f32_e32 v154, v154
	v_exp_f32_e32 v155, v155
	v_pk_fma_f32 v[148:149], v[144:145], v[198:199], v[200:201]
	v_pk_fma_f32 v[156:157], v[152:153], v[198:199], v[200:201]
	v_pk_fma_f32 v[148:149], v[148:149], v[144:145], v[202:203]
	v_pk_fma_f32 v[156:157], v[156:157], v[152:153], v[202:203]
	v_pk_fma_f32 v[148:149], v[148:149], v[144:145], v[210:211]
	v_pk_fma_f32 v[156:157], v[156:157], v[152:153], v[210:211]
	v_pk_fma_f32 v[148:149], v[148:149], v[144:145], v[212:213]
	v_pk_fma_f32 v[156:157], v[156:157], v[152:153], v[212:213]
	v_pk_mul_f32 v[148:149], v[148:149], v[144:145]
	v_pk_mul_f32 v[156:157], v[156:157], v[152:153]
	v_max_f32_e32 v150, 0, v124
	v_max_f32_e32 v151, 0, v125
	v_max_f32_e32 v166, 0, v126
	v_max_f32_e32 v167, 0, v127
	v_pk_mul_f32 v[148:149], v[148:149], v[146:147]
	v_pk_mul_f32 v[156:157], v[156:157], v[154:155]
	v_fma_f32 v124, -|v124|, v148, v150
	v_fma_f32 v125, -|v125|, v149, v151
	v_fma_f32 v126, -|v126|, v156, v166
	v_fma_f32 v127, -|v127|, v157, v167
	v_pk_mul_f32 v[226:227], v[124:125], v[124:125]
	v_pk_fma_f32 v[226:227], v[126:127], v[126:127], v[226:227]
	v_cvt_pk_bf16_f32 v168, v124, v125
	v_cvt_pk_bf16_f32 v169, v126, v127
	v_fma_f32 v144, |v120|, v196, 1.0
	v_fma_f32 v145, |v121|, v196, 1.0
	v_fma_f32 v152, |v122|, v196, 1.0
	v_fma_f32 v153, |v123|, v196, 1.0
	v_pk_mul_f32 v[146:147], v[120:121], v[120:121]
	v_pk_mul_f32 v[154:155], v[122:123], v[122:123]
	v_rcp_f32_e32 v144, v144
	v_rcp_f32_e32 v145, v145
	v_rcp_f32_e32 v152, v152
	v_rcp_f32_e32 v153, v153
	v_pk_mul_f32 v[146:147], v[146:147], v[214:215]
	v_pk_mul_f32 v[154:155], v[154:155], v[214:215]
	v_exp_f32_e32 v146, v146
	v_exp_f32_e32 v147, v147
	v_exp_f32_e32 v154, v154
	v_exp_f32_e32 v155, v155
	v_pk_fma_f32 v[148:149], v[144:145], v[198:199], v[200:201]
	v_pk_fma_f32 v[156:157], v[152:153], v[198:199], v[200:201]
	v_pk_fma_f32 v[148:149], v[148:149], v[144:145], v[202:203]
	v_pk_fma_f32 v[156:157], v[156:157], v[152:153], v[202:203]
	v_pk_fma_f32 v[148:149], v[148:149], v[144:145], v[210:211]
	v_pk_fma_f32 v[156:157], v[156:157], v[152:153], v[210:211]
	v_pk_fma_f32 v[148:149], v[148:149], v[144:145], v[212:213]
	v_pk_fma_f32 v[156:157], v[156:157], v[152:153], v[212:213]
	v_pk_mul_f32 v[148:149], v[148:149], v[144:145]
	v_pk_mul_f32 v[156:157], v[156:157], v[152:153]
	v_max_f32_e32 v150, 0, v120
	v_max_f32_e32 v151, 0, v121
	v_max_f32_e32 v166, 0, v122
	v_max_f32_e32 v167, 0, v123
	v_pk_mul_f32 v[148:149], v[148:149], v[146:147]
	v_pk_mul_f32 v[156:157], v[156:157], v[154:155]
	v_fma_f32 v120, -|v120|, v148, v150
	v_fma_f32 v121, -|v121|, v149, v151
	v_fma_f32 v122, -|v122|, v156, v166
	v_fma_f32 v123, -|v123|, v157, v167
	v_pk_fma_f32 v[226:227], v[120:121], v[120:121], v[226:227]
	v_pk_fma_f32 v[226:227], v[122:123], v[122:123], v[226:227]
	v_cvt_pk_bf16_f32 v170, v120, v121
	v_cvt_pk_bf16_f32 v171, v122, v123
	buffer_store_dwordx4 v[168:171], v216, s[72:75], 0 offen sc1
	v_fma_f32 v144, |v116|, v196, 1.0
	v_fma_f32 v145, |v117|, v196, 1.0
	v_fma_f32 v152, |v118|, v196, 1.0
	v_fma_f32 v153, |v119|, v196, 1.0
	v_pk_mul_f32 v[146:147], v[116:117], v[116:117]
	v_pk_mul_f32 v[154:155], v[118:119], v[118:119]
	v_rcp_f32_e32 v144, v144
	v_rcp_f32_e32 v145, v145
	v_rcp_f32_e32 v152, v152
	v_rcp_f32_e32 v153, v153
	v_pk_mul_f32 v[146:147], v[146:147], v[214:215]
	v_pk_mul_f32 v[154:155], v[154:155], v[214:215]
	v_exp_f32_e32 v146, v146
	v_exp_f32_e32 v147, v147
	v_exp_f32_e32 v154, v154
	v_exp_f32_e32 v155, v155
	v_pk_fma_f32 v[148:149], v[144:145], v[198:199], v[200:201]
	v_pk_fma_f32 v[156:157], v[152:153], v[198:199], v[200:201]
	v_pk_fma_f32 v[148:149], v[148:149], v[144:145], v[202:203]
	v_pk_fma_f32 v[156:157], v[156:157], v[152:153], v[202:203]
	v_pk_fma_f32 v[148:149], v[148:149], v[144:145], v[210:211]
	v_pk_fma_f32 v[156:157], v[156:157], v[152:153], v[210:211]
	v_pk_fma_f32 v[148:149], v[148:149], v[144:145], v[212:213]
	v_pk_fma_f32 v[156:157], v[156:157], v[152:153], v[212:213]
	v_pk_mul_f32 v[148:149], v[148:149], v[144:145]
	v_pk_mul_f32 v[156:157], v[156:157], v[152:153]
	v_max_f32_e32 v150, 0, v116
	v_max_f32_e32 v151, 0, v117
	v_max_f32_e32 v166, 0, v118
	v_max_f32_e32 v167, 0, v119
	v_pk_mul_f32 v[148:149], v[148:149], v[146:147]
	v_pk_mul_f32 v[156:157], v[156:157], v[154:155]
	v_fma_f32 v116, -|v116|, v148, v150
	v_fma_f32 v117, -|v117|, v149, v151
	v_fma_f32 v118, -|v118|, v156, v166
	v_fma_f32 v119, -|v119|, v157, v167
	v_pk_fma_f32 v[226:227], v[116:117], v[116:117], v[226:227]
	v_pk_fma_f32 v[226:227], v[118:119], v[118:119], v[226:227]
	v_cvt_pk_bf16_f32 v232, v116, v117
	v_cvt_pk_bf16_f32 v233, v118, v119
	v_fma_f32 v144, |v112|, v196, 1.0
	v_fma_f32 v145, |v113|, v196, 1.0
	v_fma_f32 v152, |v114|, v196, 1.0
	v_fma_f32 v153, |v115|, v196, 1.0
	v_pk_mul_f32 v[146:147], v[112:113], v[112:113]
	v_pk_mul_f32 v[154:155], v[114:115], v[114:115]
	v_rcp_f32_e32 v144, v144
	v_rcp_f32_e32 v145, v145
	v_rcp_f32_e32 v152, v152
	v_rcp_f32_e32 v153, v153
	v_pk_mul_f32 v[146:147], v[146:147], v[214:215]
	v_pk_mul_f32 v[154:155], v[154:155], v[214:215]
	v_exp_f32_e32 v146, v146
	v_exp_f32_e32 v147, v147
	v_exp_f32_e32 v154, v154
	v_exp_f32_e32 v155, v155
	v_pk_fma_f32 v[148:149], v[144:145], v[198:199], v[200:201]
	v_pk_fma_f32 v[156:157], v[152:153], v[198:199], v[200:201]
	v_pk_fma_f32 v[148:149], v[148:149], v[144:145], v[202:203]
	v_pk_fma_f32 v[156:157], v[156:157], v[152:153], v[202:203]
	v_pk_fma_f32 v[148:149], v[148:149], v[144:145], v[210:211]
	v_pk_fma_f32 v[156:157], v[156:157], v[152:153], v[210:211]
	v_pk_fma_f32 v[148:149], v[148:149], v[144:145], v[212:213]
	v_pk_fma_f32 v[156:157], v[156:157], v[152:153], v[212:213]
	v_pk_mul_f32 v[148:149], v[148:149], v[144:145]
	v_pk_mul_f32 v[156:157], v[156:157], v[152:153]
	v_max_f32_e32 v150, 0, v112
	v_max_f32_e32 v151, 0, v113
	v_max_f32_e32 v166, 0, v114
	v_max_f32_e32 v167, 0, v115
	v_pk_mul_f32 v[148:149], v[148:149], v[146:147]
	v_pk_mul_f32 v[156:157], v[156:157], v[154:155]
	v_fma_f32 v112, -|v112|, v148, v150
	v_fma_f32 v113, -|v113|, v149, v151
	v_fma_f32 v114, -|v114|, v156, v166
	v_fma_f32 v115, -|v115|, v157, v167
	v_pk_fma_f32 v[226:227], v[112:113], v[112:113], v[226:227]
	v_pk_fma_f32 v[226:227], v[114:115], v[114:115], v[226:227]
	v_cvt_pk_bf16_f32 v234, v112, v113
	v_cvt_pk_bf16_f32 v235, v114, v115
	buffer_store_dwordx4 v[232:235], v216, s[72:75], 0 offen offset:256 sc1
	v_add_f32_e32 v218, v226, v227
	v_fma_f32 v144, |v108|, v196, 1.0
	v_fma_f32 v145, |v109|, v196, 1.0
	v_fma_f32 v152, |v110|, v196, 1.0
	v_fma_f32 v153, |v111|, v196, 1.0
	v_pk_mul_f32 v[146:147], v[108:109], v[108:109]
	v_pk_mul_f32 v[154:155], v[110:111], v[110:111]
	v_rcp_f32_e32 v144, v144
	v_rcp_f32_e32 v145, v145
	v_rcp_f32_e32 v152, v152
	v_rcp_f32_e32 v153, v153
	v_pk_mul_f32 v[146:147], v[146:147], v[214:215]
	v_pk_mul_f32 v[154:155], v[154:155], v[214:215]
	v_exp_f32_e32 v146, v146
	v_exp_f32_e32 v147, v147
	v_exp_f32_e32 v154, v154
	v_exp_f32_e32 v155, v155
	v_pk_fma_f32 v[148:149], v[144:145], v[198:199], v[200:201]
	v_pk_fma_f32 v[156:157], v[152:153], v[198:199], v[200:201]
	v_pk_fma_f32 v[148:149], v[148:149], v[144:145], v[202:203]
	v_pk_fma_f32 v[156:157], v[156:157], v[152:153], v[202:203]
	v_pk_fma_f32 v[148:149], v[148:149], v[144:145], v[210:211]
	v_pk_fma_f32 v[156:157], v[156:157], v[152:153], v[210:211]
	v_pk_fma_f32 v[148:149], v[148:149], v[144:145], v[212:213]
	v_pk_fma_f32 v[156:157], v[156:157], v[152:153], v[212:213]
	v_pk_mul_f32 v[148:149], v[148:149], v[144:145]
	v_pk_mul_f32 v[156:157], v[156:157], v[152:153]
	v_max_f32_e32 v150, 0, v108
	v_max_f32_e32 v151, 0, v109
	v_max_f32_e32 v166, 0, v110
	v_max_f32_e32 v167, 0, v111
	v_pk_mul_f32 v[148:149], v[148:149], v[146:147]
	v_pk_mul_f32 v[156:157], v[156:157], v[154:155]
	v_fma_f32 v108, -|v108|, v148, v150
	v_fma_f32 v109, -|v109|, v149, v151
	v_fma_f32 v110, -|v110|, v156, v166
	v_fma_f32 v111, -|v111|, v157, v167
	v_pk_mul_f32 v[226:227], v[108:109], v[108:109]
	v_pk_fma_f32 v[226:227], v[110:111], v[110:111], v[226:227]
	v_cvt_pk_bf16_f32 v168, v108, v109
	v_cvt_pk_bf16_f32 v169, v110, v111
	v_fma_f32 v144, |v104|, v196, 1.0
	v_fma_f32 v145, |v105|, v196, 1.0
	v_fma_f32 v152, |v106|, v196, 1.0
	v_fma_f32 v153, |v107|, v196, 1.0
	v_pk_mul_f32 v[146:147], v[104:105], v[104:105]
	v_pk_mul_f32 v[154:155], v[106:107], v[106:107]
	v_rcp_f32_e32 v144, v144
	v_rcp_f32_e32 v145, v145
	v_rcp_f32_e32 v152, v152
	v_rcp_f32_e32 v153, v153
	v_pk_mul_f32 v[146:147], v[146:147], v[214:215]
	v_pk_mul_f32 v[154:155], v[154:155], v[214:215]
	v_exp_f32_e32 v146, v146
	v_exp_f32_e32 v147, v147
	v_exp_f32_e32 v154, v154
	v_exp_f32_e32 v155, v155
	v_pk_fma_f32 v[148:149], v[144:145], v[198:199], v[200:201]
	v_pk_fma_f32 v[156:157], v[152:153], v[198:199], v[200:201]
	v_pk_fma_f32 v[148:149], v[148:149], v[144:145], v[202:203]
	v_pk_fma_f32 v[156:157], v[156:157], v[152:153], v[202:203]
	v_pk_fma_f32 v[148:149], v[148:149], v[144:145], v[210:211]
	v_pk_fma_f32 v[156:157], v[156:157], v[152:153], v[210:211]
	v_pk_fma_f32 v[148:149], v[148:149], v[144:145], v[212:213]
	v_pk_fma_f32 v[156:157], v[156:157], v[152:153], v[212:213]
	v_pk_mul_f32 v[148:149], v[148:149], v[144:145]
	v_pk_mul_f32 v[156:157], v[156:157], v[152:153]
	v_max_f32_e32 v150, 0, v104
	v_max_f32_e32 v151, 0, v105
	v_max_f32_e32 v166, 0, v106
	v_max_f32_e32 v167, 0, v107
	v_pk_mul_f32 v[148:149], v[148:149], v[146:147]
	v_pk_mul_f32 v[156:157], v[156:157], v[154:155]
	v_fma_f32 v104, -|v104|, v148, v150
	v_fma_f32 v105, -|v105|, v149, v151
	v_fma_f32 v106, -|v106|, v156, v166
	v_fma_f32 v107, -|v107|, v157, v167
	v_pk_fma_f32 v[226:227], v[104:105], v[104:105], v[226:227]
	v_pk_fma_f32 v[226:227], v[106:107], v[106:107], v[226:227]
	v_cvt_pk_bf16_f32 v170, v104, v105
	v_cvt_pk_bf16_f32 v171, v106, v107
	s_mul_i32 s2, s33, 0x20
	buffer_store_dwordx4 v[168:171], v216, s[72:75], s2 offen sc1
	v_fma_f32 v144, |v100|, v196, 1.0
	v_fma_f32 v145, |v101|, v196, 1.0
	v_fma_f32 v152, |v102|, v196, 1.0
	v_fma_f32 v153, |v103|, v196, 1.0
	v_pk_mul_f32 v[146:147], v[100:101], v[100:101]
	v_pk_mul_f32 v[154:155], v[102:103], v[102:103]
	v_rcp_f32_e32 v144, v144
	v_rcp_f32_e32 v145, v145
	v_rcp_f32_e32 v152, v152
	v_rcp_f32_e32 v153, v153
	v_pk_mul_f32 v[146:147], v[146:147], v[214:215]
	v_pk_mul_f32 v[154:155], v[154:155], v[214:215]
	v_exp_f32_e32 v146, v146
	v_exp_f32_e32 v147, v147
	v_exp_f32_e32 v154, v154
	v_exp_f32_e32 v155, v155
	v_pk_fma_f32 v[148:149], v[144:145], v[198:199], v[200:201]
	v_pk_fma_f32 v[156:157], v[152:153], v[198:199], v[200:201]
	v_pk_fma_f32 v[148:149], v[148:149], v[144:145], v[202:203]
	v_pk_fma_f32 v[156:157], v[156:157], v[152:153], v[202:203]
	v_pk_fma_f32 v[148:149], v[148:149], v[144:145], v[210:211]
	v_pk_fma_f32 v[156:157], v[156:157], v[152:153], v[210:211]
	v_pk_fma_f32 v[148:149], v[148:149], v[144:145], v[212:213]
	v_pk_fma_f32 v[156:157], v[156:157], v[152:153], v[212:213]
	v_pk_mul_f32 v[148:149], v[148:149], v[144:145]
	v_pk_mul_f32 v[156:157], v[156:157], v[152:153]
	v_max_f32_e32 v150, 0, v100
	v_max_f32_e32 v151, 0, v101
	v_max_f32_e32 v166, 0, v102
	v_max_f32_e32 v167, 0, v103
	v_pk_mul_f32 v[148:149], v[148:149], v[146:147]
	v_pk_mul_f32 v[156:157], v[156:157], v[154:155]
	v_fma_f32 v100, -|v100|, v148, v150
	v_fma_f32 v101, -|v101|, v149, v151
	v_fma_f32 v102, -|v102|, v156, v166
	v_fma_f32 v103, -|v103|, v157, v167
	v_pk_fma_f32 v[226:227], v[100:101], v[100:101], v[226:227]
	v_pk_fma_f32 v[226:227], v[102:103], v[102:103], v[226:227]
	v_cvt_pk_bf16_f32 v232, v100, v101
	v_cvt_pk_bf16_f32 v233, v102, v103
	v_fma_f32 v144, |v96|, v196, 1.0
	v_fma_f32 v145, |v97|, v196, 1.0
	v_fma_f32 v152, |v98|, v196, 1.0
	v_fma_f32 v153, |v99|, v196, 1.0
	v_pk_mul_f32 v[146:147], v[96:97], v[96:97]
	v_pk_mul_f32 v[154:155], v[98:99], v[98:99]
	v_rcp_f32_e32 v144, v144
	v_rcp_f32_e32 v145, v145
	v_rcp_f32_e32 v152, v152
	v_rcp_f32_e32 v153, v153
	v_pk_mul_f32 v[146:147], v[146:147], v[214:215]
	v_pk_mul_f32 v[154:155], v[154:155], v[214:215]
	v_exp_f32_e32 v146, v146
	v_exp_f32_e32 v147, v147
	v_exp_f32_e32 v154, v154
	v_exp_f32_e32 v155, v155
	v_pk_fma_f32 v[148:149], v[144:145], v[198:199], v[200:201]
	v_pk_fma_f32 v[156:157], v[152:153], v[198:199], v[200:201]
	v_pk_fma_f32 v[148:149], v[148:149], v[144:145], v[202:203]
	v_pk_fma_f32 v[156:157], v[156:157], v[152:153], v[202:203]
	v_pk_fma_f32 v[148:149], v[148:149], v[144:145], v[210:211]
	v_pk_fma_f32 v[156:157], v[156:157], v[152:153], v[210:211]
	v_pk_fma_f32 v[148:149], v[148:149], v[144:145], v[212:213]
	v_pk_fma_f32 v[156:157], v[156:157], v[152:153], v[212:213]
	v_pk_mul_f32 v[148:149], v[148:149], v[144:145]
	v_pk_mul_f32 v[156:157], v[156:157], v[152:153]
	v_max_f32_e32 v150, 0, v96
	v_max_f32_e32 v151, 0, v97
	v_max_f32_e32 v166, 0, v98
	v_max_f32_e32 v167, 0, v99
	v_pk_mul_f32 v[148:149], v[148:149], v[146:147]
	v_pk_mul_f32 v[156:157], v[156:157], v[154:155]
	v_fma_f32 v96, -|v96|, v148, v150
	v_fma_f32 v97, -|v97|, v149, v151
	v_fma_f32 v98, -|v98|, v156, v166
	v_fma_f32 v99, -|v99|, v157, v167
	v_pk_fma_f32 v[226:227], v[96:97], v[96:97], v[226:227]
	v_pk_fma_f32 v[226:227], v[98:99], v[98:99], v[226:227]
	v_cvt_pk_bf16_f32 v234, v96, v97
	v_cvt_pk_bf16_f32 v235, v98, v99
	buffer_store_dwordx4 v[232:235], v216, s[72:75], s2 offen offset:256 sc1
	v_add_f32_e32 v219, v226, v227
	v_fma_f32 v144, |v92|, v196, 1.0
	v_fma_f32 v145, |v93|, v196, 1.0
	v_fma_f32 v152, |v94|, v196, 1.0
	v_fma_f32 v153, |v95|, v196, 1.0
	v_pk_mul_f32 v[146:147], v[92:93], v[92:93]
	v_pk_mul_f32 v[154:155], v[94:95], v[94:95]
	v_rcp_f32_e32 v144, v144
	v_rcp_f32_e32 v145, v145
	v_rcp_f32_e32 v152, v152
	v_rcp_f32_e32 v153, v153
	v_pk_mul_f32 v[146:147], v[146:147], v[214:215]
	v_pk_mul_f32 v[154:155], v[154:155], v[214:215]
	v_exp_f32_e32 v146, v146
	v_exp_f32_e32 v147, v147
	v_exp_f32_e32 v154, v154
	v_exp_f32_e32 v155, v155
	v_pk_fma_f32 v[148:149], v[144:145], v[198:199], v[200:201]
	v_pk_fma_f32 v[156:157], v[152:153], v[198:199], v[200:201]
	v_pk_fma_f32 v[148:149], v[148:149], v[144:145], v[202:203]
	v_pk_fma_f32 v[156:157], v[156:157], v[152:153], v[202:203]
	v_pk_fma_f32 v[148:149], v[148:149], v[144:145], v[210:211]
	v_pk_fma_f32 v[156:157], v[156:157], v[152:153], v[210:211]
	v_pk_fma_f32 v[148:149], v[148:149], v[144:145], v[212:213]
	v_pk_fma_f32 v[156:157], v[156:157], v[152:153], v[212:213]
	v_pk_mul_f32 v[148:149], v[148:149], v[144:145]
	v_pk_mul_f32 v[156:157], v[156:157], v[152:153]
	v_max_f32_e32 v150, 0, v92
	v_max_f32_e32 v151, 0, v93
	v_max_f32_e32 v166, 0, v94
	v_max_f32_e32 v167, 0, v95
	v_pk_mul_f32 v[148:149], v[148:149], v[146:147]
	v_pk_mul_f32 v[156:157], v[156:157], v[154:155]
	v_fma_f32 v92, -|v92|, v148, v150
	v_fma_f32 v93, -|v93|, v149, v151
	v_fma_f32 v94, -|v94|, v156, v166
	v_fma_f32 v95, -|v95|, v157, v167
	v_pk_mul_f32 v[226:227], v[92:93], v[92:93]
	v_pk_fma_f32 v[226:227], v[94:95], v[94:95], v[226:227]
	v_cvt_pk_bf16_f32 v168, v92, v93
	v_cvt_pk_bf16_f32 v169, v94, v95
	v_fma_f32 v144, |v88|, v196, 1.0
	v_fma_f32 v145, |v89|, v196, 1.0
	v_fma_f32 v152, |v90|, v196, 1.0
	v_fma_f32 v153, |v91|, v196, 1.0
	v_pk_mul_f32 v[146:147], v[88:89], v[88:89]
	v_pk_mul_f32 v[154:155], v[90:91], v[90:91]
	v_rcp_f32_e32 v144, v144
	v_rcp_f32_e32 v145, v145
	v_rcp_f32_e32 v152, v152
	v_rcp_f32_e32 v153, v153
	v_pk_mul_f32 v[146:147], v[146:147], v[214:215]
	v_pk_mul_f32 v[154:155], v[154:155], v[214:215]
	v_exp_f32_e32 v146, v146
	v_exp_f32_e32 v147, v147
	v_exp_f32_e32 v154, v154
	v_exp_f32_e32 v155, v155
	v_pk_fma_f32 v[148:149], v[144:145], v[198:199], v[200:201]
	v_pk_fma_f32 v[156:157], v[152:153], v[198:199], v[200:201]
	v_pk_fma_f32 v[148:149], v[148:149], v[144:145], v[202:203]
	v_pk_fma_f32 v[156:157], v[156:157], v[152:153], v[202:203]
	v_pk_fma_f32 v[148:149], v[148:149], v[144:145], v[210:211]
	v_pk_fma_f32 v[156:157], v[156:157], v[152:153], v[210:211]
	v_pk_fma_f32 v[148:149], v[148:149], v[144:145], v[212:213]
	v_pk_fma_f32 v[156:157], v[156:157], v[152:153], v[212:213]
	v_pk_mul_f32 v[148:149], v[148:149], v[144:145]
	v_pk_mul_f32 v[156:157], v[156:157], v[152:153]
	v_max_f32_e32 v150, 0, v88
	v_max_f32_e32 v151, 0, v89
	v_max_f32_e32 v166, 0, v90
	v_max_f32_e32 v167, 0, v91
	v_pk_mul_f32 v[148:149], v[148:149], v[146:147]
	v_pk_mul_f32 v[156:157], v[156:157], v[154:155]
	v_fma_f32 v88, -|v88|, v148, v150
	v_fma_f32 v89, -|v89|, v149, v151
	v_fma_f32 v90, -|v90|, v156, v166
	v_fma_f32 v91, -|v91|, v157, v167
	v_pk_fma_f32 v[226:227], v[88:89], v[88:89], v[226:227]
	v_pk_fma_f32 v[226:227], v[90:91], v[90:91], v[226:227]
	v_cvt_pk_bf16_f32 v170, v88, v89
	v_cvt_pk_bf16_f32 v171, v90, v91
	s_mul_i32 s2, s33, 0x40
	buffer_store_dwordx4 v[168:171], v216, s[72:75], s2 offen sc1
	v_fma_f32 v144, |v84|, v196, 1.0
	v_fma_f32 v145, |v85|, v196, 1.0
	v_fma_f32 v152, |v86|, v196, 1.0
	v_fma_f32 v153, |v87|, v196, 1.0
	v_pk_mul_f32 v[146:147], v[84:85], v[84:85]
	v_pk_mul_f32 v[154:155], v[86:87], v[86:87]
	v_rcp_f32_e32 v144, v144
	v_rcp_f32_e32 v145, v145
	v_rcp_f32_e32 v152, v152
	v_rcp_f32_e32 v153, v153
	v_pk_mul_f32 v[146:147], v[146:147], v[214:215]
	v_pk_mul_f32 v[154:155], v[154:155], v[214:215]
	v_exp_f32_e32 v146, v146
	v_exp_f32_e32 v147, v147
	v_exp_f32_e32 v154, v154
	v_exp_f32_e32 v155, v155
	v_pk_fma_f32 v[148:149], v[144:145], v[198:199], v[200:201]
	v_pk_fma_f32 v[156:157], v[152:153], v[198:199], v[200:201]
	v_pk_fma_f32 v[148:149], v[148:149], v[144:145], v[202:203]
	v_pk_fma_f32 v[156:157], v[156:157], v[152:153], v[202:203]
	v_pk_fma_f32 v[148:149], v[148:149], v[144:145], v[210:211]
	v_pk_fma_f32 v[156:157], v[156:157], v[152:153], v[210:211]
	v_pk_fma_f32 v[148:149], v[148:149], v[144:145], v[212:213]
	v_pk_fma_f32 v[156:157], v[156:157], v[152:153], v[212:213]
	v_pk_mul_f32 v[148:149], v[148:149], v[144:145]
	v_pk_mul_f32 v[156:157], v[156:157], v[152:153]
	v_max_f32_e32 v150, 0, v84
	v_max_f32_e32 v151, 0, v85
	v_max_f32_e32 v166, 0, v86
	v_max_f32_e32 v167, 0, v87
	v_pk_mul_f32 v[148:149], v[148:149], v[146:147]
	v_pk_mul_f32 v[156:157], v[156:157], v[154:155]
	v_fma_f32 v84, -|v84|, v148, v150
	v_fma_f32 v85, -|v85|, v149, v151
	v_fma_f32 v86, -|v86|, v156, v166
	v_fma_f32 v87, -|v87|, v157, v167
	v_pk_fma_f32 v[226:227], v[84:85], v[84:85], v[226:227]
	v_pk_fma_f32 v[226:227], v[86:87], v[86:87], v[226:227]
	v_cvt_pk_bf16_f32 v232, v84, v85
	v_cvt_pk_bf16_f32 v233, v86, v87
	v_fma_f32 v144, |v80|, v196, 1.0
	v_fma_f32 v145, |v81|, v196, 1.0
	v_fma_f32 v152, |v82|, v196, 1.0
	v_fma_f32 v153, |v83|, v196, 1.0
	v_pk_mul_f32 v[146:147], v[80:81], v[80:81]
	v_pk_mul_f32 v[154:155], v[82:83], v[82:83]
	v_rcp_f32_e32 v144, v144
	v_rcp_f32_e32 v145, v145
	v_rcp_f32_e32 v152, v152
	v_rcp_f32_e32 v153, v153
	v_pk_mul_f32 v[146:147], v[146:147], v[214:215]
	v_pk_mul_f32 v[154:155], v[154:155], v[214:215]
	v_exp_f32_e32 v146, v146
	v_exp_f32_e32 v147, v147
	v_exp_f32_e32 v154, v154
	v_exp_f32_e32 v155, v155
	v_pk_fma_f32 v[148:149], v[144:145], v[198:199], v[200:201]
	v_pk_fma_f32 v[156:157], v[152:153], v[198:199], v[200:201]
	v_pk_fma_f32 v[148:149], v[148:149], v[144:145], v[202:203]
	v_pk_fma_f32 v[156:157], v[156:157], v[152:153], v[202:203]
	v_pk_fma_f32 v[148:149], v[148:149], v[144:145], v[210:211]
	v_pk_fma_f32 v[156:157], v[156:157], v[152:153], v[210:211]
	v_pk_fma_f32 v[148:149], v[148:149], v[144:145], v[212:213]
	v_pk_fma_f32 v[156:157], v[156:157], v[152:153], v[212:213]
	v_pk_mul_f32 v[148:149], v[148:149], v[144:145]
	v_pk_mul_f32 v[156:157], v[156:157], v[152:153]
	v_max_f32_e32 v150, 0, v80
	v_max_f32_e32 v151, 0, v81
	v_max_f32_e32 v166, 0, v82
	v_max_f32_e32 v167, 0, v83
	v_pk_mul_f32 v[148:149], v[148:149], v[146:147]
	v_pk_mul_f32 v[156:157], v[156:157], v[154:155]
	v_fma_f32 v80, -|v80|, v148, v150
	v_fma_f32 v81, -|v81|, v149, v151
	v_fma_f32 v82, -|v82|, v156, v166
	v_fma_f32 v83, -|v83|, v157, v167
	v_pk_fma_f32 v[226:227], v[80:81], v[80:81], v[226:227]
	v_pk_fma_f32 v[226:227], v[82:83], v[82:83], v[226:227]
	v_cvt_pk_bf16_f32 v234, v80, v81
	v_cvt_pk_bf16_f32 v235, v82, v83
	buffer_store_dwordx4 v[232:235], v216, s[72:75], s2 offen offset:256 sc1
	v_add_f32_e32 v220, v226, v227
	v_fma_f32 v144, |v76|, v196, 1.0
	v_fma_f32 v145, |v77|, v196, 1.0
	v_fma_f32 v152, |v78|, v196, 1.0
	v_fma_f32 v153, |v79|, v196, 1.0
	v_pk_mul_f32 v[146:147], v[76:77], v[76:77]
	v_pk_mul_f32 v[154:155], v[78:79], v[78:79]
	v_rcp_f32_e32 v144, v144
	v_rcp_f32_e32 v145, v145
	v_rcp_f32_e32 v152, v152
	v_rcp_f32_e32 v153, v153
	v_pk_mul_f32 v[146:147], v[146:147], v[214:215]
	v_pk_mul_f32 v[154:155], v[154:155], v[214:215]
	v_exp_f32_e32 v146, v146
	v_exp_f32_e32 v147, v147
	v_exp_f32_e32 v154, v154
	v_exp_f32_e32 v155, v155
	v_pk_fma_f32 v[148:149], v[144:145], v[198:199], v[200:201]
	v_pk_fma_f32 v[156:157], v[152:153], v[198:199], v[200:201]
	v_pk_fma_f32 v[148:149], v[148:149], v[144:145], v[202:203]
	v_pk_fma_f32 v[156:157], v[156:157], v[152:153], v[202:203]
	v_pk_fma_f32 v[148:149], v[148:149], v[144:145], v[210:211]
	v_pk_fma_f32 v[156:157], v[156:157], v[152:153], v[210:211]
	v_pk_fma_f32 v[148:149], v[148:149], v[144:145], v[212:213]
	v_pk_fma_f32 v[156:157], v[156:157], v[152:153], v[212:213]
	v_pk_mul_f32 v[148:149], v[148:149], v[144:145]
	v_pk_mul_f32 v[156:157], v[156:157], v[152:153]
	v_max_f32_e32 v150, 0, v76
	v_max_f32_e32 v151, 0, v77
	v_max_f32_e32 v166, 0, v78
	v_max_f32_e32 v167, 0, v79
	v_pk_mul_f32 v[148:149], v[148:149], v[146:147]
	v_pk_mul_f32 v[156:157], v[156:157], v[154:155]
	v_fma_f32 v76, -|v76|, v148, v150
	v_fma_f32 v77, -|v77|, v149, v151
	v_fma_f32 v78, -|v78|, v156, v166
	v_fma_f32 v79, -|v79|, v157, v167
	v_pk_mul_f32 v[226:227], v[76:77], v[76:77]
	v_pk_fma_f32 v[226:227], v[78:79], v[78:79], v[226:227]
	v_cvt_pk_bf16_f32 v168, v76, v77
	v_cvt_pk_bf16_f32 v169, v78, v79
	v_fma_f32 v144, |v72|, v196, 1.0
	v_fma_f32 v145, |v73|, v196, 1.0
	v_fma_f32 v152, |v74|, v196, 1.0
	v_fma_f32 v153, |v75|, v196, 1.0
	v_pk_mul_f32 v[146:147], v[72:73], v[72:73]
	v_pk_mul_f32 v[154:155], v[74:75], v[74:75]
	v_rcp_f32_e32 v144, v144
	v_rcp_f32_e32 v145, v145
	v_rcp_f32_e32 v152, v152
	v_rcp_f32_e32 v153, v153
	v_pk_mul_f32 v[146:147], v[146:147], v[214:215]
	v_pk_mul_f32 v[154:155], v[154:155], v[214:215]
	v_exp_f32_e32 v146, v146
	v_exp_f32_e32 v147, v147
	v_exp_f32_e32 v154, v154
	v_exp_f32_e32 v155, v155
	v_pk_fma_f32 v[148:149], v[144:145], v[198:199], v[200:201]
	v_pk_fma_f32 v[156:157], v[152:153], v[198:199], v[200:201]
	v_pk_fma_f32 v[148:149], v[148:149], v[144:145], v[202:203]
	v_pk_fma_f32 v[156:157], v[156:157], v[152:153], v[202:203]
	v_pk_fma_f32 v[148:149], v[148:149], v[144:145], v[210:211]
	v_pk_fma_f32 v[156:157], v[156:157], v[152:153], v[210:211]
	v_pk_fma_f32 v[148:149], v[148:149], v[144:145], v[212:213]
	v_pk_fma_f32 v[156:157], v[156:157], v[152:153], v[212:213]
	v_pk_mul_f32 v[148:149], v[148:149], v[144:145]
	v_pk_mul_f32 v[156:157], v[156:157], v[152:153]
	v_max_f32_e32 v150, 0, v72
	v_max_f32_e32 v151, 0, v73
	v_max_f32_e32 v166, 0, v74
	v_max_f32_e32 v167, 0, v75
	v_pk_mul_f32 v[148:149], v[148:149], v[146:147]
	v_pk_mul_f32 v[156:157], v[156:157], v[154:155]
	v_fma_f32 v72, -|v72|, v148, v150
	v_fma_f32 v73, -|v73|, v149, v151
	v_fma_f32 v74, -|v74|, v156, v166
	v_fma_f32 v75, -|v75|, v157, v167
	v_pk_fma_f32 v[226:227], v[72:73], v[72:73], v[226:227]
	v_pk_fma_f32 v[226:227], v[74:75], v[74:75], v[226:227]
	v_cvt_pk_bf16_f32 v170, v72, v73
	v_cvt_pk_bf16_f32 v171, v74, v75
	s_mul_i32 s2, s33, 0x60
	buffer_store_dwordx4 v[168:171], v216, s[72:75], s2 offen sc1
	v_fma_f32 v144, |v68|, v196, 1.0
	v_fma_f32 v145, |v69|, v196, 1.0
	v_fma_f32 v152, |v70|, v196, 1.0
	v_fma_f32 v153, |v71|, v196, 1.0
	v_pk_mul_f32 v[146:147], v[68:69], v[68:69]
	v_pk_mul_f32 v[154:155], v[70:71], v[70:71]
	v_rcp_f32_e32 v144, v144
	v_rcp_f32_e32 v145, v145
	v_rcp_f32_e32 v152, v152
	v_rcp_f32_e32 v153, v153
	v_pk_mul_f32 v[146:147], v[146:147], v[214:215]
	v_pk_mul_f32 v[154:155], v[154:155], v[214:215]
	v_exp_f32_e32 v146, v146
	v_exp_f32_e32 v147, v147
	v_exp_f32_e32 v154, v154
	v_exp_f32_e32 v155, v155
	v_pk_fma_f32 v[148:149], v[144:145], v[198:199], v[200:201]
	v_pk_fma_f32 v[156:157], v[152:153], v[198:199], v[200:201]
	v_pk_fma_f32 v[148:149], v[148:149], v[144:145], v[202:203]
	v_pk_fma_f32 v[156:157], v[156:157], v[152:153], v[202:203]
	v_pk_fma_f32 v[148:149], v[148:149], v[144:145], v[210:211]
	v_pk_fma_f32 v[156:157], v[156:157], v[152:153], v[210:211]
	v_pk_fma_f32 v[148:149], v[148:149], v[144:145], v[212:213]
	v_pk_fma_f32 v[156:157], v[156:157], v[152:153], v[212:213]
	v_pk_mul_f32 v[148:149], v[148:149], v[144:145]
	v_pk_mul_f32 v[156:157], v[156:157], v[152:153]
	v_max_f32_e32 v150, 0, v68
	v_max_f32_e32 v151, 0, v69
	v_max_f32_e32 v166, 0, v70
	v_max_f32_e32 v167, 0, v71
	v_pk_mul_f32 v[148:149], v[148:149], v[146:147]
	v_pk_mul_f32 v[156:157], v[156:157], v[154:155]
	v_fma_f32 v68, -|v68|, v148, v150
	v_fma_f32 v69, -|v69|, v149, v151
	v_fma_f32 v70, -|v70|, v156, v166
	v_fma_f32 v71, -|v71|, v157, v167
	v_pk_fma_f32 v[226:227], v[68:69], v[68:69], v[226:227]
	v_pk_fma_f32 v[226:227], v[70:71], v[70:71], v[226:227]
	v_cvt_pk_bf16_f32 v232, v68, v69
	v_cvt_pk_bf16_f32 v233, v70, v71
	v_fma_f32 v144, |v64|, v196, 1.0
	v_fma_f32 v145, |v65|, v196, 1.0
	v_fma_f32 v152, |v66|, v196, 1.0
	v_fma_f32 v153, |v67|, v196, 1.0
	v_pk_mul_f32 v[146:147], v[64:65], v[64:65]
	v_pk_mul_f32 v[154:155], v[66:67], v[66:67]
	v_rcp_f32_e32 v144, v144
	v_rcp_f32_e32 v145, v145
	v_rcp_f32_e32 v152, v152
	v_rcp_f32_e32 v153, v153
	v_pk_mul_f32 v[146:147], v[146:147], v[214:215]
	v_pk_mul_f32 v[154:155], v[154:155], v[214:215]
	v_exp_f32_e32 v146, v146
	v_exp_f32_e32 v147, v147
	v_exp_f32_e32 v154, v154
	v_exp_f32_e32 v155, v155
	v_pk_fma_f32 v[148:149], v[144:145], v[198:199], v[200:201]
	v_pk_fma_f32 v[156:157], v[152:153], v[198:199], v[200:201]
	v_pk_fma_f32 v[148:149], v[148:149], v[144:145], v[202:203]
	v_pk_fma_f32 v[156:157], v[156:157], v[152:153], v[202:203]
	v_pk_fma_f32 v[148:149], v[148:149], v[144:145], v[210:211]
	v_pk_fma_f32 v[156:157], v[156:157], v[152:153], v[210:211]
	v_pk_fma_f32 v[148:149], v[148:149], v[144:145], v[212:213]
	v_pk_fma_f32 v[156:157], v[156:157], v[152:153], v[212:213]
	v_pk_mul_f32 v[148:149], v[148:149], v[144:145]
	v_pk_mul_f32 v[156:157], v[156:157], v[152:153]
	v_max_f32_e32 v150, 0, v64
	v_max_f32_e32 v151, 0, v65
	v_max_f32_e32 v166, 0, v66
	v_max_f32_e32 v167, 0, v67
	v_pk_mul_f32 v[148:149], v[148:149], v[146:147]
	v_pk_mul_f32 v[156:157], v[156:157], v[154:155]
	v_fma_f32 v64, -|v64|, v148, v150
	v_fma_f32 v65, -|v65|, v149, v151
	v_fma_f32 v66, -|v66|, v156, v166
	v_fma_f32 v67, -|v67|, v157, v167
	v_pk_fma_f32 v[226:227], v[64:65], v[64:65], v[226:227]
	v_pk_fma_f32 v[226:227], v[66:67], v[66:67], v[226:227]
	v_cvt_pk_bf16_f32 v234, v64, v65
	v_cvt_pk_bf16_f32 v235, v66, v67
	buffer_store_dwordx4 v[232:235], v216, s[72:75], s2 offen offset:256 sc1
	v_add_f32_e32 v221, v226, v227
	v_fma_f32 v144, |v60|, v196, 1.0
	v_fma_f32 v145, |v61|, v196, 1.0
	v_fma_f32 v152, |v62|, v196, 1.0
	v_fma_f32 v153, |v63|, v196, 1.0
	v_pk_mul_f32 v[146:147], v[60:61], v[60:61]
	v_pk_mul_f32 v[154:155], v[62:63], v[62:63]
	v_rcp_f32_e32 v144, v144
	v_rcp_f32_e32 v145, v145
	v_rcp_f32_e32 v152, v152
	v_rcp_f32_e32 v153, v153
	v_pk_mul_f32 v[146:147], v[146:147], v[214:215]
	v_pk_mul_f32 v[154:155], v[154:155], v[214:215]
	v_exp_f32_e32 v146, v146
	v_exp_f32_e32 v147, v147
	v_exp_f32_e32 v154, v154
	v_exp_f32_e32 v155, v155
	v_pk_fma_f32 v[148:149], v[144:145], v[198:199], v[200:201]
	v_pk_fma_f32 v[156:157], v[152:153], v[198:199], v[200:201]
	v_pk_fma_f32 v[148:149], v[148:149], v[144:145], v[202:203]
	v_pk_fma_f32 v[156:157], v[156:157], v[152:153], v[202:203]
	v_pk_fma_f32 v[148:149], v[148:149], v[144:145], v[210:211]
	v_pk_fma_f32 v[156:157], v[156:157], v[152:153], v[210:211]
	v_pk_fma_f32 v[148:149], v[148:149], v[144:145], v[212:213]
	v_pk_fma_f32 v[156:157], v[156:157], v[152:153], v[212:213]
	v_pk_mul_f32 v[148:149], v[148:149], v[144:145]
	v_pk_mul_f32 v[156:157], v[156:157], v[152:153]
	v_max_f32_e32 v150, 0, v60
	v_max_f32_e32 v151, 0, v61
	v_max_f32_e32 v166, 0, v62
	v_max_f32_e32 v167, 0, v63
	v_pk_mul_f32 v[148:149], v[148:149], v[146:147]
	v_pk_mul_f32 v[156:157], v[156:157], v[154:155]
	v_fma_f32 v60, -|v60|, v148, v150
	v_fma_f32 v61, -|v61|, v149, v151
	v_fma_f32 v62, -|v62|, v156, v166
	v_fma_f32 v63, -|v63|, v157, v167
	v_pk_mul_f32 v[226:227], v[60:61], v[60:61]
	v_pk_fma_f32 v[226:227], v[62:63], v[62:63], v[226:227]
	v_cvt_pk_bf16_f32 v168, v60, v61
	v_cvt_pk_bf16_f32 v169, v62, v63
	v_fma_f32 v144, |v56|, v196, 1.0
	v_fma_f32 v145, |v57|, v196, 1.0
	v_fma_f32 v152, |v58|, v196, 1.0
	v_fma_f32 v153, |v59|, v196, 1.0
	v_pk_mul_f32 v[146:147], v[56:57], v[56:57]
	v_pk_mul_f32 v[154:155], v[58:59], v[58:59]
	v_rcp_f32_e32 v144, v144
	v_rcp_f32_e32 v145, v145
	v_rcp_f32_e32 v152, v152
	v_rcp_f32_e32 v153, v153
	v_pk_mul_f32 v[146:147], v[146:147], v[214:215]
	v_pk_mul_f32 v[154:155], v[154:155], v[214:215]
	v_exp_f32_e32 v146, v146
	v_exp_f32_e32 v147, v147
	v_exp_f32_e32 v154, v154
	v_exp_f32_e32 v155, v155
	v_pk_fma_f32 v[148:149], v[144:145], v[198:199], v[200:201]
	v_pk_fma_f32 v[156:157], v[152:153], v[198:199], v[200:201]
	v_pk_fma_f32 v[148:149], v[148:149], v[144:145], v[202:203]
	v_pk_fma_f32 v[156:157], v[156:157], v[152:153], v[202:203]
	v_pk_fma_f32 v[148:149], v[148:149], v[144:145], v[210:211]
	v_pk_fma_f32 v[156:157], v[156:157], v[152:153], v[210:211]
	v_pk_fma_f32 v[148:149], v[148:149], v[144:145], v[212:213]
	v_pk_fma_f32 v[156:157], v[156:157], v[152:153], v[212:213]
	v_pk_mul_f32 v[148:149], v[148:149], v[144:145]
	v_pk_mul_f32 v[156:157], v[156:157], v[152:153]
	v_max_f32_e32 v150, 0, v56
	v_max_f32_e32 v151, 0, v57
	v_max_f32_e32 v166, 0, v58
	v_max_f32_e32 v167, 0, v59
	v_pk_mul_f32 v[148:149], v[148:149], v[146:147]
	v_pk_mul_f32 v[156:157], v[156:157], v[154:155]
	v_fma_f32 v56, -|v56|, v148, v150
	v_fma_f32 v57, -|v57|, v149, v151
	v_fma_f32 v58, -|v58|, v156, v166
	v_fma_f32 v59, -|v59|, v157, v167
	v_pk_fma_f32 v[226:227], v[56:57], v[56:57], v[226:227]
	v_pk_fma_f32 v[226:227], v[58:59], v[58:59], v[226:227]
	v_cvt_pk_bf16_f32 v170, v56, v57
	v_cvt_pk_bf16_f32 v171, v58, v59
	s_mul_i32 s2, s33, 0x100
	buffer_store_dwordx4 v[168:171], v216, s[72:75], s2 offen sc1
	v_fma_f32 v144, |v52|, v196, 1.0
	v_fma_f32 v145, |v53|, v196, 1.0
	v_fma_f32 v152, |v54|, v196, 1.0
	v_fma_f32 v153, |v55|, v196, 1.0
	v_pk_mul_f32 v[146:147], v[52:53], v[52:53]
	v_pk_mul_f32 v[154:155], v[54:55], v[54:55]
	v_rcp_f32_e32 v144, v144
	v_rcp_f32_e32 v145, v145
	v_rcp_f32_e32 v152, v152
	v_rcp_f32_e32 v153, v153
	v_pk_mul_f32 v[146:147], v[146:147], v[214:215]
	v_pk_mul_f32 v[154:155], v[154:155], v[214:215]
	v_exp_f32_e32 v146, v146
	v_exp_f32_e32 v147, v147
	v_exp_f32_e32 v154, v154
	v_exp_f32_e32 v155, v155
	v_pk_fma_f32 v[148:149], v[144:145], v[198:199], v[200:201]
	v_pk_fma_f32 v[156:157], v[152:153], v[198:199], v[200:201]
	v_pk_fma_f32 v[148:149], v[148:149], v[144:145], v[202:203]
	v_pk_fma_f32 v[156:157], v[156:157], v[152:153], v[202:203]
	v_pk_fma_f32 v[148:149], v[148:149], v[144:145], v[210:211]
	v_pk_fma_f32 v[156:157], v[156:157], v[152:153], v[210:211]
	v_pk_fma_f32 v[148:149], v[148:149], v[144:145], v[212:213]
	v_pk_fma_f32 v[156:157], v[156:157], v[152:153], v[212:213]
	v_pk_mul_f32 v[148:149], v[148:149], v[144:145]
	v_pk_mul_f32 v[156:157], v[156:157], v[152:153]
	v_max_f32_e32 v150, 0, v52
	v_max_f32_e32 v151, 0, v53
	v_max_f32_e32 v166, 0, v54
	v_max_f32_e32 v167, 0, v55
	v_pk_mul_f32 v[148:149], v[148:149], v[146:147]
	v_pk_mul_f32 v[156:157], v[156:157], v[154:155]
	v_fma_f32 v52, -|v52|, v148, v150
	v_fma_f32 v53, -|v53|, v149, v151
	v_fma_f32 v54, -|v54|, v156, v166
	v_fma_f32 v55, -|v55|, v157, v167
	v_pk_fma_f32 v[226:227], v[52:53], v[52:53], v[226:227]
	v_pk_fma_f32 v[226:227], v[54:55], v[54:55], v[226:227]
	v_cvt_pk_bf16_f32 v232, v52, v53
	v_cvt_pk_bf16_f32 v233, v54, v55
	v_fma_f32 v144, |v48|, v196, 1.0
	v_fma_f32 v145, |v49|, v196, 1.0
	v_fma_f32 v152, |v50|, v196, 1.0
	v_fma_f32 v153, |v51|, v196, 1.0
	v_pk_mul_f32 v[146:147], v[48:49], v[48:49]
	v_pk_mul_f32 v[154:155], v[50:51], v[50:51]
	v_rcp_f32_e32 v144, v144
	v_rcp_f32_e32 v145, v145
	v_rcp_f32_e32 v152, v152
	v_rcp_f32_e32 v153, v153
	v_pk_mul_f32 v[146:147], v[146:147], v[214:215]
	v_pk_mul_f32 v[154:155], v[154:155], v[214:215]
	v_exp_f32_e32 v146, v146
	v_exp_f32_e32 v147, v147
	v_exp_f32_e32 v154, v154
	v_exp_f32_e32 v155, v155
	v_pk_fma_f32 v[148:149], v[144:145], v[198:199], v[200:201]
	v_pk_fma_f32 v[156:157], v[152:153], v[198:199], v[200:201]
	v_pk_fma_f32 v[148:149], v[148:149], v[144:145], v[202:203]
	v_pk_fma_f32 v[156:157], v[156:157], v[152:153], v[202:203]
	v_pk_fma_f32 v[148:149], v[148:149], v[144:145], v[210:211]
	v_pk_fma_f32 v[156:157], v[156:157], v[152:153], v[210:211]
	v_pk_fma_f32 v[148:149], v[148:149], v[144:145], v[212:213]
	v_pk_fma_f32 v[156:157], v[156:157], v[152:153], v[212:213]
	v_pk_mul_f32 v[148:149], v[148:149], v[144:145]
	v_pk_mul_f32 v[156:157], v[156:157], v[152:153]
	v_max_f32_e32 v150, 0, v48
	v_max_f32_e32 v151, 0, v49
	v_max_f32_e32 v166, 0, v50
	v_max_f32_e32 v167, 0, v51
	v_pk_mul_f32 v[148:149], v[148:149], v[146:147]
	v_pk_mul_f32 v[156:157], v[156:157], v[154:155]
	v_fma_f32 v48, -|v48|, v148, v150
	v_fma_f32 v49, -|v49|, v149, v151
	v_fma_f32 v50, -|v50|, v156, v166
	v_fma_f32 v51, -|v51|, v157, v167
	v_pk_fma_f32 v[226:227], v[48:49], v[48:49], v[226:227]
	v_pk_fma_f32 v[226:227], v[50:51], v[50:51], v[226:227]
	v_cvt_pk_bf16_f32 v234, v48, v49
	v_cvt_pk_bf16_f32 v235, v50, v51
	buffer_store_dwordx4 v[232:235], v216, s[72:75], s2 offen offset:256 sc1
	v_add_f32_e32 v222, v226, v227
	v_fma_f32 v144, |v44|, v196, 1.0
	v_fma_f32 v145, |v45|, v196, 1.0
	v_fma_f32 v152, |v46|, v196, 1.0
	v_fma_f32 v153, |v47|, v196, 1.0
	v_pk_mul_f32 v[146:147], v[44:45], v[44:45]
	v_pk_mul_f32 v[154:155], v[46:47], v[46:47]
	v_rcp_f32_e32 v144, v144
	v_rcp_f32_e32 v145, v145
	v_rcp_f32_e32 v152, v152
	v_rcp_f32_e32 v153, v153
	v_pk_mul_f32 v[146:147], v[146:147], v[214:215]
	v_pk_mul_f32 v[154:155], v[154:155], v[214:215]
	v_exp_f32_e32 v146, v146
	v_exp_f32_e32 v147, v147
	v_exp_f32_e32 v154, v154
	v_exp_f32_e32 v155, v155
	v_pk_fma_f32 v[148:149], v[144:145], v[198:199], v[200:201]
	v_pk_fma_f32 v[156:157], v[152:153], v[198:199], v[200:201]
	v_pk_fma_f32 v[148:149], v[148:149], v[144:145], v[202:203]
	v_pk_fma_f32 v[156:157], v[156:157], v[152:153], v[202:203]
	v_pk_fma_f32 v[148:149], v[148:149], v[144:145], v[210:211]
	v_pk_fma_f32 v[156:157], v[156:157], v[152:153], v[210:211]
	v_pk_fma_f32 v[148:149], v[148:149], v[144:145], v[212:213]
	v_pk_fma_f32 v[156:157], v[156:157], v[152:153], v[212:213]
	v_pk_mul_f32 v[148:149], v[148:149], v[144:145]
	v_pk_mul_f32 v[156:157], v[156:157], v[152:153]
	v_max_f32_e32 v150, 0, v44
	v_max_f32_e32 v151, 0, v45
	v_max_f32_e32 v166, 0, v46
	v_max_f32_e32 v167, 0, v47
	v_pk_mul_f32 v[148:149], v[148:149], v[146:147]
	v_pk_mul_f32 v[156:157], v[156:157], v[154:155]
	v_fma_f32 v44, -|v44|, v148, v150
	v_fma_f32 v45, -|v45|, v149, v151
	v_fma_f32 v46, -|v46|, v156, v166
	v_fma_f32 v47, -|v47|, v157, v167
	v_pk_mul_f32 v[226:227], v[44:45], v[44:45]
	v_pk_fma_f32 v[226:227], v[46:47], v[46:47], v[226:227]
	v_cvt_pk_bf16_f32 v168, v44, v45
	v_cvt_pk_bf16_f32 v169, v46, v47
	v_fma_f32 v144, |v40|, v196, 1.0
	v_fma_f32 v145, |v41|, v196, 1.0
	v_fma_f32 v152, |v42|, v196, 1.0
	v_fma_f32 v153, |v43|, v196, 1.0
	v_pk_mul_f32 v[146:147], v[40:41], v[40:41]
	v_pk_mul_f32 v[154:155], v[42:43], v[42:43]
	v_rcp_f32_e32 v144, v144
	v_rcp_f32_e32 v145, v145
	v_rcp_f32_e32 v152, v152
	v_rcp_f32_e32 v153, v153
	v_pk_mul_f32 v[146:147], v[146:147], v[214:215]
	v_pk_mul_f32 v[154:155], v[154:155], v[214:215]
	v_exp_f32_e32 v146, v146
	v_exp_f32_e32 v147, v147
	v_exp_f32_e32 v154, v154
	v_exp_f32_e32 v155, v155
	v_pk_fma_f32 v[148:149], v[144:145], v[198:199], v[200:201]
	v_pk_fma_f32 v[156:157], v[152:153], v[198:199], v[200:201]
	v_pk_fma_f32 v[148:149], v[148:149], v[144:145], v[202:203]
	v_pk_fma_f32 v[156:157], v[156:157], v[152:153], v[202:203]
	v_pk_fma_f32 v[148:149], v[148:149], v[144:145], v[210:211]
	v_pk_fma_f32 v[156:157], v[156:157], v[152:153], v[210:211]
	v_pk_fma_f32 v[148:149], v[148:149], v[144:145], v[212:213]
	v_pk_fma_f32 v[156:157], v[156:157], v[152:153], v[212:213]
	v_pk_mul_f32 v[148:149], v[148:149], v[144:145]
	v_pk_mul_f32 v[156:157], v[156:157], v[152:153]
	v_max_f32_e32 v150, 0, v40
	v_max_f32_e32 v151, 0, v41
	v_max_f32_e32 v166, 0, v42
	v_max_f32_e32 v167, 0, v43
	v_pk_mul_f32 v[148:149], v[148:149], v[146:147]
	v_pk_mul_f32 v[156:157], v[156:157], v[154:155]
	v_fma_f32 v40, -|v40|, v148, v150
	v_fma_f32 v41, -|v41|, v149, v151
	v_fma_f32 v42, -|v42|, v156, v166
	v_fma_f32 v43, -|v43|, v157, v167
	v_pk_fma_f32 v[226:227], v[40:41], v[40:41], v[226:227]
	v_pk_fma_f32 v[226:227], v[42:43], v[42:43], v[226:227]
	v_cvt_pk_bf16_f32 v170, v40, v41
	v_cvt_pk_bf16_f32 v171, v42, v43
	s_mul_i32 s2, s33, 0x120
	buffer_store_dwordx4 v[168:171], v216, s[72:75], s2 offen sc1
	v_fma_f32 v144, |v36|, v196, 1.0
	v_fma_f32 v145, |v37|, v196, 1.0
	v_fma_f32 v152, |v38|, v196, 1.0
	v_fma_f32 v153, |v39|, v196, 1.0
	v_pk_mul_f32 v[146:147], v[36:37], v[36:37]
	v_pk_mul_f32 v[154:155], v[38:39], v[38:39]
	v_rcp_f32_e32 v144, v144
	v_rcp_f32_e32 v145, v145
	v_rcp_f32_e32 v152, v152
	v_rcp_f32_e32 v153, v153
	v_pk_mul_f32 v[146:147], v[146:147], v[214:215]
	v_pk_mul_f32 v[154:155], v[154:155], v[214:215]
	v_exp_f32_e32 v146, v146
	v_exp_f32_e32 v147, v147
	v_exp_f32_e32 v154, v154
	v_exp_f32_e32 v155, v155
	v_pk_fma_f32 v[148:149], v[144:145], v[198:199], v[200:201]
	v_pk_fma_f32 v[156:157], v[152:153], v[198:199], v[200:201]
	v_pk_fma_f32 v[148:149], v[148:149], v[144:145], v[202:203]
	v_pk_fma_f32 v[156:157], v[156:157], v[152:153], v[202:203]
	v_pk_fma_f32 v[148:149], v[148:149], v[144:145], v[210:211]
	v_pk_fma_f32 v[156:157], v[156:157], v[152:153], v[210:211]
	v_pk_fma_f32 v[148:149], v[148:149], v[144:145], v[212:213]
	v_pk_fma_f32 v[156:157], v[156:157], v[152:153], v[212:213]
	v_pk_mul_f32 v[148:149], v[148:149], v[144:145]
	v_pk_mul_f32 v[156:157], v[156:157], v[152:153]
	v_max_f32_e32 v150, 0, v36
	v_max_f32_e32 v151, 0, v37
	v_max_f32_e32 v166, 0, v38
	v_max_f32_e32 v167, 0, v39
	v_pk_mul_f32 v[148:149], v[148:149], v[146:147]
	v_pk_mul_f32 v[156:157], v[156:157], v[154:155]
	v_fma_f32 v36, -|v36|, v148, v150
	v_fma_f32 v37, -|v37|, v149, v151
	v_fma_f32 v38, -|v38|, v156, v166
	v_fma_f32 v39, -|v39|, v157, v167
	v_pk_fma_f32 v[226:227], v[36:37], v[36:37], v[226:227]
	v_pk_fma_f32 v[226:227], v[38:39], v[38:39], v[226:227]
	v_cvt_pk_bf16_f32 v232, v36, v37
	v_cvt_pk_bf16_f32 v233, v38, v39
	v_fma_f32 v144, |v32|, v196, 1.0
	v_fma_f32 v145, |v33|, v196, 1.0
	v_fma_f32 v152, |v34|, v196, 1.0
	v_fma_f32 v153, |v35|, v196, 1.0
	v_pk_mul_f32 v[146:147], v[32:33], v[32:33]
	v_pk_mul_f32 v[154:155], v[34:35], v[34:35]
	v_rcp_f32_e32 v144, v144
	v_rcp_f32_e32 v145, v145
	v_rcp_f32_e32 v152, v152
	v_rcp_f32_e32 v153, v153
	v_pk_mul_f32 v[146:147], v[146:147], v[214:215]
	v_pk_mul_f32 v[154:155], v[154:155], v[214:215]
	v_exp_f32_e32 v146, v146
	v_exp_f32_e32 v147, v147
	v_exp_f32_e32 v154, v154
	v_exp_f32_e32 v155, v155
	v_pk_fma_f32 v[148:149], v[144:145], v[198:199], v[200:201]
	v_pk_fma_f32 v[156:157], v[152:153], v[198:199], v[200:201]
	v_pk_fma_f32 v[148:149], v[148:149], v[144:145], v[202:203]
	v_pk_fma_f32 v[156:157], v[156:157], v[152:153], v[202:203]
	v_pk_fma_f32 v[148:149], v[148:149], v[144:145], v[210:211]
	v_pk_fma_f32 v[156:157], v[156:157], v[152:153], v[210:211]
	v_pk_fma_f32 v[148:149], v[148:149], v[144:145], v[212:213]
	v_pk_fma_f32 v[156:157], v[156:157], v[152:153], v[212:213]
	v_pk_mul_f32 v[148:149], v[148:149], v[144:145]
	v_pk_mul_f32 v[156:157], v[156:157], v[152:153]
	v_max_f32_e32 v150, 0, v32
	v_max_f32_e32 v151, 0, v33
	v_max_f32_e32 v166, 0, v34
	v_max_f32_e32 v167, 0, v35
	v_pk_mul_f32 v[148:149], v[148:149], v[146:147]
	v_pk_mul_f32 v[156:157], v[156:157], v[154:155]
	v_fma_f32 v32, -|v32|, v148, v150
	v_fma_f32 v33, -|v33|, v149, v151
	v_fma_f32 v34, -|v34|, v156, v166
	v_fma_f32 v35, -|v35|, v157, v167
	v_pk_fma_f32 v[226:227], v[32:33], v[32:33], v[226:227]
	v_pk_fma_f32 v[226:227], v[34:35], v[34:35], v[226:227]
	v_cvt_pk_bf16_f32 v234, v32, v33
	v_cvt_pk_bf16_f32 v235, v34, v35
	buffer_store_dwordx4 v[232:235], v216, s[72:75], s2 offen offset:256 sc1
	v_add_f32_e32 v223, v226, v227
	v_fma_f32 v144, |v28|, v196, 1.0
	v_fma_f32 v145, |v29|, v196, 1.0
	v_fma_f32 v152, |v30|, v196, 1.0
	v_fma_f32 v153, |v31|, v196, 1.0
	v_pk_mul_f32 v[146:147], v[28:29], v[28:29]
	v_pk_mul_f32 v[154:155], v[30:31], v[30:31]
	v_rcp_f32_e32 v144, v144
	v_rcp_f32_e32 v145, v145
	v_rcp_f32_e32 v152, v152
	v_rcp_f32_e32 v153, v153
	v_pk_mul_f32 v[146:147], v[146:147], v[214:215]
	v_pk_mul_f32 v[154:155], v[154:155], v[214:215]
	v_exp_f32_e32 v146, v146
	v_exp_f32_e32 v147, v147
	v_exp_f32_e32 v154, v154
	v_exp_f32_e32 v155, v155
	v_pk_fma_f32 v[148:149], v[144:145], v[198:199], v[200:201]
	v_pk_fma_f32 v[156:157], v[152:153], v[198:199], v[200:201]
	v_pk_fma_f32 v[148:149], v[148:149], v[144:145], v[202:203]
	v_pk_fma_f32 v[156:157], v[156:157], v[152:153], v[202:203]
	v_pk_fma_f32 v[148:149], v[148:149], v[144:145], v[210:211]
	v_pk_fma_f32 v[156:157], v[156:157], v[152:153], v[210:211]
	v_pk_fma_f32 v[148:149], v[148:149], v[144:145], v[212:213]
	v_pk_fma_f32 v[156:157], v[156:157], v[152:153], v[212:213]
	v_pk_mul_f32 v[148:149], v[148:149], v[144:145]
	v_pk_mul_f32 v[156:157], v[156:157], v[152:153]
	v_max_f32_e32 v150, 0, v28
	v_max_f32_e32 v151, 0, v29
	v_max_f32_e32 v166, 0, v30
	v_max_f32_e32 v167, 0, v31
	v_pk_mul_f32 v[148:149], v[148:149], v[146:147]
	v_pk_mul_f32 v[156:157], v[156:157], v[154:155]
	v_fma_f32 v28, -|v28|, v148, v150
	v_fma_f32 v29, -|v29|, v149, v151
	v_fma_f32 v30, -|v30|, v156, v166
	v_fma_f32 v31, -|v31|, v157, v167
	v_pk_mul_f32 v[226:227], v[28:29], v[28:29]
	v_pk_fma_f32 v[226:227], v[30:31], v[30:31], v[226:227]
	v_cvt_pk_bf16_f32 v168, v28, v29
	v_cvt_pk_bf16_f32 v169, v30, v31
	v_fma_f32 v144, |v24|, v196, 1.0
	v_fma_f32 v145, |v25|, v196, 1.0
	v_fma_f32 v152, |v26|, v196, 1.0
	v_fma_f32 v153, |v27|, v196, 1.0
	v_pk_mul_f32 v[146:147], v[24:25], v[24:25]
	v_pk_mul_f32 v[154:155], v[26:27], v[26:27]
	v_rcp_f32_e32 v144, v144
	v_rcp_f32_e32 v145, v145
	v_rcp_f32_e32 v152, v152
	v_rcp_f32_e32 v153, v153
	v_pk_mul_f32 v[146:147], v[146:147], v[214:215]
	v_pk_mul_f32 v[154:155], v[154:155], v[214:215]
	v_exp_f32_e32 v146, v146
	v_exp_f32_e32 v147, v147
	v_exp_f32_e32 v154, v154
	v_exp_f32_e32 v155, v155
	v_pk_fma_f32 v[148:149], v[144:145], v[198:199], v[200:201]
	v_pk_fma_f32 v[156:157], v[152:153], v[198:199], v[200:201]
	v_pk_fma_f32 v[148:149], v[148:149], v[144:145], v[202:203]
	v_pk_fma_f32 v[156:157], v[156:157], v[152:153], v[202:203]
	v_pk_fma_f32 v[148:149], v[148:149], v[144:145], v[210:211]
	v_pk_fma_f32 v[156:157], v[156:157], v[152:153], v[210:211]
	v_pk_fma_f32 v[148:149], v[148:149], v[144:145], v[212:213]
	v_pk_fma_f32 v[156:157], v[156:157], v[152:153], v[212:213]
	v_pk_mul_f32 v[148:149], v[148:149], v[144:145]
	v_pk_mul_f32 v[156:157], v[156:157], v[152:153]
	v_max_f32_e32 v150, 0, v24
	v_max_f32_e32 v151, 0, v25
	v_max_f32_e32 v166, 0, v26
	v_max_f32_e32 v167, 0, v27
	v_pk_mul_f32 v[148:149], v[148:149], v[146:147]
	v_pk_mul_f32 v[156:157], v[156:157], v[154:155]
	v_fma_f32 v24, -|v24|, v148, v150
	v_fma_f32 v25, -|v25|, v149, v151
	v_fma_f32 v26, -|v26|, v156, v166
	v_fma_f32 v27, -|v27|, v157, v167
	v_pk_fma_f32 v[226:227], v[24:25], v[24:25], v[226:227]
	v_pk_fma_f32 v[226:227], v[26:27], v[26:27], v[226:227]
	v_cvt_pk_bf16_f32 v170, v24, v25
	v_cvt_pk_bf16_f32 v171, v26, v27
	s_mul_i32 s2, s33, 0x140
	buffer_store_dwordx4 v[168:171], v216, s[72:75], s2 offen sc1
	v_fma_f32 v144, |v20|, v196, 1.0
	v_fma_f32 v145, |v21|, v196, 1.0
	v_fma_f32 v152, |v22|, v196, 1.0
	v_fma_f32 v153, |v23|, v196, 1.0
	v_pk_mul_f32 v[146:147], v[20:21], v[20:21]
	v_pk_mul_f32 v[154:155], v[22:23], v[22:23]
	v_rcp_f32_e32 v144, v144
	v_rcp_f32_e32 v145, v145
	v_rcp_f32_e32 v152, v152
	v_rcp_f32_e32 v153, v153
	v_pk_mul_f32 v[146:147], v[146:147], v[214:215]
	v_pk_mul_f32 v[154:155], v[154:155], v[214:215]
	v_exp_f32_e32 v146, v146
	v_exp_f32_e32 v147, v147
	v_exp_f32_e32 v154, v154
	v_exp_f32_e32 v155, v155
	v_pk_fma_f32 v[148:149], v[144:145], v[198:199], v[200:201]
	v_pk_fma_f32 v[156:157], v[152:153], v[198:199], v[200:201]
	v_pk_fma_f32 v[148:149], v[148:149], v[144:145], v[202:203]
	v_pk_fma_f32 v[156:157], v[156:157], v[152:153], v[202:203]
	v_pk_fma_f32 v[148:149], v[148:149], v[144:145], v[210:211]
	v_pk_fma_f32 v[156:157], v[156:157], v[152:153], v[210:211]
	v_pk_fma_f32 v[148:149], v[148:149], v[144:145], v[212:213]
	v_pk_fma_f32 v[156:157], v[156:157], v[152:153], v[212:213]
	v_pk_mul_f32 v[148:149], v[148:149], v[144:145]
	v_pk_mul_f32 v[156:157], v[156:157], v[152:153]
	v_max_f32_e32 v150, 0, v20
	v_max_f32_e32 v151, 0, v21
	v_max_f32_e32 v166, 0, v22
	v_max_f32_e32 v167, 0, v23
	v_pk_mul_f32 v[148:149], v[148:149], v[146:147]
	v_pk_mul_f32 v[156:157], v[156:157], v[154:155]
	v_fma_f32 v20, -|v20|, v148, v150
	v_fma_f32 v21, -|v21|, v149, v151
	v_fma_f32 v22, -|v22|, v156, v166
	v_fma_f32 v23, -|v23|, v157, v167
	v_pk_fma_f32 v[226:227], v[20:21], v[20:21], v[226:227]
	v_pk_fma_f32 v[226:227], v[22:23], v[22:23], v[226:227]
	v_cvt_pk_bf16_f32 v232, v20, v21
	v_cvt_pk_bf16_f32 v233, v22, v23
	v_fma_f32 v144, |v16|, v196, 1.0
	v_fma_f32 v145, |v17|, v196, 1.0
	v_fma_f32 v152, |v18|, v196, 1.0
	v_fma_f32 v153, |v19|, v196, 1.0
	v_pk_mul_f32 v[146:147], v[16:17], v[16:17]
	v_pk_mul_f32 v[154:155], v[18:19], v[18:19]
	v_rcp_f32_e32 v144, v144
	v_rcp_f32_e32 v145, v145
	v_rcp_f32_e32 v152, v152
	v_rcp_f32_e32 v153, v153
	v_pk_mul_f32 v[146:147], v[146:147], v[214:215]
	v_pk_mul_f32 v[154:155], v[154:155], v[214:215]
	v_exp_f32_e32 v146, v146
	v_exp_f32_e32 v147, v147
	v_exp_f32_e32 v154, v154
	v_exp_f32_e32 v155, v155
	v_pk_fma_f32 v[148:149], v[144:145], v[198:199], v[200:201]
	v_pk_fma_f32 v[156:157], v[152:153], v[198:199], v[200:201]
	v_pk_fma_f32 v[148:149], v[148:149], v[144:145], v[202:203]
	v_pk_fma_f32 v[156:157], v[156:157], v[152:153], v[202:203]
	v_pk_fma_f32 v[148:149], v[148:149], v[144:145], v[210:211]
	v_pk_fma_f32 v[156:157], v[156:157], v[152:153], v[210:211]
	v_pk_fma_f32 v[148:149], v[148:149], v[144:145], v[212:213]
	v_pk_fma_f32 v[156:157], v[156:157], v[152:153], v[212:213]
	v_pk_mul_f32 v[148:149], v[148:149], v[144:145]
	v_pk_mul_f32 v[156:157], v[156:157], v[152:153]
	v_max_f32_e32 v150, 0, v16
	v_max_f32_e32 v151, 0, v17
	v_max_f32_e32 v166, 0, v18
	v_max_f32_e32 v167, 0, v19
	v_pk_mul_f32 v[148:149], v[148:149], v[146:147]
	v_pk_mul_f32 v[156:157], v[156:157], v[154:155]
	v_fma_f32 v16, -|v16|, v148, v150
	v_fma_f32 v17, -|v17|, v149, v151
	v_fma_f32 v18, -|v18|, v156, v166
	v_fma_f32 v19, -|v19|, v157, v167
	v_pk_fma_f32 v[226:227], v[16:17], v[16:17], v[226:227]
	v_pk_fma_f32 v[226:227], v[18:19], v[18:19], v[226:227]
	v_cvt_pk_bf16_f32 v234, v16, v17
	v_cvt_pk_bf16_f32 v235, v18, v19
	buffer_store_dwordx4 v[232:235], v216, s[72:75], s2 offen offset:256 sc1
	v_add_f32_e32 v224, v226, v227
	v_fma_f32 v144, |v12|, v196, 1.0
	v_fma_f32 v145, |v13|, v196, 1.0
	v_fma_f32 v152, |v14|, v196, 1.0
	v_fma_f32 v153, |v15|, v196, 1.0
	v_pk_mul_f32 v[146:147], v[12:13], v[12:13]
	v_pk_mul_f32 v[154:155], v[14:15], v[14:15]
	v_rcp_f32_e32 v144, v144
	v_rcp_f32_e32 v145, v145
	v_rcp_f32_e32 v152, v152
	v_rcp_f32_e32 v153, v153
	v_pk_mul_f32 v[146:147], v[146:147], v[214:215]
	v_pk_mul_f32 v[154:155], v[154:155], v[214:215]
	v_exp_f32_e32 v146, v146
	v_exp_f32_e32 v147, v147
	v_exp_f32_e32 v154, v154
	v_exp_f32_e32 v155, v155
	v_pk_fma_f32 v[148:149], v[144:145], v[198:199], v[200:201]
	v_pk_fma_f32 v[156:157], v[152:153], v[198:199], v[200:201]
	v_pk_fma_f32 v[148:149], v[148:149], v[144:145], v[202:203]
	v_pk_fma_f32 v[156:157], v[156:157], v[152:153], v[202:203]
	v_pk_fma_f32 v[148:149], v[148:149], v[144:145], v[210:211]
	v_pk_fma_f32 v[156:157], v[156:157], v[152:153], v[210:211]
	v_pk_fma_f32 v[148:149], v[148:149], v[144:145], v[212:213]
	v_pk_fma_f32 v[156:157], v[156:157], v[152:153], v[212:213]
	v_pk_mul_f32 v[148:149], v[148:149], v[144:145]
	v_pk_mul_f32 v[156:157], v[156:157], v[152:153]
	v_max_f32_e32 v150, 0, v12
	v_max_f32_e32 v151, 0, v13
	v_max_f32_e32 v166, 0, v14
	v_max_f32_e32 v167, 0, v15
	v_pk_mul_f32 v[148:149], v[148:149], v[146:147]
	v_pk_mul_f32 v[156:157], v[156:157], v[154:155]
	v_fma_f32 v12, -|v12|, v148, v150
	v_fma_f32 v13, -|v13|, v149, v151
	v_fma_f32 v14, -|v14|, v156, v166
	v_fma_f32 v15, -|v15|, v157, v167
	v_pk_mul_f32 v[226:227], v[12:13], v[12:13]
	v_pk_fma_f32 v[226:227], v[14:15], v[14:15], v[226:227]
	v_cvt_pk_bf16_f32 v168, v12, v13
	v_cvt_pk_bf16_f32 v169, v14, v15
	v_fma_f32 v144, |v8|, v196, 1.0
	v_fma_f32 v145, |v9|, v196, 1.0
	v_fma_f32 v152, |v10|, v196, 1.0
	v_fma_f32 v153, |v11|, v196, 1.0
	v_pk_mul_f32 v[146:147], v[8:9], v[8:9]
	v_pk_mul_f32 v[154:155], v[10:11], v[10:11]
	v_rcp_f32_e32 v144, v144
	v_rcp_f32_e32 v145, v145
	v_rcp_f32_e32 v152, v152
	v_rcp_f32_e32 v153, v153
	v_pk_mul_f32 v[146:147], v[146:147], v[214:215]
	v_pk_mul_f32 v[154:155], v[154:155], v[214:215]
	v_exp_f32_e32 v146, v146
	v_exp_f32_e32 v147, v147
	v_exp_f32_e32 v154, v154
	v_exp_f32_e32 v155, v155
	v_pk_fma_f32 v[148:149], v[144:145], v[198:199], v[200:201]
	v_pk_fma_f32 v[156:157], v[152:153], v[198:199], v[200:201]
	v_pk_fma_f32 v[148:149], v[148:149], v[144:145], v[202:203]
	v_pk_fma_f32 v[156:157], v[156:157], v[152:153], v[202:203]
	v_pk_fma_f32 v[148:149], v[148:149], v[144:145], v[210:211]
	v_pk_fma_f32 v[156:157], v[156:157], v[152:153], v[210:211]
	v_pk_fma_f32 v[148:149], v[148:149], v[144:145], v[212:213]
	v_pk_fma_f32 v[156:157], v[156:157], v[152:153], v[212:213]
	v_pk_mul_f32 v[148:149], v[148:149], v[144:145]
	v_pk_mul_f32 v[156:157], v[156:157], v[152:153]
	v_max_f32_e32 v150, 0, v8
	v_max_f32_e32 v151, 0, v9
	v_max_f32_e32 v166, 0, v10
	v_max_f32_e32 v167, 0, v11
	v_pk_mul_f32 v[148:149], v[148:149], v[146:147]
	v_pk_mul_f32 v[156:157], v[156:157], v[154:155]
	v_fma_f32 v8, -|v8|, v148, v150
	v_fma_f32 v9, -|v9|, v149, v151
	v_fma_f32 v10, -|v10|, v156, v166
	v_fma_f32 v11, -|v11|, v157, v167
	v_pk_fma_f32 v[226:227], v[8:9], v[8:9], v[226:227]
	v_pk_fma_f32 v[226:227], v[10:11], v[10:11], v[226:227]
	v_cvt_pk_bf16_f32 v170, v8, v9
	v_cvt_pk_bf16_f32 v171, v10, v11
	s_mul_i32 s2, s33, 0x160
	buffer_store_dwordx4 v[168:171], v216, s[72:75], s2 offen sc1
	v_fma_f32 v144, |v4|, v196, 1.0
	v_fma_f32 v145, |v5|, v196, 1.0
	v_fma_f32 v152, |v6|, v196, 1.0
	v_fma_f32 v153, |v7|, v196, 1.0
	v_pk_mul_f32 v[146:147], v[4:5], v[4:5]
	v_pk_mul_f32 v[154:155], v[6:7], v[6:7]
	v_rcp_f32_e32 v144, v144
	v_rcp_f32_e32 v145, v145
	v_rcp_f32_e32 v152, v152
	v_rcp_f32_e32 v153, v153
	v_pk_mul_f32 v[146:147], v[146:147], v[214:215]
	v_pk_mul_f32 v[154:155], v[154:155], v[214:215]
	v_exp_f32_e32 v146, v146
	v_exp_f32_e32 v147, v147
	v_exp_f32_e32 v154, v154
	v_exp_f32_e32 v155, v155
	v_pk_fma_f32 v[148:149], v[144:145], v[198:199], v[200:201]
	v_pk_fma_f32 v[156:157], v[152:153], v[198:199], v[200:201]
	v_pk_fma_f32 v[148:149], v[148:149], v[144:145], v[202:203]
	v_pk_fma_f32 v[156:157], v[156:157], v[152:153], v[202:203]
	v_pk_fma_f32 v[148:149], v[148:149], v[144:145], v[210:211]
	v_pk_fma_f32 v[156:157], v[156:157], v[152:153], v[210:211]
	v_pk_fma_f32 v[148:149], v[148:149], v[144:145], v[212:213]
	v_pk_fma_f32 v[156:157], v[156:157], v[152:153], v[212:213]
	v_pk_mul_f32 v[148:149], v[148:149], v[144:145]
	v_pk_mul_f32 v[156:157], v[156:157], v[152:153]
	v_max_f32_e32 v150, 0, v4
	v_max_f32_e32 v151, 0, v5
	v_max_f32_e32 v166, 0, v6
	v_max_f32_e32 v167, 0, v7
	v_pk_mul_f32 v[148:149], v[148:149], v[146:147]
	v_pk_mul_f32 v[156:157], v[156:157], v[154:155]
	v_fma_f32 v4, -|v4|, v148, v150
	v_fma_f32 v5, -|v5|, v149, v151
	v_fma_f32 v6, -|v6|, v156, v166
	v_fma_f32 v7, -|v7|, v157, v167
	v_pk_fma_f32 v[226:227], v[4:5], v[4:5], v[226:227]
	v_pk_fma_f32 v[226:227], v[6:7], v[6:7], v[226:227]
	v_cvt_pk_bf16_f32 v232, v4, v5
	v_cvt_pk_bf16_f32 v233, v6, v7
	v_fma_f32 v144, |v0|, v196, 1.0
	v_fma_f32 v145, |v1|, v196, 1.0
	v_fma_f32 v152, |v2|, v196, 1.0
	v_fma_f32 v153, |v3|, v196, 1.0
	v_pk_mul_f32 v[146:147], v[0:1], v[0:1]
	v_pk_mul_f32 v[154:155], v[2:3], v[2:3]
	v_rcp_f32_e32 v144, v144
	v_rcp_f32_e32 v145, v145
	v_rcp_f32_e32 v152, v152
	v_rcp_f32_e32 v153, v153
	v_pk_mul_f32 v[146:147], v[146:147], v[214:215]
	v_pk_mul_f32 v[154:155], v[154:155], v[214:215]
	v_exp_f32_e32 v146, v146
	v_exp_f32_e32 v147, v147
	v_exp_f32_e32 v154, v154
	v_exp_f32_e32 v155, v155
	v_pk_fma_f32 v[148:149], v[144:145], v[198:199], v[200:201]
	v_pk_fma_f32 v[156:157], v[152:153], v[198:199], v[200:201]
	v_pk_fma_f32 v[148:149], v[148:149], v[144:145], v[202:203]
	v_pk_fma_f32 v[156:157], v[156:157], v[152:153], v[202:203]
	v_pk_fma_f32 v[148:149], v[148:149], v[144:145], v[210:211]
	v_pk_fma_f32 v[156:157], v[156:157], v[152:153], v[210:211]
	v_pk_fma_f32 v[148:149], v[148:149], v[144:145], v[212:213]
	v_pk_fma_f32 v[156:157], v[156:157], v[152:153], v[212:213]
	v_pk_mul_f32 v[148:149], v[148:149], v[144:145]
	v_pk_mul_f32 v[156:157], v[156:157], v[152:153]
	v_max_f32_e32 v150, 0, v0
	v_max_f32_e32 v151, 0, v1
	v_max_f32_e32 v166, 0, v2
	v_max_f32_e32 v167, 0, v3
	v_pk_mul_f32 v[148:149], v[148:149], v[146:147]
	v_pk_mul_f32 v[156:157], v[156:157], v[154:155]
	v_fma_f32 v0, -|v0|, v148, v150
	v_fma_f32 v1, -|v1|, v149, v151
	v_fma_f32 v2, -|v2|, v156, v166
	v_fma_f32 v3, -|v3|, v157, v167
	v_pk_fma_f32 v[226:227], v[0:1], v[0:1], v[226:227]
	v_pk_fma_f32 v[226:227], v[2:3], v[2:3], v[226:227]
	v_cvt_pk_bf16_f32 v234, v0, v1
	v_cvt_pk_bf16_f32 v235, v2, v3
	buffer_store_dwordx4 v[232:235], v216, s[72:75], s2 offen offset:256 sc1
	v_add_f32_e32 v225, v226, v227
	s_cmp_ge_i32 s18, s58
	s_cselect_b64 s[2:3], -1, 0
	s_and_b64 s[2:3], s[2:3], s[22:23]
	s_and_b64 vcc, exec, s[2:3]
	s_cbranch_vccz .LBB0_509
	v_xor_b32_e32 v228, 16, v177
	v_xor_b32_e32 v229, 32, v177
	v_lshlrev_b32_e32 v228, 2, v228
	v_lshlrev_b32_e32 v229, 2, v229
	ds_bpermute_b32 v144, v228, v218
	ds_bpermute_b32 v145, v228, v219
	ds_bpermute_b32 v146, v228, v220
	ds_bpermute_b32 v147, v228, v221
	ds_bpermute_b32 v148, v228, v222
	ds_bpermute_b32 v149, v228, v223
	ds_bpermute_b32 v150, v228, v224
	ds_bpermute_b32 v151, v228, v225
	s_waitcnt lgkmcnt(0)
	v_add_f32_e32 v218, v218, v144
	v_add_f32_e32 v219, v219, v145
	v_add_f32_e32 v220, v220, v146
	v_add_f32_e32 v221, v221, v147
	v_add_f32_e32 v222, v222, v148
	v_add_f32_e32 v223, v223, v149
	v_add_f32_e32 v224, v224, v150
	v_add_f32_e32 v225, v225, v151
	ds_bpermute_b32 v144, v229, v218
	ds_bpermute_b32 v145, v229, v219
	ds_bpermute_b32 v146, v229, v220
	ds_bpermute_b32 v147, v229, v221
	ds_bpermute_b32 v148, v229, v222
	ds_bpermute_b32 v149, v229, v223
	ds_bpermute_b32 v150, v229, v224
	ds_bpermute_b32 v151, v229, v225
	s_sub_i32 s2, s18, s58
	s_lshl_b32 s2, s2, 2
	s_or_b32 s2, s2, s62
	s_ashr_i32 s3, s2, 31
	s_lshl_b64 s[2:3], s[2:3], 17
	s_add_u32 s2, s48, s2
	s_addc_u32 s3, s49, s3
	v_mov_b32_e32 v237, 0
	v_lshl_add_u64 v[230:231], v[236:237], 2, s[2:3]
	s_waitcnt lgkmcnt(0)
	v_add_f32_e32 v218, v218, v144
	v_add_f32_e32 v219, v219, v145
	v_add_f32_e32 v220, v220, v146
	v_add_f32_e32 v221, v221, v147
	v_add_f32_e32 v222, v222, v148
	v_add_f32_e32 v223, v223, v149
	v_add_f32_e32 v224, v224, v150
	v_add_f32_e32 v225, v225, v151
	s_mov_b64 exec, 0xffff
	global_store_dword v[230:231], v218, off sc1
	global_store_dword v[230:231], v219, off offset:64 sc1
	global_store_dword v[230:231], v220, off offset:128 sc1
	global_store_dword v[230:231], v221, off offset:192 sc1
	global_store_dword v[230:231], v222, off offset:512 sc1
	global_store_dword v[230:231], v223, off offset:576 sc1
	global_store_dword v[230:231], v224, off offset:640 sc1
	global_store_dword v[230:231], v225, off offset:704 sc1
	s_mov_b64 exec, -1
	s_branch .LBB0_509
.Lepi_notgelu:
	s_cmp_lg_u32 s95, 2
	s_cbranch_scc1 .Lepi_generic
	s_or_b64 s[2:3], s[24:25], s[22:23]
	s_and_b64 vcc, exec, s[2:3]
	s_cbranch_vccnz .Lepi_generic
	s_and_b64 vcc, exec, s[26:27]
	s_cbranch_vccz .Lepi_generic
	v_lshl_add_u32 v156, s6, 8, v163
	s_lshl_b32 s2, s18, 8
	s_or_b32 s2, s2, s38
	v_or_b32_e32 v157, s2, v137
	v_mul_lo_u32 v156, v156, s33
	v_add_lshl_u32 v156, v156, v157, 1
	v_max_f32_e32 v124, 0, v124
	v_max_f32_e32 v125, 0, v125
	v_max_f32_e32 v126, 0, v126
	v_max_f32_e32 v127, 0, v127
	v_max_f32_e32 v120, 0, v120
	v_max_f32_e32 v121, 0, v121
	v_max_f32_e32 v122, 0, v122
	v_max_f32_e32 v123, 0, v123
	v_mul_f32_e32 v124, v124, v124
	v_mul_f32_e32 v125, v125, v125
	v_mul_f32_e32 v126, v126, v126
	v_mul_f32_e32 v127, v127, v127
	v_mul_f32_e32 v120, v120, v120
	v_mul_f32_e32 v121, v121, v121
	v_mul_f32_e32 v122, v122, v122
	v_mul_f32_e32 v123, v123, v123
	v_cvt_pk_bf16_f32 v144, v124, v125
	v_cvt_pk_bf16_f32 v145, v126, v127
	v_cvt_pk_bf16_f32 v146, v120, v121
	v_cvt_pk_bf16_f32 v147, v122, v123
	buffer_store_dwordx4 v[144:147], v156, s[72:75], 0 offen sc1
	v_max_f32_e32 v116, 0, v116
	v_max_f32_e32 v117, 0, v117
	v_max_f32_e32 v118, 0, v118
	v_max_f32_e32 v119, 0, v119
	v_max_f32_e32 v112, 0, v112
	v_max_f32_e32 v113, 0, v113
	v_max_f32_e32 v114, 0, v114
	v_max_f32_e32 v115, 0, v115
	v_mul_f32_e32 v116, v116, v116
	v_mul_f32_e32 v117, v117, v117
	v_mul_f32_e32 v118, v118, v118
	v_mul_f32_e32 v119, v119, v119
	v_mul_f32_e32 v112, v112, v112
	v_mul_f32_e32 v113, v113, v113
	v_mul_f32_e32 v114, v114, v114
	v_mul_f32_e32 v115, v115, v115
	v_cvt_pk_bf16_f32 v152, v116, v117
	v_cvt_pk_bf16_f32 v153, v118, v119
	v_cvt_pk_bf16_f32 v154, v112, v113
	v_cvt_pk_bf16_f32 v155, v114, v115
	buffer_store_dwordx4 v[152:155], v156, s[72:75], 0 offen offset:256 sc1
	s_mul_i32 s2, s33, 0x20
	v_max_f32_e32 v108, 0, v108
	v_max_f32_e32 v109, 0, v109
	v_max_f32_e32 v110, 0, v110
	v_max_f32_e32 v111, 0, v111
	v_max_f32_e32 v104, 0, v104
	v_max_f32_e32 v105, 0, v105
	v_max_f32_e32 v106, 0, v106
	v_max_f32_e32 v107, 0, v107
	v_mul_f32_e32 v108, v108, v108
	v_mul_f32_e32 v109, v109, v109
	v_mul_f32_e32 v110, v110, v110
	v_mul_f32_e32 v111, v111, v111
	v_mul_f32_e32 v104, v104, v104
	v_mul_f32_e32 v105, v105, v105
	v_mul_f32_e32 v106, v106, v106
	v_mul_f32_e32 v107, v107, v107
	v_cvt_pk_bf16_f32 v144, v108, v109
	v_cvt_pk_bf16_f32 v145, v110, v111
	v_cvt_pk_bf16_f32 v146, v104, v105
	v_cvt_pk_bf16_f32 v147, v106, v107
	buffer_store_dwordx4 v[144:147], v156, s[72:75], s2 offen sc1
	v_max_f32_e32 v100, 0, v100
	v_max_f32_e32 v101, 0, v101
	v_max_f32_e32 v102, 0, v102
	v_max_f32_e32 v103, 0, v103
	v_max_f32_e32 v96, 0, v96
	v_max_f32_e32 v97, 0, v97
	v_max_f32_e32 v98, 0, v98
	v_max_f32_e32 v99, 0, v99
	v_mul_f32_e32 v100, v100, v100
	v_mul_f32_e32 v101, v101, v101
	v_mul_f32_e32 v102, v102, v102
	v_mul_f32_e32 v103, v103, v103
	v_mul_f32_e32 v96, v96, v96
	v_mul_f32_e32 v97, v97, v97
	v_mul_f32_e32 v98, v98, v98
	v_mul_f32_e32 v99, v99, v99
	v_cvt_pk_bf16_f32 v152, v100, v101
	v_cvt_pk_bf16_f32 v153, v102, v103
	v_cvt_pk_bf16_f32 v154, v96, v97
	v_cvt_pk_bf16_f32 v155, v98, v99
	buffer_store_dwordx4 v[152:155], v156, s[72:75], s2 offen offset:256 sc1
	s_mul_i32 s2, s33, 0x40
	v_max_f32_e32 v92, 0, v92
	v_max_f32_e32 v93, 0, v93
	v_max_f32_e32 v94, 0, v94
	v_max_f32_e32 v95, 0, v95
	v_max_f32_e32 v88, 0, v88
	v_max_f32_e32 v89, 0, v89
	v_max_f32_e32 v90, 0, v90
	v_max_f32_e32 v91, 0, v91
	v_mul_f32_e32 v92, v92, v92
	v_mul_f32_e32 v93, v93, v93
	v_mul_f32_e32 v94, v94, v94
	v_mul_f32_e32 v95, v95, v95
	v_mul_f32_e32 v88, v88, v88
	v_mul_f32_e32 v89, v89, v89
	v_mul_f32_e32 v90, v90, v90
	v_mul_f32_e32 v91, v91, v91
	v_cvt_pk_bf16_f32 v144, v92, v93
	v_cvt_pk_bf16_f32 v145, v94, v95
	v_cvt_pk_bf16_f32 v146, v88, v89
	v_cvt_pk_bf16_f32 v147, v90, v91
	buffer_store_dwordx4 v[144:147], v156, s[72:75], s2 offen sc1
	v_max_f32_e32 v84, 0, v84
	v_max_f32_e32 v85, 0, v85
	v_max_f32_e32 v86, 0, v86
	v_max_f32_e32 v87, 0, v87
	v_max_f32_e32 v80, 0, v80
	v_max_f32_e32 v81, 0, v81
	v_max_f32_e32 v82, 0, v82
	v_max_f32_e32 v83, 0, v83
	v_mul_f32_e32 v84, v84, v84
	v_mul_f32_e32 v85, v85, v85
	v_mul_f32_e32 v86, v86, v86
	v_mul_f32_e32 v87, v87, v87
	v_mul_f32_e32 v80, v80, v80
	v_mul_f32_e32 v81, v81, v81
	v_mul_f32_e32 v82, v82, v82
	v_mul_f32_e32 v83, v83, v83
	v_cvt_pk_bf16_f32 v152, v84, v85
	v_cvt_pk_bf16_f32 v153, v86, v87
	v_cvt_pk_bf16_f32 v154, v80, v81
	v_cvt_pk_bf16_f32 v155, v82, v83
	buffer_store_dwordx4 v[152:155], v156, s[72:75], s2 offen offset:256 sc1
	s_mul_i32 s2, s33, 0x60
	v_max_f32_e32 v76, 0, v76
	v_max_f32_e32 v77, 0, v77
	v_max_f32_e32 v78, 0, v78
	v_max_f32_e32 v79, 0, v79
	v_max_f32_e32 v72, 0, v72
	v_max_f32_e32 v73, 0, v73
	v_max_f32_e32 v74, 0, v74
	v_max_f32_e32 v75, 0, v75
	v_mul_f32_e32 v76, v76, v76
	v_mul_f32_e32 v77, v77, v77
	v_mul_f32_e32 v78, v78, v78
	v_mul_f32_e32 v79, v79, v79
	v_mul_f32_e32 v72, v72, v72
	v_mul_f32_e32 v73, v73, v73
	v_mul_f32_e32 v74, v74, v74
	v_mul_f32_e32 v75, v75, v75
	v_cvt_pk_bf16_f32 v144, v76, v77
	v_cvt_pk_bf16_f32 v145, v78, v79
	v_cvt_pk_bf16_f32 v146, v72, v73
	v_cvt_pk_bf16_f32 v147, v74, v75
	buffer_store_dwordx4 v[144:147], v156, s[72:75], s2 offen sc1
	v_max_f32_e32 v68, 0, v68
	v_max_f32_e32 v69, 0, v69
	v_max_f32_e32 v70, 0, v70
	v_max_f32_e32 v71, 0, v71
	v_max_f32_e32 v64, 0, v64
	v_max_f32_e32 v65, 0, v65
	v_max_f32_e32 v66, 0, v66
	v_max_f32_e32 v67, 0, v67
	v_mul_f32_e32 v68, v68, v68
	v_mul_f32_e32 v69, v69, v69
	v_mul_f32_e32 v70, v70, v70
	v_mul_f32_e32 v71, v71, v71
	v_mul_f32_e32 v64, v64, v64
	v_mul_f32_e32 v65, v65, v65
	v_mul_f32_e32 v66, v66, v66
	v_mul_f32_e32 v67, v67, v67
	v_cvt_pk_bf16_f32 v152, v68, v69
	v_cvt_pk_bf16_f32 v153, v70, v71
	v_cvt_pk_bf16_f32 v154, v64, v65
	v_cvt_pk_bf16_f32 v155, v66, v67
	buffer_store_dwordx4 v[152:155], v156, s[72:75], s2 offen offset:256 sc1
	s_mul_i32 s2, s33, 0x100
	v_max_f32_e32 v60, 0, v60
	v_max_f32_e32 v61, 0, v61
	v_max_f32_e32 v62, 0, v62
	v_max_f32_e32 v63, 0, v63
	v_max_f32_e32 v56, 0, v56
	v_max_f32_e32 v57, 0, v57
	v_max_f32_e32 v58, 0, v58
	v_max_f32_e32 v59, 0, v59
	v_mul_f32_e32 v60, v60, v60
	v_mul_f32_e32 v61, v61, v61
	v_mul_f32_e32 v62, v62, v62
	v_mul_f32_e32 v63, v63, v63
	v_mul_f32_e32 v56, v56, v56
	v_mul_f32_e32 v57, v57, v57
	v_mul_f32_e32 v58, v58, v58
	v_mul_f32_e32 v59, v59, v59
	v_cvt_pk_bf16_f32 v144, v60, v61
	v_cvt_pk_bf16_f32 v145, v62, v63
	v_cvt_pk_bf16_f32 v146, v56, v57
	v_cvt_pk_bf16_f32 v147, v58, v59
	buffer_store_dwordx4 v[144:147], v156, s[72:75], s2 offen sc1
	v_max_f32_e32 v52, 0, v52
	v_max_f32_e32 v53, 0, v53
	v_max_f32_e32 v54, 0, v54
	v_max_f32_e32 v55, 0, v55
	v_max_f32_e32 v48, 0, v48
	v_max_f32_e32 v49, 0, v49
	v_max_f32_e32 v50, 0, v50
	v_max_f32_e32 v51, 0, v51
	v_mul_f32_e32 v52, v52, v52
	v_mul_f32_e32 v53, v53, v53
	v_mul_f32_e32 v54, v54, v54
	v_mul_f32_e32 v55, v55, v55
	v_mul_f32_e32 v48, v48, v48
	v_mul_f32_e32 v49, v49, v49
	v_mul_f32_e32 v50, v50, v50
	v_mul_f32_e32 v51, v51, v51
	v_cvt_pk_bf16_f32 v152, v52, v53
	v_cvt_pk_bf16_f32 v153, v54, v55
	v_cvt_pk_bf16_f32 v154, v48, v49
	v_cvt_pk_bf16_f32 v155, v50, v51
	buffer_store_dwordx4 v[152:155], v156, s[72:75], s2 offen offset:256 sc1
	s_mul_i32 s2, s33, 0x120
	v_max_f32_e32 v44, 0, v44
	v_max_f32_e32 v45, 0, v45
	v_max_f32_e32 v46, 0, v46
	v_max_f32_e32 v47, 0, v47
	v_max_f32_e32 v40, 0, v40
	v_max_f32_e32 v41, 0, v41
	v_max_f32_e32 v42, 0, v42
	v_max_f32_e32 v43, 0, v43
	v_mul_f32_e32 v44, v44, v44
	v_mul_f32_e32 v45, v45, v45
	v_mul_f32_e32 v46, v46, v46
	v_mul_f32_e32 v47, v47, v47
	v_mul_f32_e32 v40, v40, v40
	v_mul_f32_e32 v41, v41, v41
	v_mul_f32_e32 v42, v42, v42
	v_mul_f32_e32 v43, v43, v43
	v_cvt_pk_bf16_f32 v144, v44, v45
	v_cvt_pk_bf16_f32 v145, v46, v47
	v_cvt_pk_bf16_f32 v146, v40, v41
	v_cvt_pk_bf16_f32 v147, v42, v43
	buffer_store_dwordx4 v[144:147], v156, s[72:75], s2 offen sc1
	v_max_f32_e32 v36, 0, v36
	v_max_f32_e32 v37, 0, v37
	v_max_f32_e32 v38, 0, v38
	v_max_f32_e32 v39, 0, v39
	v_max_f32_e32 v32, 0, v32
	v_max_f32_e32 v33, 0, v33
	v_max_f32_e32 v34, 0, v34
	v_max_f32_e32 v35, 0, v35
	v_mul_f32_e32 v36, v36, v36
	v_mul_f32_e32 v37, v37, v37
	v_mul_f32_e32 v38, v38, v38
	v_mul_f32_e32 v39, v39, v39
	v_mul_f32_e32 v32, v32, v32
	v_mul_f32_e32 v33, v33, v33
	v_mul_f32_e32 v34, v34, v34
	v_mul_f32_e32 v35, v35, v35
	v_cvt_pk_bf16_f32 v152, v36, v37
	v_cvt_pk_bf16_f32 v153, v38, v39
	v_cvt_pk_bf16_f32 v154, v32, v33
	v_cvt_pk_bf16_f32 v155, v34, v35
	buffer_store_dwordx4 v[152:155], v156, s[72:75], s2 offen offset:256 sc1
	s_mul_i32 s2, s33, 0x140
	v_max_f32_e32 v28, 0, v28
	v_max_f32_e32 v29, 0, v29
	v_max_f32_e32 v30, 0, v30
	v_max_f32_e32 v31, 0, v31
	v_max_f32_e32 v24, 0, v24
	v_max_f32_e32 v25, 0, v25
	v_max_f32_e32 v26, 0, v26
	v_max_f32_e32 v27, 0, v27
	v_mul_f32_e32 v28, v28, v28
	v_mul_f32_e32 v29, v29, v29
	v_mul_f32_e32 v30, v30, v30
	v_mul_f32_e32 v31, v31, v31
	v_mul_f32_e32 v24, v24, v24
	v_mul_f32_e32 v25, v25, v25
	v_mul_f32_e32 v26, v26, v26
	v_mul_f32_e32 v27, v27, v27
	v_cvt_pk_bf16_f32 v144, v28, v29
	v_cvt_pk_bf16_f32 v145, v30, v31
	v_cvt_pk_bf16_f32 v146, v24, v25
	v_cvt_pk_bf16_f32 v147, v26, v27
	buffer_store_dwordx4 v[144:147], v156, s[72:75], s2 offen sc1
	v_max_f32_e32 v20, 0, v20
	v_max_f32_e32 v21, 0, v21
	v_max_f32_e32 v22, 0, v22
	v_max_f32_e32 v23, 0, v23
	v_max_f32_e32 v16, 0, v16
	v_max_f32_e32 v17, 0, v17
	v_max_f32_e32 v18, 0, v18
	v_max_f32_e32 v19, 0, v19
	v_mul_f32_e32 v20, v20, v20
	v_mul_f32_e32 v21, v21, v21
	v_mul_f32_e32 v22, v22, v22
	v_mul_f32_e32 v23, v23, v23
	v_mul_f32_e32 v16, v16, v16
	v_mul_f32_e32 v17, v17, v17
	v_mul_f32_e32 v18, v18, v18
	v_mul_f32_e32 v19, v19, v19
	v_cvt_pk_bf16_f32 v152, v20, v21
	v_cvt_pk_bf16_f32 v153, v22, v23
	v_cvt_pk_bf16_f32 v154, v16, v17
	v_cvt_pk_bf16_f32 v155, v18, v19
	buffer_store_dwordx4 v[152:155], v156, s[72:75], s2 offen offset:256 sc1
	s_mul_i32 s2, s33, 0x160
	v_max_f32_e32 v12, 0, v12
	v_max_f32_e32 v13, 0, v13
	v_max_f32_e32 v14, 0, v14
	v_max_f32_e32 v15, 0, v15
	v_max_f32_e32 v8, 0, v8
	v_max_f32_e32 v9, 0, v9
	v_max_f32_e32 v10, 0, v10
	v_max_f32_e32 v11, 0, v11
	v_mul_f32_e32 v12, v12, v12
	v_mul_f32_e32 v13, v13, v13
	v_mul_f32_e32 v14, v14, v14
	v_mul_f32_e32 v15, v15, v15
	v_mul_f32_e32 v8, v8, v8
	v_mul_f32_e32 v9, v9, v9
	v_mul_f32_e32 v10, v10, v10
	v_mul_f32_e32 v11, v11, v11
	v_cvt_pk_bf16_f32 v144, v12, v13
	v_cvt_pk_bf16_f32 v145, v14, v15
	v_cvt_pk_bf16_f32 v146, v8, v9
	v_cvt_pk_bf16_f32 v147, v10, v11
	buffer_store_dwordx4 v[144:147], v156, s[72:75], s2 offen sc1
	v_max_f32_e32 v4, 0, v4
	v_max_f32_e32 v5, 0, v5
	v_max_f32_e32 v6, 0, v6
	v_max_f32_e32 v7, 0, v7
	v_max_f32_e32 v0, 0, v0
	v_max_f32_e32 v1, 0, v1
	v_max_f32_e32 v2, 0, v2
	v_max_f32_e32 v3, 0, v3
	v_mul_f32_e32 v4, v4, v4
	v_mul_f32_e32 v5, v5, v5
	v_mul_f32_e32 v6, v6, v6
	v_mul_f32_e32 v7, v7, v7
	v_mul_f32_e32 v0, v0, v0
	v_mul_f32_e32 v1, v1, v1
	v_mul_f32_e32 v2, v2, v2
	v_mul_f32_e32 v3, v3, v3
	v_cvt_pk_bf16_f32 v152, v4, v5
	v_cvt_pk_bf16_f32 v153, v6, v7
	v_cvt_pk_bf16_f32 v154, v0, v1
	v_cvt_pk_bf16_f32 v155, v2, v3
	buffer_store_dwordx4 v[152:155], v156, s[72:75], s2 offen offset:256 sc1
	s_branch .LBB0_509

.LBB0_255:
	v_cvt_pk_bf16_f32 v120, v148, v149
	v_cvt_pk_bf16_f32 v121, v144, v145
	v_cvt_pk_bf16_f32 v122, v150, v151
	v_cvt_pk_bf16_f32 v123, v146, v147
	s_mov_b64 s[8:9], -1
	s_and_b64 vcc, exec, s[26:27]
	s_cbranch_vccz .LBB0_257
	v_subrev_u32_e32 v125, s44, v154
	buffer_store_dwordx4 v[120:123], v125, s[72:75], 0 offen sc1
	s_mov_b64 s[8:9], 0
.LBB0_257:
	s_and_b32 s89, s18, 0x1ff0
	v_lshrrev_b32_e32 v125, 6, v124
	s_and_b32 s35, s31, 0xf60
	s_andn2_b64 vcc, exec, s[8:9]
	v_add_lshl_u32 v168, v125, s89, 8
	s_cbranch_vccnz .LBB0_259
	s_lshr_b32 s2, s35, 4
	v_or_b32_e32 v125, s2, v168
	v_lshl_or_b32 v125, v125, 11, v160
	buffer_store_dwordx2 v[120:121], v125, s[72:75], 0 offen sc1
	buffer_store_dwordx2 v[122:123], v125, s[72:75], 0 offen offset:512 sc1

.LBB0_270:
	v_cndmask_b32_e64 v117, 0, 1, s[26:27]
	v_cvt_pk_bf16_f32 v112, v154, v155
	v_cvt_pk_bf16_f32 v113, v120, v121
	v_cvt_pk_bf16_f32 v114, v156, v157
	v_cvt_pk_bf16_f32 v115, v122, v123
	v_cmp_ne_u32_e64 s[8:9], 1, v117
	s_andn2_b64 vcc, exec, s[26:27]
	s_mov_b64 s[10:11], -1
	s_cbranch_vccnz .LBB0_272
	v_subrev_u32_e32 v116, s44, v116
	s_mov_b64 s[10:11], 0
	buffer_store_dwordx4 v[112:115], v116, s[72:75], 0 offen sc1
.LBB0_272:
	s_andn2_b64 vcc, exec, s[10:11]
	s_cbranch_vccnz .LBB0_274
	s_lshr_b32 s2, s35, 4
	v_or_b32_e32 v116, s2, v168
	v_lshl_or_b32 v116, v116, 11, v160
	v_add_u32_e32 v117, 0x4000, v116
	buffer_store_dwordx2 v[112:113], v117, s[72:75], 0 offen sc1
	v_or_b32_e32 v112, 0x4200, v116
	buffer_store_dwordx2 v[114:115], v112, s[72:75], 0 offen sc1
.LBB0_274:
	s_cmp_ge_i32 s18, s58
	s_cselect_b64 s[2:3], -1, 0
	s_and_b64 s[2:3], s[22:23], s[2:3]
	v_cndmask_b32_e64 v112, 0, 1, s[2:3]
	v_cmp_ne_u32_e64 s[10:11], 1, v112
	s_andn2_b64 vcc, exec, s[2:3]
	s_cbranch_vccnz .LBB0_278
	v_mul_f32_e32 v112, v149, v149
	v_mul_f32_e32 v113, v145, v145
	v_fmac_f32_e32 v112, v148, v148
	v_fmac_f32_e32 v113, v144, v144
	v_add_f32_e32 v112, v112, v113
	v_mul_f32_e32 v113, v151, v151
	v_fmac_f32_e32 v113, v150, v150
	v_add_f32_e32 v112, v113, v112
	v_mul_f32_e32 v113, v147, v147
	v_fmac_f32_e32 v113, v146, v146
	v_add_f32_e32 v112, v113, v112
	v_mul_f32_e32 v113, v155, v155
	v_mul_f32_e32 v114, v121, v121
	v_fmac_f32_e32 v113, v154, v154
	v_fmac_f32_e32 v114, v120, v120
	v_add_f32_e32 v113, v113, v114
	v_mul_f32_e32 v114, v157, v157
	v_fmac_f32_e32 v114, v156, v156
	v_add_f32_e32 v113, v114, v113
	v_mul_f32_e32 v114, v123, v123
	v_fmac_f32_e32 v114, v122, v122
	v_add_f32_e32 v113, v114, v113
	v_and_b32_e32 v114, 64, v177
	v_add_f32_e32 v112, v112, v113
	v_xor_b32_e32 v113, 16, v177
	v_add_u32_e32 v114, 64, v114
	v_cmp_lt_i32_e32 vcc, v113, v114
	s_nop 1
	v_cndmask_b32_e32 v113, v177, v113, vcc
	v_lshlrev_b32_e32 v113, 2, v113
	ds_bpermute_b32 v113, v113, v112
	s_waitcnt lgkmcnt(0)
	v_add_f32_e32 v112, v112, v113
	v_xor_b32_e32 v113, 32, v177
	v_cmp_lt_i32_e32 vcc, v113, v114
	s_nop 1
	v_cndmask_b32_e32 v113, v177, v113, vcc
	v_lshlrev_b32_e32 v113, 2, v113
	ds_bpermute_b32 v113, v113, v112
	s_and_saveexec_b64 s[52:53], s[0:1]
	s_cbranch_execz .LBB0_277
	s_sub_i32 s2, s18, s58
	s_lshl_b32 s2, s2, 2
	s_or_b32 s2, s2, s62
	s_ashr_i32 s3, s2, 31
	s_lshl_b64 s[2:3], s[2:3], 17
	s_add_u32 s2, s48, s2
	s_addc_u32 s3, s49, s3
	s_waitcnt lgkmcnt(0)
	v_add_f32_e32 v114, v112, v113
	v_lshl_add_u64 v[112:113], v[124:125], 2, s[2:3]
	global_store_dword v[112:113], v114, off sc1

.LBB0_288:
	v_cvt_pk_bf16_f32 v104, v116, v117
	s_waitcnt lgkmcnt(0)
	v_cvt_pk_bf16_f32 v105, v112, v113
	v_cvt_pk_bf16_f32 v106, v118, v119
	v_cvt_pk_bf16_f32 v107, v114, v115
	s_and_b64 vcc, exec, s[8:9]
	s_mov_b64 s[52:53], -1
	s_cbranch_vccnz .LBB0_290
	v_subrev_u32_e32 v110, s44, v110
	buffer_store_dwordx4 v[104:107], v110, s[72:75], 0 offen sc1
	s_cbranch_execnz .LBB0_292
	s_branch .LBB0_291

.LBB0_291:
	s_lshr_b32 s2, s35, 4
	v_or_b32_e32 v110, s2, v168
	v_lshl_or_b32 v110, v110, 11, v161
	buffer_store_dwordx2 v[104:105], v110, s[72:75], 0 offen sc1
	buffer_store_dwordx2 v[106:107], v110, s[72:75], 0 offen offset:512 sc1

.LBB0_303:
	v_cvt_pk_bf16_f32 v96, v110, v111
	v_cvt_pk_bf16_f32 v97, v104, v105
	v_cvt_pk_bf16_f32 v98, v120, v121
	v_cvt_pk_bf16_f32 v99, v106, v107
	s_and_b64 vcc, exec, s[8:9]
	s_mov_b64 s[52:53], -1
	s_cbranch_vccnz .LBB0_310
	v_subrev_u32_e32 v100, s44, v100
	buffer_store_dwordx4 v[96:99], v100, s[72:75], 0 offen sc1
	s_cbranch_execz .LBB0_311

.LBB0_311:
	s_lshr_b32 s2, s35, 4
	v_or_b32_e32 v100, s2, v168
	v_lshl_or_b32 v100, v100, 11, v161
	v_add_u32_e32 v101, 0x4000, v100
	buffer_store_dwordx2 v[96:97], v101, s[72:75], 0 offen sc1
	v_or_b32_e32 v96, 0x4200, v100
	buffer_store_dwordx2 v[98:99], v96, s[72:75], 0 offen sc1
	s_and_b64 vcc, exec, s[10:11]
	s_cbranch_vccnz .LBB0_306
.LBB0_312:
	v_mul_f32_e32 v96, v117, v117
	v_mul_f32_e32 v97, v113, v113
	v_fmac_f32_e32 v96, v116, v116
	v_fmac_f32_e32 v97, v112, v112
	v_add_f32_e32 v96, v96, v97
	v_mul_f32_e32 v97, v119, v119
	v_fmac_f32_e32 v97, v118, v118
	v_add_f32_e32 v96, v97, v96
	v_mul_f32_e32 v97, v115, v115
	v_fmac_f32_e32 v97, v114, v114
	v_add_f32_e32 v96, v97, v96
	v_mul_f32_e32 v97, v111, v111
	v_mul_f32_e32 v98, v105, v105
	v_fmac_f32_e32 v97, v110, v110
	v_fmac_f32_e32 v98, v104, v104
	v_add_f32_e32 v97, v97, v98
	v_mul_f32_e32 v98, v121, v121
	v_fmac_f32_e32 v98, v120, v120
	v_add_f32_e32 v97, v98, v97
	v_mul_f32_e32 v98, v107, v107
	v_fmac_f32_e32 v98, v106, v106
	v_add_f32_e32 v97, v98, v97
	v_and_b32_e32 v98, 64, v177
	v_add_f32_e32 v96, v96, v97
	v_xor_b32_e32 v97, 16, v177
	v_add_u32_e32 v98, 64, v98
	v_cmp_lt_i32_e32 vcc, v97, v98
	s_nop 1
	v_cndmask_b32_e32 v97, v177, v97, vcc
	v_lshlrev_b32_e32 v97, 2, v97
	ds_bpermute_b32 v97, v97, v96
	s_waitcnt lgkmcnt(0)
	v_add_f32_e32 v96, v96, v97
	v_xor_b32_e32 v97, 32, v177
	v_cmp_lt_i32_e32 vcc, v97, v98
	s_nop 1
	v_cndmask_b32_e32 v97, v177, v97, vcc
	v_lshlrev_b32_e32 v97, 2, v97
	ds_bpermute_b32 v97, v97, v96
	s_and_saveexec_b64 s[52:53], s[0:1]
	s_cbranch_execz .LBB0_314
	s_sub_i32 s2, s18, s58
	s_lshl_b32 s2, s2, 2
	s_or_b32 s2, s2, s62
	s_ashr_i32 s3, s2, 31
	s_lshl_b64 s[2:3], s[2:3], 17
	s_add_u32 s2, s48, s2
	s_addc_u32 s3, s49, s3
	s_waitcnt lgkmcnt(0)
	v_add_f32_e32 v98, v96, v97
	v_lshl_add_u64 v[96:97], v[124:125], 2, s[2:3]
	global_store_dword v[96:97], v98, off offset:64 sc1

.LBB0_321:
	v_cvt_pk_bf16_f32 v88, v100, v101
	s_waitcnt lgkmcnt(0)
	v_cvt_pk_bf16_f32 v89, v96, v97
	v_cvt_pk_bf16_f32 v90, v102, v103
	v_cvt_pk_bf16_f32 v91, v98, v99
	s_and_b64 vcc, exec, s[8:9]
	s_mov_b64 s[52:53], -1
	s_cbranch_vccnz .LBB0_323
	v_subrev_u32_e32 v94, s44, v94
	buffer_store_dwordx4 v[88:91], v94, s[72:75], 0 offen sc1
	v_or_b32_e32 v106, 1, v168
	s_cbranch_execnz .LBB0_325
	s_branch .LBB0_324

.LBB0_324:
	s_lshr_b32 s2, s35, 4
	v_or_b32_e32 v94, s2, v106
	v_lshl_or_b32 v94, v94, 11, v160
	buffer_store_dwordx2 v[88:89], v94, s[72:75], 0 offen sc1
	buffer_store_dwordx2 v[90:91], v94, s[72:75], 0 offen offset:512 sc1

.LBB0_336:
	v_cvt_pk_bf16_f32 v80, v94, v95
	v_cvt_pk_bf16_f32 v81, v88, v89
	v_cvt_pk_bf16_f32 v82, v104, v105
	v_cvt_pk_bf16_f32 v83, v90, v91
	s_and_b64 vcc, exec, s[8:9]
	s_mov_b64 s[52:53], -1
	s_cbranch_vccnz .LBB0_343
	v_subrev_u32_e32 v84, s44, v84
	buffer_store_dwordx4 v[80:83], v84, s[72:75], 0 offen sc1
	s_cbranch_execz .LBB0_344

.LBB0_344:
	s_lshr_b32 s2, s35, 4
	v_or_b32_e32 v84, s2, v106
	v_lshl_or_b32 v84, v84, 11, v160
	v_add_u32_e32 v85, 0x4000, v84
	buffer_store_dwordx2 v[80:81], v85, s[72:75], 0 offen sc1
	v_or_b32_e32 v80, 0x4200, v84
	buffer_store_dwordx2 v[82:83], v80, s[72:75], 0 offen sc1
	s_and_b64 vcc, exec, s[10:11]
	s_cbranch_vccnz .LBB0_339
.LBB0_345:
	v_mul_f32_e32 v80, v101, v101
	v_mul_f32_e32 v81, v97, v97
	v_fmac_f32_e32 v80, v100, v100
	v_fmac_f32_e32 v81, v96, v96
	v_add_f32_e32 v80, v80, v81
	v_mul_f32_e32 v81, v103, v103
	v_fmac_f32_e32 v81, v102, v102
	v_add_f32_e32 v80, v81, v80
	v_mul_f32_e32 v81, v99, v99
	v_fmac_f32_e32 v81, v98, v98
	v_add_f32_e32 v80, v81, v80
	v_mul_f32_e32 v81, v95, v95
	v_mul_f32_e32 v82, v89, v89
	v_fmac_f32_e32 v81, v94, v94
	v_fmac_f32_e32 v82, v88, v88
	v_add_f32_e32 v81, v81, v82
	v_mul_f32_e32 v82, v105, v105
	v_fmac_f32_e32 v82, v104, v104
	v_add_f32_e32 v81, v82, v81
	v_mul_f32_e32 v82, v91, v91
	v_fmac_f32_e32 v82, v90, v90
	v_add_f32_e32 v81, v82, v81
	v_and_b32_e32 v82, 64, v177
	v_add_f32_e32 v80, v80, v81
	v_xor_b32_e32 v81, 16, v177
	v_add_u32_e32 v82, 64, v82
	v_cmp_lt_i32_e32 vcc, v81, v82
	s_nop 1
	v_cndmask_b32_e32 v81, v177, v81, vcc
	v_lshlrev_b32_e32 v81, 2, v81
	ds_bpermute_b32 v81, v81, v80
	s_waitcnt lgkmcnt(0)
	v_add_f32_e32 v80, v80, v81
	v_xor_b32_e32 v81, 32, v177
	v_cmp_lt_i32_e32 vcc, v81, v82
	s_nop 1
	v_cndmask_b32_e32 v81, v177, v81, vcc
	v_lshlrev_b32_e32 v81, 2, v81
	ds_bpermute_b32 v81, v81, v80
	s_and_saveexec_b64 s[52:53], s[0:1]
	s_cbranch_execz .LBB0_347
	s_sub_i32 s2, s18, s58
	s_lshl_b32 s2, s2, 2
	s_or_b32 s2, s2, s62
	s_ashr_i32 s3, s2, 31
	s_lshl_b64 s[2:3], s[2:3], 17
	s_add_u32 s2, s48, s2
	s_addc_u32 s3, s49, s3
	s_waitcnt lgkmcnt(0)
	v_add_f32_e32 v82, v80, v81
	v_lshl_add_u64 v[80:81], v[124:125], 2, s[2:3]
	global_store_dword v[80:81], v82, off offset:128 sc1

.LBB0_354:
	v_cvt_pk_bf16_f32 v72, v84, v85
	s_waitcnt lgkmcnt(0)
	v_cvt_pk_bf16_f32 v73, v80, v81
	v_cvt_pk_bf16_f32 v74, v86, v87
	v_cvt_pk_bf16_f32 v75, v82, v83
	s_and_b64 vcc, exec, s[8:9]
	s_mov_b64 s[52:53], -1
	s_cbranch_vccnz .LBB0_356
	v_subrev_u32_e32 v78, s44, v78
	buffer_store_dwordx4 v[72:75], v78, s[72:75], 0 offen sc1
	s_cbranch_execnz .LBB0_358
	s_branch .LBB0_357

.LBB0_357:
	s_lshr_b32 s2, s35, 4
	v_or_b32_e32 v78, s2, v106
	v_lshl_or_b32 v78, v78, 11, v161
	buffer_store_dwordx2 v[72:73], v78, s[72:75], 0 offen sc1
	buffer_store_dwordx2 v[74:75], v78, s[72:75], 0 offen offset:512 sc1

.LBB0_369:
	v_cvt_pk_bf16_f32 v64, v78, v79
	v_cvt_pk_bf16_f32 v65, v72, v73
	v_cvt_pk_bf16_f32 v66, v88, v89
	v_cvt_pk_bf16_f32 v67, v74, v75
	s_and_b64 vcc, exec, s[8:9]
	s_mov_b64 s[52:53], -1
	s_cbranch_vccnz .LBB0_376
	v_subrev_u32_e32 v68, s44, v68
	buffer_store_dwordx4 v[64:67], v68, s[72:75], 0 offen sc1
	s_cbranch_execz .LBB0_377

.LBB0_377:
	s_lshr_b32 s2, s35, 4
	v_or_b32_e32 v68, s2, v106
	v_lshl_or_b32 v68, v68, 11, v161
	v_add_u32_e32 v69, 0x4000, v68
	buffer_store_dwordx2 v[64:65], v69, s[72:75], 0 offen sc1
	v_or_b32_e32 v64, 0x4200, v68
	buffer_store_dwordx2 v[66:67], v64, s[72:75], 0 offen sc1
	s_and_b64 vcc, exec, s[10:11]
	s_cbranch_vccnz .LBB0_372
.LBB0_378:
	v_mul_f32_e32 v64, v85, v85
	v_mul_f32_e32 v65, v81, v81
	v_fmac_f32_e32 v64, v84, v84
	v_fmac_f32_e32 v65, v80, v80
	v_add_f32_e32 v64, v64, v65
	v_mul_f32_e32 v65, v87, v87
	v_fmac_f32_e32 v65, v86, v86
	v_add_f32_e32 v64, v65, v64
	v_mul_f32_e32 v65, v83, v83
	v_fmac_f32_e32 v65, v82, v82
	v_add_f32_e32 v64, v65, v64
	v_mul_f32_e32 v65, v79, v79
	v_mul_f32_e32 v66, v73, v73
	v_fmac_f32_e32 v65, v78, v78
	v_fmac_f32_e32 v66, v72, v72
	v_add_f32_e32 v65, v65, v66
	v_mul_f32_e32 v66, v89, v89
	v_fmac_f32_e32 v66, v88, v88
	v_add_f32_e32 v65, v66, v65
	v_mul_f32_e32 v66, v75, v75
	v_fmac_f32_e32 v66, v74, v74
	v_add_f32_e32 v65, v66, v65
	v_and_b32_e32 v66, 64, v177
	v_add_f32_e32 v64, v64, v65
	v_xor_b32_e32 v65, 16, v177
	v_add_u32_e32 v66, 64, v66
	v_cmp_lt_i32_e32 vcc, v65, v66
	s_nop 1
	v_cndmask_b32_e32 v65, v177, v65, vcc
	v_lshlrev_b32_e32 v65, 2, v65
	ds_bpermute_b32 v65, v65, v64
	s_waitcnt lgkmcnt(0)
	v_add_f32_e32 v64, v64, v65
	v_xor_b32_e32 v65, 32, v177
	v_cmp_lt_i32_e32 vcc, v65, v66
	s_nop 1
	v_cndmask_b32_e32 v65, v177, v65, vcc
	v_lshlrev_b32_e32 v65, 2, v65
	ds_bpermute_b32 v65, v65, v64
	s_and_saveexec_b64 s[52:53], s[0:1]
	s_cbranch_execz .LBB0_380
	s_sub_i32 s2, s18, s58
	s_lshl_b32 s2, s2, 2
	s_or_b32 s2, s2, s62
	s_ashr_i32 s3, s2, 31
	s_lshl_b64 s[2:3], s[2:3], 17
	s_add_u32 s2, s48, s2
	s_addc_u32 s3, s49, s3
	s_waitcnt lgkmcnt(0)
	v_add_f32_e32 v66, v64, v65
	v_lshl_add_u64 v[64:65], v[124:125], 2, s[2:3]
	global_store_dword v[64:65], v66, off offset:192 sc1

.LBB0_387:
	v_cvt_pk_bf16_f32 v56, v68, v69
	s_waitcnt lgkmcnt(0)
	v_cvt_pk_bf16_f32 v57, v64, v65
	v_cvt_pk_bf16_f32 v58, v70, v71
	v_cvt_pk_bf16_f32 v59, v66, v67
	s_and_b64 vcc, exec, s[8:9]
	s_mov_b64 s[52:53], -1
	s_cbranch_vccnz .LBB0_389
	v_subrev_u32_e32 v62, s44, v62
	buffer_store_dwordx4 v[56:59], v62, s[72:75], 0 offen sc1
	v_lshrrev_b32_e32 v62, 6, v72
	v_add_lshl_u32 v75, v62, s89, 8
	s_cbranch_execnz .LBB0_391
	s_branch .LBB0_390

.LBB0_390:
	s_lshr_b32 s2, s35, 4
	v_or_b32_e32 v62, s2, v75
	v_lshl_or_b32 v62, v62, 11, v160
	buffer_store_dwordx2 v[56:57], v62, s[72:75], 0 offen sc1
	buffer_store_dwordx2 v[58:59], v62, s[72:75], 0 offen offset:512 sc1

.LBB0_402:
	v_cvt_pk_bf16_f32 v48, v62, v63
	v_cvt_pk_bf16_f32 v49, v56, v57
	v_cvt_pk_bf16_f32 v50, v72, v73
	v_cvt_pk_bf16_f32 v51, v58, v59
	s_and_b64 vcc, exec, s[8:9]
	s_mov_b64 s[52:53], -1
	s_cbranch_vccnz .LBB0_409
	v_subrev_u32_e32 v52, s44, v52
	buffer_store_dwordx4 v[48:51], v52, s[72:75], 0 offen sc1
	s_cbranch_execz .LBB0_410

.LBB0_410:
	s_lshr_b32 s2, s35, 4
	v_or_b32_e32 v52, s2, v75
	v_lshl_or_b32 v52, v52, 11, v160
	v_add_u32_e32 v53, 0x4000, v52
	buffer_store_dwordx2 v[48:49], v53, s[72:75], 0 offen sc1
	v_or_b32_e32 v48, 0x4200, v52
	buffer_store_dwordx2 v[50:51], v48, s[72:75], 0 offen sc1
	s_and_b64 vcc, exec, s[10:11]
	s_cbranch_vccnz .LBB0_405
.LBB0_411:
	v_mul_f32_e32 v48, v69, v69
	v_mul_f32_e32 v49, v65, v65
	v_fmac_f32_e32 v48, v68, v68
	v_fmac_f32_e32 v49, v64, v64
	v_add_f32_e32 v48, v48, v49
	v_mul_f32_e32 v49, v71, v71
	v_fmac_f32_e32 v49, v70, v70
	v_add_f32_e32 v48, v49, v48
	v_mul_f32_e32 v49, v67, v67
	v_fmac_f32_e32 v49, v66, v66
	v_add_f32_e32 v48, v49, v48
	v_mul_f32_e32 v49, v63, v63
	v_mul_f32_e32 v50, v57, v57
	v_fmac_f32_e32 v49, v62, v62
	v_fmac_f32_e32 v50, v56, v56
	v_add_f32_e32 v49, v49, v50
	v_mul_f32_e32 v50, v73, v73
	v_fmac_f32_e32 v50, v72, v72
	v_add_f32_e32 v49, v50, v49
	v_mul_f32_e32 v50, v59, v59
	v_fmac_f32_e32 v50, v58, v58
	v_add_f32_e32 v49, v50, v49
	v_and_b32_e32 v50, 64, v177
	v_add_f32_e32 v48, v48, v49
	v_xor_b32_e32 v49, 16, v177
	v_add_u32_e32 v50, 64, v50
	v_cmp_lt_i32_e32 vcc, v49, v50
	s_nop 1
	v_cndmask_b32_e32 v49, v177, v49, vcc
	v_lshlrev_b32_e32 v49, 2, v49
	ds_bpermute_b32 v49, v49, v48
	s_waitcnt lgkmcnt(0)
	v_add_f32_e32 v48, v48, v49
	v_xor_b32_e32 v49, 32, v177
	v_cmp_lt_i32_e32 vcc, v49, v50
	s_nop 1
	v_cndmask_b32_e32 v49, v177, v49, vcc
	v_lshlrev_b32_e32 v49, 2, v49
	ds_bpermute_b32 v49, v49, v48
	s_and_saveexec_b64 s[52:53], s[0:1]
	s_cbranch_execz .LBB0_413
	s_sub_i32 s2, s18, s58
	s_lshl_b32 s2, s2, 2
	s_or_b32 s2, s2, s62
	s_ashr_i32 s3, s2, 31
	s_lshl_b64 s[2:3], s[2:3], 17
	s_add_u32 s2, s48, s2
	s_addc_u32 s3, s49, s3
	s_waitcnt lgkmcnt(0)
	v_add_f32_e32 v50, v48, v49
	v_lshl_add_u64 v[48:49], v[124:125], 2, s[2:3]
	global_store_dword v[48:49], v50, off offset:512 sc1

.LBB0_420:
	v_cvt_pk_bf16_f32 v40, v52, v53
	s_waitcnt lgkmcnt(0)
	v_cvt_pk_bf16_f32 v41, v48, v49
	v_cvt_pk_bf16_f32 v42, v54, v55
	v_cvt_pk_bf16_f32 v43, v50, v51
	s_and_b64 vcc, exec, s[8:9]
	s_mov_b64 s[52:53], -1
	s_cbranch_vccnz .LBB0_422
	v_subrev_u32_e32 v46, s44, v46
	buffer_store_dwordx4 v[40:43], v46, s[72:75], 0 offen sc1
	s_cbranch_execnz .LBB0_424
	s_branch .LBB0_423

.LBB0_423:
	s_lshr_b32 s2, s35, 4
	v_or_b32_e32 v46, s2, v75
	v_lshl_or_b32 v46, v46, 11, v161
	buffer_store_dwordx2 v[40:41], v46, s[72:75], 0 offen sc1
	buffer_store_dwordx2 v[42:43], v46, s[72:75], 0 offen offset:512 sc1

.LBB0_435:
	v_cvt_pk_bf16_f32 v32, v46, v47
	v_cvt_pk_bf16_f32 v33, v40, v41
	v_cvt_pk_bf16_f32 v34, v56, v57
	v_cvt_pk_bf16_f32 v35, v42, v43
	s_and_b64 vcc, exec, s[8:9]
	s_mov_b64 s[52:53], -1
	s_cbranch_vccnz .LBB0_442
	v_subrev_u32_e32 v36, s44, v36
	buffer_store_dwordx4 v[32:35], v36, s[72:75], 0 offen sc1
	s_cbranch_execz .LBB0_443

.LBB0_443:
	s_lshr_b32 s2, s35, 4
	v_or_b32_e32 v36, s2, v75
	v_lshl_or_b32 v36, v36, 11, v161
	v_add_u32_e32 v37, 0x4000, v36
	buffer_store_dwordx2 v[32:33], v37, s[72:75], 0 offen sc1
	v_or_b32_e32 v32, 0x4200, v36
	buffer_store_dwordx2 v[34:35], v32, s[72:75], 0 offen sc1
	s_and_b64 vcc, exec, s[10:11]
	s_cbranch_vccnz .LBB0_438
.LBB0_444:
	v_mul_f32_e32 v32, v53, v53
	v_mul_f32_e32 v33, v49, v49
	v_fmac_f32_e32 v32, v52, v52
	v_fmac_f32_e32 v33, v48, v48
	v_add_f32_e32 v32, v32, v33
	v_mul_f32_e32 v33, v55, v55
	v_fmac_f32_e32 v33, v54, v54
	v_add_f32_e32 v32, v33, v32
	v_mul_f32_e32 v33, v51, v51
	v_fmac_f32_e32 v33, v50, v50
	v_add_f32_e32 v32, v33, v32
	v_mul_f32_e32 v33, v47, v47
	v_mul_f32_e32 v34, v41, v41
	v_fmac_f32_e32 v33, v46, v46
	v_fmac_f32_e32 v34, v40, v40
	v_add_f32_e32 v33, v33, v34
	v_mul_f32_e32 v34, v57, v57
	v_fmac_f32_e32 v34, v56, v56
	v_add_f32_e32 v33, v34, v33
	v_mul_f32_e32 v34, v43, v43
	v_fmac_f32_e32 v34, v42, v42
	v_add_f32_e32 v33, v34, v33
	v_and_b32_e32 v34, 64, v177
	v_add_f32_e32 v32, v32, v33
	v_xor_b32_e32 v33, 16, v177
	v_add_u32_e32 v34, 64, v34
	v_cmp_lt_i32_e32 vcc, v33, v34
	s_nop 1
	v_cndmask_b32_e32 v33, v177, v33, vcc
	v_lshlrev_b32_e32 v33, 2, v33
	ds_bpermute_b32 v33, v33, v32
	s_waitcnt lgkmcnt(0)
	v_add_f32_e32 v32, v32, v33
	v_xor_b32_e32 v33, 32, v177
	v_cmp_lt_i32_e32 vcc, v33, v34
	s_nop 1
	v_cndmask_b32_e32 v33, v177, v33, vcc
	v_lshlrev_b32_e32 v33, 2, v33
	ds_bpermute_b32 v33, v33, v32
	s_and_saveexec_b64 s[52:53], s[0:1]
	s_cbranch_execz .LBB0_446
	s_sub_i32 s2, s18, s58
	s_lshl_b32 s2, s2, 2
	s_or_b32 s2, s2, s62
	s_ashr_i32 s3, s2, 31
	s_lshl_b64 s[2:3], s[2:3], 17
	s_add_u32 s2, s48, s2
	s_addc_u32 s3, s49, s3
	s_waitcnt lgkmcnt(0)
	v_add_f32_e32 v34, v32, v33
	v_lshl_add_u64 v[32:33], v[124:125], 2, s[2:3]
	global_store_dword v[32:33], v34, off offset:576 sc1

.LBB0_453:
	v_cvt_pk_bf16_f32 v24, v36, v37
	s_waitcnt lgkmcnt(0)
	v_cvt_pk_bf16_f32 v25, v32, v33
	v_cvt_pk_bf16_f32 v26, v38, v39
	v_cvt_pk_bf16_f32 v27, v34, v35
	s_and_b64 vcc, exec, s[8:9]
	s_mov_b64 s[52:53], -1
	s_cbranch_vccnz .LBB0_455
	v_subrev_u32_e32 v30, s44, v30
	buffer_store_dwordx4 v[24:27], v30, s[72:75], 0 offen sc1
	v_or_b32_e32 v42, 1, v75
	s_cbranch_execnz .LBB0_457
	s_branch .LBB0_456

.LBB0_456:
	s_lshr_b32 s2, s35, 4
	v_or_b32_e32 v30, s2, v42
	v_lshl_or_b32 v30, v30, 11, v160
	buffer_store_dwordx2 v[24:25], v30, s[72:75], 0 offen sc1
	buffer_store_dwordx2 v[26:27], v30, s[72:75], 0 offen offset:512 sc1

.LBB0_468:
	v_cvt_pk_bf16_f32 v16, v30, v31
	v_cvt_pk_bf16_f32 v17, v24, v25
	v_cvt_pk_bf16_f32 v18, v40, v41
	v_cvt_pk_bf16_f32 v19, v26, v27
	s_and_b64 vcc, exec, s[8:9]
	s_mov_b64 s[52:53], -1
	s_cbranch_vccnz .LBB0_475
	v_subrev_u32_e32 v20, s44, v20
	buffer_store_dwordx4 v[16:19], v20, s[72:75], 0 offen sc1
	s_cbranch_execz .LBB0_476

.LBB0_476:
	s_lshr_b32 s2, s35, 4
	v_or_b32_e32 v20, s2, v42
	v_lshl_or_b32 v20, v20, 11, v160
	v_add_u32_e32 v21, 0x4000, v20
	buffer_store_dwordx2 v[16:17], v21, s[72:75], 0 offen sc1
	v_or_b32_e32 v16, 0x4200, v20
	buffer_store_dwordx2 v[18:19], v16, s[72:75], 0 offen sc1
	s_and_b64 vcc, exec, s[10:11]
	s_cbranch_vccnz .LBB0_471
.LBB0_477:
	v_mul_f32_e32 v16, v37, v37
	v_mul_f32_e32 v17, v33, v33
	v_fmac_f32_e32 v16, v36, v36
	v_fmac_f32_e32 v17, v32, v32
	v_add_f32_e32 v16, v16, v17
	v_mul_f32_e32 v17, v39, v39
	v_fmac_f32_e32 v17, v38, v38
	v_add_f32_e32 v16, v17, v16
	v_mul_f32_e32 v17, v35, v35
	v_fmac_f32_e32 v17, v34, v34
	v_add_f32_e32 v16, v17, v16
	v_mul_f32_e32 v17, v31, v31
	v_mul_f32_e32 v18, v25, v25
	v_fmac_f32_e32 v17, v30, v30
	v_fmac_f32_e32 v18, v24, v24
	v_add_f32_e32 v17, v17, v18
	v_mul_f32_e32 v18, v41, v41
	v_fmac_f32_e32 v18, v40, v40
	v_add_f32_e32 v17, v18, v17
	v_mul_f32_e32 v18, v27, v27
	v_fmac_f32_e32 v18, v26, v26
	v_add_f32_e32 v17, v18, v17
	v_and_b32_e32 v18, 64, v177
	v_add_f32_e32 v16, v16, v17
	v_xor_b32_e32 v17, 16, v177
	v_add_u32_e32 v18, 64, v18
	v_cmp_lt_i32_e32 vcc, v17, v18
	s_nop 1
	v_cndmask_b32_e32 v17, v177, v17, vcc
	v_lshlrev_b32_e32 v17, 2, v17
	ds_bpermute_b32 v17, v17, v16
	s_waitcnt lgkmcnt(0)
	v_add_f32_e32 v16, v16, v17
	v_xor_b32_e32 v17, 32, v177
	v_cmp_lt_i32_e32 vcc, v17, v18
	s_nop 1
	v_cndmask_b32_e32 v17, v177, v17, vcc
	v_lshlrev_b32_e32 v17, 2, v17
	ds_bpermute_b32 v17, v17, v16
	s_and_saveexec_b64 s[52:53], s[0:1]
	s_cbranch_execz .LBB0_479
	s_sub_i32 s2, s18, s58
	s_lshl_b32 s2, s2, 2
	s_or_b32 s2, s2, s62
	s_ashr_i32 s3, s2, 31
	s_lshl_b64 s[2:3], s[2:3], 17
	s_add_u32 s2, s48, s2
	s_addc_u32 s3, s49, s3
	s_waitcnt lgkmcnt(0)
	v_add_f32_e32 v18, v16, v17
	v_lshl_add_u64 v[16:17], v[124:125], 2, s[2:3]
	global_store_dword v[16:17], v18, off offset:640 sc1

.LBB0_486:
	v_cvt_pk_bf16_f32 v8, v20, v21
	s_waitcnt lgkmcnt(0)
	v_cvt_pk_bf16_f32 v9, v16, v17
	v_cvt_pk_bf16_f32 v10, v22, v23
	v_cvt_pk_bf16_f32 v11, v18, v19
	s_and_b64 vcc, exec, s[8:9]
	s_mov_b64 s[52:53], -1
	s_cbranch_vccnz .LBB0_488
	v_subrev_u32_e32 v14, s44, v14
	buffer_store_dwordx4 v[8:11], v14, s[72:75], 0 offen sc1
	s_cbranch_execnz .LBB0_490
	s_branch .LBB0_489

.LBB0_489:
	s_lshr_b32 s2, s35, 4
	v_or_b32_e32 v14, s2, v42
	v_lshl_or_b32 v14, v14, 11, v161
	buffer_store_dwordx2 v[8:9], v14, s[72:75], 0 offen sc1
	buffer_store_dwordx2 v[10:11], v14, s[72:75], 0 offen offset:512 sc1

.LBB0_501:
	v_cvt_pk_bf16_f32 v0, v14, v15
	v_cvt_pk_bf16_f32 v1, v8, v9
	v_cvt_pk_bf16_f32 v2, v24, v25
	v_cvt_pk_bf16_f32 v3, v10, v11
	s_and_b64 vcc, exec, s[8:9]
	s_mov_b64 s[6:7], -1
	s_cbranch_vccnz .LBB0_507
	v_subrev_u32_e32 v4, s44, v4
	buffer_store_dwordx4 v[0:3], v4, s[72:75], 0 offen sc1
	s_cbranch_execz .LBB0_508

.LBB0_504:
	v_mul_f32_e32 v0, v21, v21
	v_mul_f32_e32 v1, v17, v17
	v_fmac_f32_e32 v0, v20, v20
	v_fmac_f32_e32 v1, v16, v16
	v_add_f32_e32 v0, v0, v1
	v_mul_f32_e32 v1, v23, v23
	v_fmac_f32_e32 v1, v22, v22
	v_add_f32_e32 v0, v1, v0
	v_mul_f32_e32 v1, v19, v19
	v_fmac_f32_e32 v1, v18, v18
	v_add_f32_e32 v0, v1, v0
	v_mul_f32_e32 v1, v15, v15
	v_mul_f32_e32 v2, v9, v9
	v_fmac_f32_e32 v1, v14, v14
	v_fmac_f32_e32 v2, v8, v8
	v_add_f32_e32 v1, v1, v2
	v_mul_f32_e32 v2, v25, v25
	v_fmac_f32_e32 v2, v24, v24
	v_add_f32_e32 v1, v2, v1
	v_mul_f32_e32 v2, v11, v11
	v_fmac_f32_e32 v2, v10, v10
	v_add_f32_e32 v1, v2, v1
	v_and_b32_e32 v2, 64, v177
	v_add_f32_e32 v0, v0, v1
	v_xor_b32_e32 v1, 16, v177
	v_add_u32_e32 v2, 64, v2
	v_cmp_lt_i32_e32 vcc, v1, v2
	s_nop 1
	v_cndmask_b32_e32 v1, v177, v1, vcc
	v_lshlrev_b32_e32 v1, 2, v1
	ds_bpermute_b32 v1, v1, v0
	s_waitcnt lgkmcnt(0)
	v_add_f32_e32 v0, v0, v1
	v_xor_b32_e32 v1, 32, v177
	v_cmp_lt_i32_e32 vcc, v1, v2
	s_nop 1
	v_cndmask_b32_e32 v1, v177, v1, vcc
	v_lshlrev_b32_e32 v1, 2, v1
	ds_bpermute_b32 v1, v1, v0
	s_and_saveexec_b64 s[6:7], s[0:1]
	s_cbranch_execz .LBB0_506
	s_sub_i32 s2, s18, s58
	s_lshl_b32 s2, s2, 2
	s_or_b32 s2, s2, s62
	s_ashr_i32 s3, s2, 31
	s_lshl_b64 s[2:3], s[2:3], 17
	s_add_u32 s2, s48, s2
	s_addc_u32 s3, s49, s3
	s_waitcnt lgkmcnt(0)
	v_add_f32_e32 v2, v0, v1
	v_lshl_add_u64 v[0:1], v[124:125], 2, s[2:3]
	global_store_dword v[0:1], v2, off offset:704 sc1

.LBB0_508:
	s_lshr_b32 s2, s35, 4
	v_or_b32_e32 v4, s2, v42
	v_lshl_or_b32 v4, v4, 11, v161
	v_add_u32_e32 v5, 0x4000, v4
	buffer_store_dwordx2 v[0:1], v5, s[72:75], 0 offen sc1
	v_or_b32_e32 v0, 0x4200, v4
	buffer_store_dwordx2 v[2:3], v0, s[72:75], 0 offen sc1
	s_and_b64 vcc, exec, s[10:11]
	s_cbranch_vccz .LBB0_504

.LBB0_521:
	s_or_b32 s2, s6, s18
	s_ashr_i32 s3, s2, 31
	v_cndmask_b32_e64 v32, 0, 1, s[4:5]
	s_lshl_b64 s[4:5], s[2:3], 12
	v_lshl_add_u64 v[34:35], v[138:139], 0, s[4:5]
	global_load_dwordx4 v[44:47], v[34:35], off
	global_load_dwordx4 v[36:39], v[34:35], off offset:1024
	global_load_dwordx4 v[48:51], v[34:35], off offset:2048
	global_load_dwordx4 v[52:55], v[34:35], off offset:3072
	s_or_b32 s2, s2, 1
	s_ashr_i32 s3, s2, 31
	s_lshl_b64 s[2:3], s[2:3], 12
	v_cmp_ne_u32_e32 vcc, 1, v32
	v_lshl_add_u64 v[32:33], v[138:139], 0, s[2:3]
	global_load_dwordx4 v[68:71], v[32:33], off
	global_load_dwordx4 v[86:89], v[32:33], off offset:1024
	global_load_dwordx4 v[90:93], v[32:33], off offset:2048
	global_load_dwordx4 v[106:109], v[32:33], off offset:3072
	s_mov_b32 s2, 0x3c800000
	s_and_b64 vcc, exec, vcc
	s_waitcnt vmcnt(7)
	v_and_b32_e32 v77, 0xffff0000, v44
	s_waitcnt vmcnt(6)
	v_lshlrev_b32_e32 v57, 16, v37
	v_lshlrev_b32_e32 v56, 16, v36
	v_and_b32_e32 v37, 0xffff0000, v37
	v_and_b32_e32 v36, 0xffff0000, v36
	v_pk_mul_f32 v[40:41], v[36:37], v[36:37]
	v_lshlrev_b32_e32 v59, 16, v39
	v_lshlrev_b32_e32 v58, 16, v38
	v_and_b32_e32 v39, 0xffff0000, v39
	v_and_b32_e32 v38, 0xffff0000, v38
	v_pk_fma_f32 v[40:41], v[56:57], v[56:57], v[40:41]
	v_pk_mul_f32 v[42:43], v[38:39], v[38:39]
	v_pk_add_f32 v[40:41], v[40:41], v[40:41] op_sel:[0,1] op_sel_hi:[1,0]
	v_pk_fma_f32 v[42:43], v[58:59], v[58:59], v[42:43]
	v_and_b32_e32 v63, 0xffff0000, v45
	v_pk_add_f32 v[40:41], v[42:43], v[40:41]
	v_lshlrev_b32_e32 v76, 16, v44
	v_pk_add_f32 v[72:73], v[42:43], v[40:41] op_sel:[1,0] op_sel_hi:[0,1]
	s_waitcnt vmcnt(5)
	v_and_b32_e32 v41, 0xffff0000, v48
	v_lshlrev_b32_e32 v40, 16, v48
	v_mul_f32_e32 v42, v41, v41
	v_pk_fma_f32 v[78:79], v[40:41], v[40:41], v[42:43] op_sel_hi:[1,1,0]
	v_and_b32_e32 v43, 0xffff0000, v49
	v_lshlrev_b32_e32 v42, 16, v49
	v_mul_f32_e32 v48, v43, v43
	v_pk_fma_f32 v[82:83], v[42:43], v[42:43], v[48:49] op_sel_hi:[1,1,0]
	v_and_b32_e32 v49, 0xffff0000, v47
	v_lshlrev_b32_e32 v48, 16, v47
	v_mul_f32_e32 v60, v49, v49
	v_pk_fma_f32 v[74:75], v[48:49], v[48:49], v[60:61] op_sel_hi:[1,1,0]
	v_and_b32_e32 v61, 0xffff0000, v46
	v_lshlrev_b32_e32 v60, 16, v46
	v_mov_b32_e32 v64, v61
	v_mov_b32_e32 v65, v77
	v_lshlrev_b32_e32 v62, 16, v45
	v_mul_f32_e32 v46, v63, v63
	v_mov_b32_e32 v44, v60
	v_mov_b32_e32 v45, v76
	v_pk_mul_f32 v[64:65], v[64:65], v[64:65]
	v_pk_fma_f32 v[46:47], v[62:63], v[62:63], v[46:47] op_sel_hi:[1,1,0]
	v_pk_fma_f32 v[44:45], v[44:45], v[44:45], v[64:65]
	v_mov_b32_e32 v80, v58
	v_pk_add_f32 v[46:47], v[44:45], v[46:47] op_sel:[1,0] op_sel_hi:[0,1]
	v_pk_add_f32 v[94:95], v[44:45], v[46:47]
	v_mov_b32_e32 v81, v38
	v_mov_b32_e32 v38, v59
	v_pk_add_f32 v[58:59], v[74:75], v[94:95]
	s_waitcnt vmcnt(4)
	v_lshlrev_b32_e32 v74, 16, v53
	v_and_b32_e32 v75, 0xffff0000, v53
	v_lshlrev_b32_e32 v97, 16, v52
	v_and_b32_e32 v47, 0xffff0000, v52
	v_and_b32_e32 v46, 0xffff0000, v50
	v_pk_mov_b32 v[44:45], v[50:51], v[54:55] op_sel:[1,0]
	v_pk_mul_f32 v[52:53], v[74:75], v[74:75]
	v_lshlrev_b32_e32 v96, 16, v50
	v_lshlrev_b32_e32 v99, 16, v54
	v_lshlrev_b32_e32 v98, 16, v51
	v_and_b32_e32 v45, 0xffff0000, v45
	v_and_b32_e32 v44, 0xffff0000, v44
	v_pk_mul_f32 v[50:51], v[46:47], v[46:47]
	v_mov_b32_e32 v84, v56
	v_lshlrev_b32_e32 v56, 16, v55
	v_and_b32_e32 v55, 0xffff0000, v55
	v_and_b32_e32 v54, s0, v54
	v_mov_b32_e32 v79, v52
	v_mov_b32_e32 v83, v53
	v_pk_fma_f32 v[50:51], v[96:97], v[96:97], v[50:51]
	v_pk_mul_f32 v[64:65], v[44:45], v[44:45]
	v_mov_b32_e32 v85, v36
	v_mov_b32_e32 v36, v57
	v_mov_b32_e32 v57, v55
	v_pk_mul_f32 v[54:55], v[54:55], v[54:55]
	v_pk_add_f32 v[52:53], v[78:79], v[82:83]
	v_pk_fma_f32 v[100:101], v[98:99], v[98:99], v[64:65]
	v_mul_f32_e32 v59, v56, v56
	v_mov_b32_e32 v73, v55
	v_pk_add_f32 v[50:51], v[50:51], v[52:53]
	v_pk_add_f32 v[54:55], v[58:59], v[72:73]
	v_pk_add_f32 v[50:51], v[100:101], v[50:51]
	s_waitcnt vmcnt(2)
	v_lshlrev_b32_e32 v95, 16, v87
	v_pk_add_f32 v[110:111], v[54:55], v[50:51]
	v_and_b32_e32 v51, 0xffff0000, v87
	v_and_b32_e32 v50, 0xffff0000, v86
	v_lshlrev_b32_e32 v94, 16, v86
	v_pk_mul_f32 v[52:53], v[50:51], v[50:51]
	v_lshlrev_b32_e32 v87, 16, v89
	v_pk_fma_f32 v[52:53], v[94:95], v[94:95], v[52:53]
	v_lshlrev_b32_e32 v86, 16, v88
	v_pk_add_f32 v[54:55], v[52:53], v[52:53] op_sel:[0,1] op_sel_hi:[1,0]
	v_and_b32_e32 v53, 0xffff0000, v89
	v_and_b32_e32 v52, 0xffff0000, v88
	v_pk_mul_f32 v[58:59], v[52:53], v[52:53]
	v_mov_b32_e32 v66, v96
	v_pk_fma_f32 v[58:59], v[86:87], v[86:87], v[58:59]
	v_mov_b32_e32 v67, v46
	v_pk_add_f32 v[54:55], v[58:59], v[54:55]
	v_mov_b32_e32 v46, v97
	v_pk_add_f32 v[96:97], v[58:59], v[54:55] op_sel:[1,0] op_sel_hi:[0,1]
	s_waitcnt vmcnt(1)
	v_and_b32_e32 v55, 0xffff0000, v90
	v_lshlrev_b32_e32 v54, 16, v90
	v_mul_f32_e32 v58, v55, v55
	v_pk_fma_f32 v[112:113], v[54:55], v[54:55], v[58:59] op_sel_hi:[1,1,0]
	v_and_b32_e32 v59, 0xffff0000, v91
	v_lshlrev_b32_e32 v58, 16, v91
	v_mul_f32_e32 v72, v59, v59
	v_and_b32_e32 v83, 0xffff0000, v71
	v_mov_b32_e32 v65, v44
	v_mov_b32_e32 v44, v99
	v_pk_fma_f32 v[114:115], v[58:59], v[58:59], v[72:73] op_sel_hi:[1,1,0]
	v_lshlrev_b32_e32 v82, 16, v71
	v_mul_f32_e32 v72, v83, v83
	v_and_b32_e32 v89, 0xffff0000, v70
	v_and_b32_e32 v99, 0xffff0000, v68
	v_mov_b32_e32 v64, v98
	v_pk_fma_f32 v[116:117], v[82:83], v[82:83], v[72:73] op_sel_hi:[1,1,0]
	v_lshlrev_b32_e32 v88, 16, v70
	v_and_b32_e32 v91, 0xffff0000, v69
	v_lshlrev_b32_e32 v98, 16, v68
	v_mov_b32_e32 v72, v89
	v_mov_b32_e32 v73, v99
	v_lshlrev_b32_e32 v90, 16, v69
	v_mul_f32_e32 v70, v91, v91
	v_mov_b32_e32 v68, v88
	v_mov_b32_e32 v69, v98
	v_pk_mul_f32 v[72:73], v[72:73], v[72:73]
	v_pk_fma_f32 v[70:71], v[90:91], v[90:91], v[70:71] op_sel_hi:[1,1,0]
	v_pk_fma_f32 v[68:69], v[68:69], v[68:69], v[72:73]
	v_mov_b32_e32 v100, v86
	v_pk_add_f32 v[70:71], v[68:69], v[70:71] op_sel:[1,0] op_sel_hi:[0,1]
	v_pk_add_f32 v[118:119], v[68:69], v[70:71]
	s_waitcnt vmcnt(0)
	v_pk_mov_b32 v[70:71], v[92:93], v[108:109] op_sel:[1,0]
	v_lshlrev_b32_e32 v69, 16, v108
	v_lshlrev_b32_e32 v86, 16, v109
	v_and_b32_e32 v109, 0xffff0000, v109
	v_and_b32_e32 v108, s0, v108
	v_mov_b32_e32 v101, v52
	v_mov_b32_e32 v52, v87
	v_mov_b32_e32 v87, v109
	v_pk_mul_f32 v[108:109], v[108:109], v[108:109]
	v_pk_add_f32 v[116:117], v[116:117], v[118:119]
	v_mov_b32_e32 v97, v109
	v_mul_f32_e32 v117, v86, v86
	v_pk_add_f32 v[108:109], v[116:117], v[96:97]
	v_lshlrev_b32_e32 v96, 16, v107
	v_and_b32_e32 v97, 0xffff0000, v107
	v_lshlrev_b32_e32 v73, 16, v106
	v_and_b32_e32 v79, 0xffff0000, v106
	v_and_b32_e32 v78, 0xffff0000, v92
	v_pk_mul_f32 v[106:107], v[96:97], v[96:97]
	v_lshlrev_b32_e32 v72, 16, v92
	v_lshlrev_b32_e32 v68, 16, v93
	v_and_b32_e32 v71, 0xffff0000, v71
	v_and_b32_e32 v70, 0xffff0000, v70
	v_pk_mul_f32 v[92:93], v[78:79], v[78:79]
	v_mov_b32_e32 v113, v106
	v_mov_b32_e32 v115, v107
	v_pk_fma_f32 v[120:121], v[72:73], v[72:73], v[92:93]
	v_pk_mul_f32 v[92:93], v[70:71], v[70:71]
	v_pk_add_f32 v[106:107], v[112:113], v[114:115]
	v_pk_fma_f32 v[122:123], v[68:69], v[68:69], v[92:93]
	v_pk_add_f32 v[106:107], v[120:121], v[106:107]
	v_mov_b32_e32 v92, v68
	v_pk_add_f32 v[106:107], v[122:123], v[106:107]
	v_mov_b32_e32 v93, v70
	v_pk_add_f32 v[106:107], v[108:109], v[106:107]
	v_mov_b32_e32 v109, v110
	v_mov_b32_e32 v108, v106
	v_mov_b32_e32 v110, v107
	v_pk_add_f32 v[106:107], v[108:109], v[110:111]
	ds_bpermute_b32 v109, v104, v107
	ds_bpermute_b32 v108, v104, v106
	v_mov_b32_e32 v102, v94
	v_mov_b32_e32 v103, v50
	v_mov_b32_e32 v50, v95
	v_mov_b32_e32 v94, v72
	s_waitcnt lgkmcnt(0)
	v_pk_add_f32 v[106:107], v[106:107], v[108:109]
	v_mov_b32_e32 v95, v78
	v_pk_fma_f32 v[110:111], v[106:107], s[2:3], v[176:177] op_sel_hi:[1,0,0]
	v_mov_b32_e32 v78, v73
	v_mul_f32_e32 v68, 0x4b800000, v111
	v_cmp_gt_f32_e64 s[6:7], s91, v111
	v_cmp_gt_f32_e64 s[4:5], s91, v110
	s_nop 0
	v_cndmask_b32_e64 v68, v111, v68, s[6:7]
	v_rsq_f32_e32 v68, v68
	s_nop 0
	v_mul_f32_e32 v70, 0x45800000, v68
	v_cndmask_b32_e64 v68, v68, v70, s[6:7]
	v_pk_mul_f32 v[60:61], v[68:69], v[60:61] op_sel_hi:[0,1]
	v_pk_mul_f32 v[36:37], v[68:69], v[36:37] op_sel_hi:[0,1]
	v_pk_mul_f32 v[60:61], v[4:5], v[60:61]
	v_pk_mul_f32 v[36:37], v[10:11], v[36:37]
	v_pk_mul_f32 v[62:63], v[68:69], v[62:63] op_sel_hi:[0,1]
	v_cvt_pk_bf16_f32 v108, v60, v61
	v_cvt_pk_bf16_f32 v61, v36, v37
	v_pk_mul_f32 v[36:37], v[68:69], v[80:81] op_sel_hi:[0,1]
	v_pk_mul_f32 v[62:63], v[2:3], v[62:63]
	v_pk_mul_f32 v[36:37], v[12:13], v[36:37]
	v_cvt_pk_bf16_f32 v107, v62, v63
	v_cvt_pk_bf16_f32 v62, v36, v37
	v_pk_mul_f32 v[36:37], v[68:69], v[38:39] op_sel_hi:[0,1]
	v_pk_mul_f32 v[36:37], v[14:15], v[36:37]
	v_pk_mul_f32 v[38:39], v[68:69], v[42:43] op_sel_hi:[0,1]
	v_cvt_pk_bf16_f32 v63, v36, v37
	v_pk_mul_f32 v[36:37], v[68:69], v[40:41] op_sel_hi:[0,1]
	v_pk_mul_f32 v[36:37], v[16:17], v[36:37]
	v_pk_mul_f32 v[38:39], v[18:19], v[38:39]
	v_cvt_pk_bf16_f32 v36, v36, v37
	v_cvt_pk_bf16_f32 v37, v38, v39
	v_pk_mul_f32 v[38:39], v[68:69], v[66:67] op_sel_hi:[0,1]
	v_pk_mul_f32 v[40:41], v[68:69], v[64:65] op_sel_hi:[0,1]
	v_pk_mul_f32 v[38:39], v[20:21], v[38:39]
	v_pk_mul_f32 v[40:41], v[22:23], v[40:41]
	v_cvt_pk_bf16_f32 v38, v38, v39
	v_cvt_pk_bf16_f32 v39, v40, v41
	v_pk_mul_f32 v[48:49], v[68:69], v[48:49] op_sel_hi:[0,1]
	global_store_dwordx4 v[34:35], v[36:39], off offset:2048 sc1
	v_pk_mul_f32 v[48:49], v[6:7], v[48:49]
	v_pk_mul_f32 v[76:77], v[68:69], v[76:77] op_sel_hi:[0,1]
	v_pk_mul_f32 v[36:37], v[68:69], v[46:47] op_sel_hi:[0,1]
	v_pk_mul_f32 v[38:39], v[68:69], v[74:75] op_sel_hi:[0,1]
	v_pk_mul_f32 v[36:37], v[24:25], v[36:37]
	v_pk_mul_f32 v[38:39], v[26:27], v[38:39]
	v_cvt_pk_bf16_f32 v109, v48, v49
	v_pk_mul_f32 v[48:49], v[68:69], v[84:85] op_sel_hi:[0,1]
	v_cvt_pk_bf16_f32 v36, v36, v37
	v_cvt_pk_bf16_f32 v37, v38, v39
	v_pk_mul_f32 v[38:39], v[68:69], v[44:45] op_sel_hi:[0,1]
	v_pk_mul_f32 v[40:41], v[68:69], v[56:57] op_sel_hi:[0,1]
	v_pk_mul_f32 v[76:77], v[0:1], v[76:77]
	v_pk_mul_f32 v[48:49], v[8:9], v[48:49]
	v_pk_mul_f32 v[38:39], v[28:29], v[38:39]
	v_pk_mul_f32 v[40:41], v[30:31], v[40:41]
	v_cvt_pk_bf16_f32 v106, v76, v77
	v_cvt_pk_bf16_f32 v60, v48, v49
	v_cvt_pk_bf16_f32 v38, v38, v39
	v_cvt_pk_bf16_f32 v39, v40, v41
	global_store_dwordx4 v[34:35], v[106:109], off sc1
	global_store_dwordx4 v[34:35], v[60:63], off offset:1024 sc1
	global_store_dwordx4 v[34:35], v[36:39], off offset:3072 sc1
	v_mul_f32_e32 v34, 0x4b800000, v110
	v_cndmask_b32_e64 v34, v110, v34, s[4:5]
	v_rsq_f32_e32 v34, v34
	v_mov_b32_e32 v70, v69
	s_mov_b32 s6, 2
	v_mul_f32_e32 v35, 0x45800000, v34
	v_cndmask_b32_e64 v38, v34, v35, s[4:5]
	v_pk_mul_f32 v[34:35], v[38:39], v[98:99] op_sel_hi:[0,1]
	v_pk_mul_f32 v[36:37], v[38:39], v[90:91] op_sel_hi:[0,1]
	v_pk_mul_f32 v[34:35], v[0:1], v[34:35]
	v_pk_mul_f32 v[36:37], v[2:3], v[36:37]
	v_cvt_pk_bf16_f32 v34, v34, v35
	v_cvt_pk_bf16_f32 v35, v36, v37
	v_pk_mul_f32 v[36:37], v[38:39], v[88:89] op_sel_hi:[0,1]
	v_pk_mul_f32 v[40:41], v[38:39], v[82:83] op_sel_hi:[0,1]
	v_pk_mul_f32 v[36:37], v[4:5], v[36:37]
	v_pk_mul_f32 v[40:41], v[6:7], v[40:41]
	v_cvt_pk_bf16_f32 v36, v36, v37
	v_cvt_pk_bf16_f32 v37, v40, v41
	global_store_dwordx4 v[32:33], v[34:37], off sc1
	v_pk_mul_f32 v[40:41], v[38:39], v[52:53] op_sel_hi:[0,1]
	v_pk_mul_f32 v[40:41], v[14:15], v[40:41]
	v_pk_mul_f32 v[34:35], v[38:39], v[102:103] op_sel_hi:[0,1]
	v_pk_mul_f32 v[36:37], v[38:39], v[50:51] op_sel_hi:[0,1]
	v_pk_mul_f32 v[34:35], v[8:9], v[34:35]
	v_pk_mul_f32 v[36:37], v[10:11], v[36:37]
	v_cvt_pk_bf16_f32 v34, v34, v35
	v_cvt_pk_bf16_f32 v35, v36, v37
	v_pk_mul_f32 v[36:37], v[38:39], v[100:101] op_sel_hi:[0,1]
	v_pk_mul_f32 v[36:37], v[12:13], v[36:37]
	s_mov_b64 s[4:5], 0
	v_cvt_pk_bf16_f32 v36, v36, v37
	v_cvt_pk_bf16_f32 v37, v40, v41
	global_store_dwordx4 v[32:33], v[34:37], off offset:1024 sc1
	v_pk_mul_f32 v[40:41], v[38:39], v[92:93] op_sel_hi:[0,1]
	v_pk_mul_f32 v[40:41], v[22:23], v[40:41]
	v_pk_mul_f32 v[34:35], v[38:39], v[54:55] op_sel_hi:[0,1]
	v_pk_mul_f32 v[36:37], v[38:39], v[58:59] op_sel_hi:[0,1]
	v_pk_mul_f32 v[34:35], v[16:17], v[34:35]
	v_pk_mul_f32 v[36:37], v[18:19], v[36:37]
	v_cvt_pk_bf16_f32 v34, v34, v35
	v_cvt_pk_bf16_f32 v35, v36, v37
	v_pk_mul_f32 v[36:37], v[38:39], v[94:95] op_sel_hi:[0,1]
	v_pk_mul_f32 v[36:37], v[20:21], v[36:37]
	s_nop 0
	v_cvt_pk_bf16_f32 v36, v36, v37
	v_cvt_pk_bf16_f32 v37, v40, v41
	global_store_dwordx4 v[32:33], v[34:37], off offset:2048 sc1
	s_nop 1
	v_pk_mul_f32 v[34:35], v[38:39], v[78:79] op_sel_hi:[0,1]
	v_pk_mul_f32 v[36:37], v[38:39], v[96:97] op_sel_hi:[0,1]
	v_pk_mul_f32 v[34:35], v[24:25], v[34:35]
	v_pk_mul_f32 v[36:37], v[26:27], v[36:37]
	v_cvt_pk_bf16_f32 v34, v34, v35
	v_cvt_pk_bf16_f32 v35, v36, v37
	v_pk_mul_f32 v[36:37], v[38:39], v[70:71] op_sel_hi:[0,1]
	v_pk_mul_f32 v[38:39], v[38:39], v[86:87] op_sel_hi:[0,1]
	v_pk_mul_f32 v[36:37], v[28:29], v[36:37]
	v_pk_mul_f32 v[38:39], v[30:31], v[38:39]
	v_cvt_pk_bf16_f32 v36, v36, v37
	v_cvt_pk_bf16_f32 v37, v38, v39
	global_store_dwordx4 v[32:33], v[34:37], off offset:3072 sc1
	s_cbranch_vccz .LBB0_521
	s_add_i32 s16, s16, 1
	s_mov_b64 s[6:7], 0
	s_branch .LBB0_514

.LBB0_533:
	s_ashr_i32 s2, s24, 8
	v_mad_i64_i32 v[86:87], s[4:5], s2, v207, v[82:83]
	v_mad_i64_i32 v[88:89], s[4:5], s2, v207, v[80:81]
	global_load_dwordx4 v[100:103], v[86:87], off
	global_load_dwordx4 v[104:107], v[86:87], off offset:1024
	global_load_dwordx4 v[108:111], v[86:87], off offset:2048
	global_load_dwordx4 v[112:115], v[86:87], off offset:3072
	global_load_dwordx4 v[64:67], v[96:97], off
	global_load_dwordx4 v[68:71], v[96:97], off offset:1024
	global_load_dwordx4 v[72:75], v[96:97], off offset:2048
	global_load_dwordx4 v[76:79], v[96:97], off offset:3072
	global_load_dwordx4 v[116:119], v[88:89], off
	global_load_dwordx4 v[120:123], v[88:89], off offset:1024
	global_load_dwordx4 v[124:127], v[88:89], off offset:2048
	global_load_dwordx4 v[128:131], v[88:89], off offset:3072
	s_ashr_i32 s7, s6, 31
	s_lshl_b64 s[14:15], s[6:7], 12
	s_add_u32 s14, s30, s14
	s_addc_u32 s15, s31, s15
	s_lshl_b64 s[20:21], s[6:7], 11
	v_mov_b32_e32 v228, s70
	v_lshl_add_u64 v[230:231], s[14:15], 0, v[174:175]
	global_load_dwordx4 v[0:3], v[230:231], off
	global_load_dwordx4 v[4:7], v[230:231], off offset:1024
	global_load_dwordx4 v[8:11], v[230:231], off offset:2048
	global_load_dwordx4 v[12:15], v[230:231], off offset:3072
	s_add_u32 s14, s14, 0x1000
	s_addc_u32 s15, s15, 0
	v_lshl_add_u64 v[232:233], s[14:15], 0, v[174:175]
	global_load_dwordx4 v[16:19], v[232:233], off
	global_load_dwordx4 v[20:23], v[232:233], off offset:1024
	global_load_dwordx4 v[24:27], v[232:233], off offset:2048
	global_load_dwordx4 v[28:31], v[232:233], off offset:3072
	s_add_u32 s14, s14, 0x1000
	s_addc_u32 s15, s15, 0
	v_lshl_add_u64 v[230:231], s[14:15], 0, v[174:175]
	global_load_dwordx4 v[32:35], v[230:231], off
	global_load_dwordx4 v[36:39], v[230:231], off offset:1024
	global_load_dwordx4 v[40:43], v[230:231], off offset:2048
	global_load_dwordx4 v[44:47], v[230:231], off offset:3072
	s_add_u32 s14, s14, 0x1000
	s_addc_u32 s15, s15, 0
	v_lshl_add_u64 v[232:233], s[14:15], 0, v[174:175]
	global_load_dwordx4 v[48:51], v[232:233], off
	global_load_dwordx4 v[52:55], v[232:233], off offset:1024
	global_load_dwordx4 v[56:59], v[232:233], off offset:2048
	global_load_dwordx4 v[60:63], v[232:233], off offset:3072
	s_add_u32 s14, s14, 0x1000
	s_addc_u32 s15, s15, 0
	v_lshl_add_u64 v[230:231], s[14:15], 0, v[174:175]
	global_load_dwordx4 v[136:139], v[230:231], off
	global_load_dwordx4 v[140:143], v[230:231], off offset:1024
	global_load_dwordx4 v[144:147], v[230:231], off offset:2048
	global_load_dwordx4 v[148:151], v[230:231], off offset:3072
	s_add_u32 s14, s14, 0x1000
	s_addc_u32 s15, s15, 0
	v_lshl_add_u64 v[232:233], s[14:15], 0, v[174:175]
	global_load_dwordx4 v[152:155], v[232:233], off
	global_load_dwordx4 v[156:159], v[232:233], off offset:1024
	global_load_dwordx4 v[160:163], v[232:233], off offset:2048
	global_load_dwordx4 v[164:167], v[232:233], off offset:3072
	s_add_u32 s14, s14, 0x1000
	s_addc_u32 s15, s15, 0
	v_lshl_add_u64 v[230:231], s[14:15], 0, v[174:175]
	global_load_dwordx4 v[168:171], v[230:231], off
	global_load_dwordx4 v[184:187], v[230:231], off offset:1024
	global_load_dwordx4 v[188:191], v[230:231], off offset:2048
	global_load_dwordx4 v[192:195], v[230:231], off offset:3072
	s_add_u32 s14, s14, 0x1000
	s_addc_u32 s15, s15, 0
	v_lshl_add_u64 v[232:233], s[14:15], 0, v[174:175]
	global_load_dwordx4 v[196:199], v[232:233], off
	global_load_dwordx4 v[200:203], v[232:233], off offset:1024
	global_load_dwordx4 v[212:215], v[232:233], off offset:2048
	global_load_dwordx4 v[216:219], v[232:233], off offset:3072
	s_add_u32 s14, s14, 0x1000
	s_addc_u32 s15, s15, 0
	s_waitcnt vmcnt(32)
	v_pk_add_f32 v[100:101], v[100:101], 1.0 op_sel_hi:[1,0]
	v_pk_add_f32 v[102:103], v[102:103], 1.0 op_sel_hi:[1,0]
	v_pk_add_f32 v[104:105], v[104:105], 1.0 op_sel_hi:[1,0]
	v_pk_add_f32 v[106:107], v[106:107], 1.0 op_sel_hi:[1,0]
	v_pk_add_f32 v[108:109], v[108:109], 1.0 op_sel_hi:[1,0]
	v_pk_add_f32 v[110:111], v[110:111], 1.0 op_sel_hi:[1,0]
	v_pk_add_f32 v[112:113], v[112:113], 1.0 op_sel_hi:[1,0]
	v_pk_add_f32 v[114:115], v[114:115], 1.0 op_sel_hi:[1,0]
	v_pk_mul_f32 v[64:65], v[64:65], v[100:101]
	v_pk_mul_f32 v[66:67], v[66:67], v[102:103]
	v_pk_mul_f32 v[68:69], v[68:69], v[104:105]
	v_pk_mul_f32 v[70:71], v[70:71], v[106:107]
	v_pk_mul_f32 v[72:73], v[72:73], v[108:109]
	v_pk_mul_f32 v[74:75], v[74:75], v[110:111]
	v_pk_mul_f32 v[76:77], v[76:77], v[112:113]
	v_pk_mul_f32 v[78:79], v[78:79], v[114:115]
	s_waitcnt vmcnt(16)
	v_pk_mul_f32 v[220:221], v[0:1], v[0:1]
	v_pk_mul_f32 v[222:223], v[16:17], v[16:17]
	v_pk_mul_f32 v[224:225], v[32:33], v[32:33]
	v_pk_mul_f32 v[226:227], v[48:49], v[48:49]
	v_pk_fma_f32 v[220:221], v[2:3], v[2:3], v[220:221]
	v_pk_fma_f32 v[222:223], v[18:19], v[18:19], v[222:223]
	v_pk_fma_f32 v[224:225], v[34:35], v[34:35], v[224:225]
	v_pk_fma_f32 v[226:227], v[50:51], v[50:51], v[226:227]
	v_pk_fma_f32 v[220:221], v[4:5], v[4:5], v[220:221]
	v_pk_fma_f32 v[222:223], v[20:21], v[20:21], v[222:223]
	v_pk_fma_f32 v[224:225], v[36:37], v[36:37], v[224:225]
	v_pk_fma_f32 v[226:227], v[52:53], v[52:53], v[226:227]
	v_pk_fma_f32 v[220:221], v[6:7], v[6:7], v[220:221]
	v_pk_fma_f32 v[222:223], v[22:23], v[22:23], v[222:223]
	v_pk_fma_f32 v[224:225], v[38:39], v[38:39], v[224:225]
	v_pk_fma_f32 v[226:227], v[54:55], v[54:55], v[226:227]
	v_pk_fma_f32 v[220:221], v[8:9], v[8:9], v[220:221]
	v_pk_fma_f32 v[222:223], v[24:25], v[24:25], v[222:223]
	v_pk_fma_f32 v[224:225], v[40:41], v[40:41], v[224:225]
	v_pk_fma_f32 v[226:227], v[56:57], v[56:57], v[226:227]
	v_pk_fma_f32 v[220:221], v[10:11], v[10:11], v[220:221]
	v_pk_fma_f32 v[222:223], v[26:27], v[26:27], v[222:223]
	v_pk_fma_f32 v[224:225], v[42:43], v[42:43], v[224:225]
	v_pk_fma_f32 v[226:227], v[58:59], v[58:59], v[226:227]
	v_pk_fma_f32 v[220:221], v[12:13], v[12:13], v[220:221]
	v_pk_fma_f32 v[222:223], v[28:29], v[28:29], v[222:223]
	v_pk_fma_f32 v[224:225], v[44:45], v[44:45], v[224:225]
	v_pk_fma_f32 v[226:227], v[60:61], v[60:61], v[226:227]
	v_pk_fma_f32 v[220:221], v[14:15], v[14:15], v[220:221]
	v_pk_fma_f32 v[222:223], v[30:31], v[30:31], v[222:223]
	v_pk_fma_f32 v[224:225], v[46:47], v[46:47], v[224:225]
	v_pk_fma_f32 v[226:227], v[62:63], v[62:63], v[226:227]
	v_add_f32_e32 v220, v220, v221
	v_add_f32_e32 v222, v222, v223
	v_add_f32_e32 v224, v224, v225
	v_add_f32_e32 v226, v226, v227
	v_add_f32_dpp v220, v220, v220 quad_perm:[1,0,3,2] row_mask:0xf bank_mask:0xf
	v_add_f32_dpp v222, v222, v222 quad_perm:[1,0,3,2] row_mask:0xf bank_mask:0xf
	v_add_f32_dpp v224, v224, v224 quad_perm:[1,0,3,2] row_mask:0xf bank_mask:0xf
	v_add_f32_dpp v226, v226, v226 quad_perm:[1,0,3,2] row_mask:0xf bank_mask:0xf
	v_add_f32_dpp v220, v220, v220 quad_perm:[2,3,0,1] row_mask:0xf bank_mask:0xf
	v_add_f32_dpp v222, v222, v222 quad_perm:[2,3,0,1] row_mask:0xf bank_mask:0xf
	v_add_f32_dpp v224, v224, v224 quad_perm:[2,3,0,1] row_mask:0xf bank_mask:0xf
	v_add_f32_dpp v226, v226, v226 quad_perm:[2,3,0,1] row_mask:0xf bank_mask:0xf
	v_add_f32_dpp v220, v220, v220 row_half_mirror row_mask:0xf bank_mask:0xf
	v_add_f32_dpp v222, v222, v222 row_half_mirror row_mask:0xf bank_mask:0xf
	v_add_f32_dpp v224, v224, v224 row_half_mirror row_mask:0xf bank_mask:0xf
	v_add_f32_dpp v226, v226, v226 row_half_mirror row_mask:0xf bank_mask:0xf
	v_add_f32_dpp v220, v220, v220 row_mirror row_mask:0xf bank_mask:0xf
	v_add_f32_dpp v222, v222, v222 row_mirror row_mask:0xf bank_mask:0xf
	v_add_f32_dpp v224, v224, v224 row_mirror row_mask:0xf bank_mask:0xf
	v_add_f32_dpp v226, v226, v226 row_mirror row_mask:0xf bank_mask:0xf
	v_add_f32_dpp v220, v220, v220 row_bcast:15 row_mask:0xa bank_mask:0xf
	v_add_f32_dpp v222, v222, v222 row_bcast:15 row_mask:0xa bank_mask:0xf
	v_add_f32_dpp v224, v224, v224 row_bcast:15 row_mask:0xa bank_mask:0xf
	v_add_f32_dpp v226, v226, v226 row_bcast:15 row_mask:0xa bank_mask:0xf
	v_add_f32_dpp v220, v220, v220 row_bcast:31 row_mask:0xc bank_mask:0xf
	v_add_f32_dpp v222, v222, v222 row_bcast:31 row_mask:0xc bank_mask:0xf
	v_add_f32_dpp v224, v224, v224 row_bcast:31 row_mask:0xc bank_mask:0xf
	v_add_f32_dpp v226, v226, v226 row_bcast:31 row_mask:0xc bank_mask:0xf
	v_fma_f32 v220, v220, s88, v228
	v_fma_f32 v222, v222, s88, v228
	v_fma_f32 v224, v224, s88, v228
	v_fma_f32 v226, v226, s88, v228
	v_rsq_f32_e32 v220, v220
	v_rsq_f32_e32 v222, v222
	v_rsq_f32_e32 v224, v224
	v_rsq_f32_e32 v226, v226
	v_readlane_b32 s16, v220, 63
	v_readlane_b32 s17, v222, 63
	v_readlane_b32 s18, v224, 63
	v_readlane_b32 s19, v226, 63
	v_lshl_add_u64 v[230:231], v[84:85], 0, s[20:21]
	s_add_u32 s20, s20, 0x1000
	s_addc_u32 s21, s21, 0
	v_lshl_add_u64 v[232:233], v[84:85], 0, s[20:21]
	s_add_u32 s20, s20, 0x1000
	s_addc_u32 s21, s21, 0
	v_pk_mul_f32 v[0:1], v[0:1], s[16:17] op_sel_hi:[1,0]
	v_pk_mul_f32 v[2:3], v[2:3], s[16:17] op_sel_hi:[1,0]
	v_pk_mul_f32 v[4:5], v[4:5], s[16:17] op_sel_hi:[1,0]
	v_pk_mul_f32 v[6:7], v[6:7], s[16:17] op_sel_hi:[1,0]
	v_pk_mul_f32 v[8:9], v[8:9], s[16:17] op_sel_hi:[1,0]
	v_pk_mul_f32 v[10:11], v[10:11], s[16:17] op_sel_hi:[1,0]
	v_pk_mul_f32 v[12:13], v[12:13], s[16:17] op_sel_hi:[1,0]
	v_pk_mul_f32 v[14:15], v[14:15], s[16:17] op_sel_hi:[1,0]
	v_pk_mul_f32 v[16:17], v[16:17], s[16:17] op_sel:[0,1] op_sel_hi:[1,1]
	v_pk_mul_f32 v[18:19], v[18:19], s[16:17] op_sel:[0,1] op_sel_hi:[1,1]
	v_pk_mul_f32 v[20:21], v[20:21], s[16:17] op_sel:[0,1] op_sel_hi:[1,1]
	v_pk_mul_f32 v[22:23], v[22:23], s[16:17] op_sel:[0,1] op_sel_hi:[1,1]
	v_pk_mul_f32 v[24:25], v[24:25], s[16:17] op_sel:[0,1] op_sel_hi:[1,1]
	v_pk_mul_f32 v[26:27], v[26:27], s[16:17] op_sel:[0,1] op_sel_hi:[1,1]
	v_pk_mul_f32 v[28:29], v[28:29], s[16:17] op_sel:[0,1] op_sel_hi:[1,1]
	v_pk_mul_f32 v[30:31], v[30:31], s[16:17] op_sel:[0,1] op_sel_hi:[1,1]
	v_pk_mul_f32 v[32:33], v[32:33], s[18:19] op_sel_hi:[1,0]
	v_pk_mul_f32 v[34:35], v[34:35], s[18:19] op_sel_hi:[1,0]
	v_pk_mul_f32 v[36:37], v[36:37], s[18:19] op_sel_hi:[1,0]
	v_pk_mul_f32 v[38:39], v[38:39], s[18:19] op_sel_hi:[1,0]
	v_pk_mul_f32 v[40:41], v[40:41], s[18:19] op_sel_hi:[1,0]
	v_pk_mul_f32 v[42:43], v[42:43], s[18:19] op_sel_hi:[1,0]
	v_pk_mul_f32 v[44:45], v[44:45], s[18:19] op_sel_hi:[1,0]
	v_pk_mul_f32 v[46:47], v[46:47], s[18:19] op_sel_hi:[1,0]
	v_pk_mul_f32 v[48:49], v[48:49], s[18:19] op_sel:[0,1] op_sel_hi:[1,1]
	v_pk_mul_f32 v[50:51], v[50:51], s[18:19] op_sel:[0,1] op_sel_hi:[1,1]
	v_pk_mul_f32 v[52:53], v[52:53], s[18:19] op_sel:[0,1] op_sel_hi:[1,1]
	v_pk_mul_f32 v[54:55], v[54:55], s[18:19] op_sel:[0,1] op_sel_hi:[1,1]
	v_pk_mul_f32 v[56:57], v[56:57], s[18:19] op_sel:[0,1] op_sel_hi:[1,1]
	v_pk_mul_f32 v[58:59], v[58:59], s[18:19] op_sel:[0,1] op_sel_hi:[1,1]
	v_pk_mul_f32 v[60:61], v[60:61], s[18:19] op_sel:[0,1] op_sel_hi:[1,1]
	v_pk_mul_f32 v[62:63], v[62:63], s[18:19] op_sel:[0,1] op_sel_hi:[1,1]
	v_pk_fma_f32 v[0:1], v[64:65], v[0:1], v[116:117]
	v_pk_fma_f32 v[2:3], v[66:67], v[2:3], v[118:119]
	v_pk_fma_f32 v[4:5], v[68:69], v[4:5], v[120:121]
	v_pk_fma_f32 v[6:7], v[70:71], v[6:7], v[122:123]
	v_pk_fma_f32 v[8:9], v[72:73], v[8:9], v[124:125]
	v_pk_fma_f32 v[10:11], v[74:75], v[10:11], v[126:127]
	v_pk_fma_f32 v[12:13], v[76:77], v[12:13], v[128:129]
	v_pk_fma_f32 v[14:15], v[78:79], v[14:15], v[130:131]
	v_pk_fma_f32 v[16:17], v[64:65], v[16:17], v[116:117]
	v_pk_fma_f32 v[18:19], v[66:67], v[18:19], v[118:119]
	v_pk_fma_f32 v[20:21], v[68:69], v[20:21], v[120:121]
	v_pk_fma_f32 v[22:23], v[70:71], v[22:23], v[122:123]
	v_pk_fma_f32 v[24:25], v[72:73], v[24:25], v[124:125]
	v_pk_fma_f32 v[26:27], v[74:75], v[26:27], v[126:127]
	v_pk_fma_f32 v[28:29], v[76:77], v[28:29], v[128:129]
	v_pk_fma_f32 v[30:31], v[78:79], v[30:31], v[130:131]
	v_pk_fma_f32 v[32:33], v[64:65], v[32:33], v[116:117]
	v_pk_fma_f32 v[34:35], v[66:67], v[34:35], v[118:119]
	v_pk_fma_f32 v[36:37], v[68:69], v[36:37], v[120:121]
	v_pk_fma_f32 v[38:39], v[70:71], v[38:39], v[122:123]
	v_pk_fma_f32 v[40:41], v[72:73], v[40:41], v[124:125]
	v_pk_fma_f32 v[42:43], v[74:75], v[42:43], v[126:127]
	v_pk_fma_f32 v[44:45], v[76:77], v[44:45], v[128:129]
	v_pk_fma_f32 v[46:47], v[78:79], v[46:47], v[130:131]
	v_pk_fma_f32 v[48:49], v[64:65], v[48:49], v[116:117]
	v_pk_fma_f32 v[50:51], v[66:67], v[50:51], v[118:119]
	v_pk_fma_f32 v[52:53], v[68:69], v[52:53], v[120:121]
	v_pk_fma_f32 v[54:55], v[70:71], v[54:55], v[122:123]
	v_pk_fma_f32 v[56:57], v[72:73], v[56:57], v[124:125]
	v_pk_fma_f32 v[58:59], v[74:75], v[58:59], v[126:127]
	v_pk_fma_f32 v[60:61], v[76:77], v[60:61], v[128:129]
	v_pk_fma_f32 v[62:63], v[78:79], v[62:63], v[130:131]
	v_cvt_pk_bf16_f32 v0, v0, v1
	v_cvt_pk_bf16_f32 v1, v2, v3
	v_cvt_pk_bf16_f32 v4, v4, v5
	v_cvt_pk_bf16_f32 v5, v6, v7
	v_cvt_pk_bf16_f32 v8, v8, v9
	v_cvt_pk_bf16_f32 v9, v10, v11
	v_cvt_pk_bf16_f32 v12, v12, v13
	v_cvt_pk_bf16_f32 v13, v14, v15
	v_cvt_pk_bf16_f32 v16, v16, v17
	v_cvt_pk_bf16_f32 v17, v18, v19
	v_cvt_pk_bf16_f32 v20, v20, v21
	v_cvt_pk_bf16_f32 v21, v22, v23
	v_cvt_pk_bf16_f32 v24, v24, v25
	v_cvt_pk_bf16_f32 v25, v26, v27
	v_cvt_pk_bf16_f32 v28, v28, v29
	v_cvt_pk_bf16_f32 v29, v30, v31
	v_cvt_pk_bf16_f32 v32, v32, v33
	v_cvt_pk_bf16_f32 v33, v34, v35
	v_cvt_pk_bf16_f32 v36, v36, v37
	v_cvt_pk_bf16_f32 v37, v38, v39
	v_cvt_pk_bf16_f32 v40, v40, v41
	v_cvt_pk_bf16_f32 v41, v42, v43
	v_cvt_pk_bf16_f32 v44, v44, v45
	v_cvt_pk_bf16_f32 v45, v46, v47
	v_cvt_pk_bf16_f32 v48, v48, v49
	v_cvt_pk_bf16_f32 v49, v50, v51
	v_cvt_pk_bf16_f32 v52, v52, v53
	v_cvt_pk_bf16_f32 v53, v54, v55
	v_cvt_pk_bf16_f32 v56, v56, v57
	v_cvt_pk_bf16_f32 v57, v58, v59
	v_cvt_pk_bf16_f32 v60, v60, v61
	v_cvt_pk_bf16_f32 v61, v62, v63
	global_store_dwordx2 v[230:231], v[0:1], off sc1
	global_store_dwordx2 v[230:231], v[4:5], off offset:512 sc1
	global_store_dwordx2 v[230:231], v[8:9], off offset:1024 sc1
	global_store_dwordx2 v[230:231], v[12:13], off offset:1536 sc1
	global_store_dwordx2 v[230:231], v[16:17], off offset:2048 sc1
	global_store_dwordx2 v[230:231], v[20:21], off offset:2560 sc1
	global_store_dwordx2 v[230:231], v[24:25], off offset:3072 sc1
	global_store_dwordx2 v[230:231], v[28:29], off offset:3584 sc1
	global_store_dwordx2 v[232:233], v[32:33], off sc1
	global_store_dwordx2 v[232:233], v[36:37], off offset:512 sc1
	global_store_dwordx2 v[232:233], v[40:41], off offset:1024 sc1
	global_store_dwordx2 v[232:233], v[44:45], off offset:1536 sc1
	global_store_dwordx2 v[232:233], v[48:49], off offset:2048 sc1
	global_store_dwordx2 v[232:233], v[52:53], off offset:2560 sc1
	global_store_dwordx2 v[232:233], v[56:57], off offset:3072 sc1
	global_store_dwordx2 v[232:233], v[60:61], off offset:3584 sc1
	v_lshl_add_u64 v[230:231], s[14:15], 0, v[174:175]
	global_load_dwordx4 v[0:3], v[230:231], off
	global_load_dwordx4 v[4:7], v[230:231], off offset:1024
	global_load_dwordx4 v[8:11], v[230:231], off offset:2048
	global_load_dwordx4 v[12:15], v[230:231], off offset:3072
	s_add_u32 s14, s14, 0x1000
	s_addc_u32 s15, s15, 0
	v_lshl_add_u64 v[232:233], s[14:15], 0, v[174:175]
	global_load_dwordx4 v[16:19], v[232:233], off
	global_load_dwordx4 v[20:23], v[232:233], off offset:1024
	global_load_dwordx4 v[24:27], v[232:233], off offset:2048
	global_load_dwordx4 v[28:31], v[232:233], off offset:3072
	s_add_u32 s14, s14, 0x1000
	s_addc_u32 s15, s15, 0
	v_lshl_add_u64 v[230:231], s[14:15], 0, v[174:175]
	global_load_dwordx4 v[32:35], v[230:231], off
	global_load_dwordx4 v[36:39], v[230:231], off offset:1024
	global_load_dwordx4 v[40:43], v[230:231], off offset:2048
	global_load_dwordx4 v[44:47], v[230:231], off offset:3072
	s_add_u32 s14, s14, 0x1000
	s_addc_u32 s15, s15, 0
	v_lshl_add_u64 v[232:233], s[14:15], 0, v[174:175]
	global_load_dwordx4 v[48:51], v[232:233], off
	global_load_dwordx4 v[52:55], v[232:233], off offset:1024
	global_load_dwordx4 v[56:59], v[232:233], off offset:2048
	global_load_dwordx4 v[60:63], v[232:233], off offset:3072
	s_add_u32 s14, s14, 0x1000
	s_addc_u32 s15, s15, 0
	s_waitcnt vmcnt(32)
	v_pk_mul_f32 v[220:221], v[136:137], v[136:137]
	v_pk_mul_f32 v[222:223], v[152:153], v[152:153]
	v_pk_mul_f32 v[224:225], v[168:169], v[168:169]
	v_pk_mul_f32 v[226:227], v[196:197], v[196:197]
	v_pk_fma_f32 v[220:221], v[138:139], v[138:139], v[220:221]
	v_pk_fma_f32 v[222:223], v[154:155], v[154:155], v[222:223]
	v_pk_fma_f32 v[224:225], v[170:171], v[170:171], v[224:225]
	v_pk_fma_f32 v[226:227], v[198:199], v[198:199], v[226:227]
	v_pk_fma_f32 v[220:221], v[140:141], v[140:141], v[220:221]
	v_pk_fma_f32 v[222:223], v[156:157], v[156:157], v[222:223]
	v_pk_fma_f32 v[224:225], v[184:185], v[184:185], v[224:225]
	v_pk_fma_f32 v[226:227], v[200:201], v[200:201], v[226:227]
	v_pk_fma_f32 v[220:221], v[142:143], v[142:143], v[220:221]
	v_pk_fma_f32 v[222:223], v[158:159], v[158:159], v[222:223]
	v_pk_fma_f32 v[224:225], v[186:187], v[186:187], v[224:225]
	v_pk_fma_f32 v[226:227], v[202:203], v[202:203], v[226:227]
	v_pk_fma_f32 v[220:221], v[144:145], v[144:145], v[220:221]
	v_pk_fma_f32 v[222:223], v[160:161], v[160:161], v[222:223]
	v_pk_fma_f32 v[224:225], v[188:189], v[188:189], v[224:225]
	v_pk_fma_f32 v[226:227], v[212:213], v[212:213], v[226:227]
	v_pk_fma_f32 v[220:221], v[146:147], v[146:147], v[220:221]
	v_pk_fma_f32 v[222:223], v[162:163], v[162:163], v[222:223]
	v_pk_fma_f32 v[224:225], v[190:191], v[190:191], v[224:225]
	v_pk_fma_f32 v[226:227], v[214:215], v[214:215], v[226:227]
	v_pk_fma_f32 v[220:221], v[148:149], v[148:149], v[220:221]
	v_pk_fma_f32 v[222:223], v[164:165], v[164:165], v[222:223]
	v_pk_fma_f32 v[224:225], v[192:193], v[192:193], v[224:225]
	v_pk_fma_f32 v[226:227], v[216:217], v[216:217], v[226:227]
	v_pk_fma_f32 v[220:221], v[150:151], v[150:151], v[220:221]
	v_pk_fma_f32 v[222:223], v[166:167], v[166:167], v[222:223]
	v_pk_fma_f32 v[224:225], v[194:195], v[194:195], v[224:225]
	v_pk_fma_f32 v[226:227], v[218:219], v[218:219], v[226:227]
	v_add_f32_e32 v220, v220, v221
	v_add_f32_e32 v222, v222, v223
	v_add_f32_e32 v224, v224, v225
	v_add_f32_e32 v226, v226, v227
	v_add_f32_dpp v220, v220, v220 quad_perm:[1,0,3,2] row_mask:0xf bank_mask:0xf
	v_add_f32_dpp v222, v222, v222 quad_perm:[1,0,3,2] row_mask:0xf bank_mask:0xf
	v_add_f32_dpp v224, v224, v224 quad_perm:[1,0,3,2] row_mask:0xf bank_mask:0xf
	v_add_f32_dpp v226, v226, v226 quad_perm:[1,0,3,2] row_mask:0xf bank_mask:0xf
	v_add_f32_dpp v220, v220, v220 quad_perm:[2,3,0,1] row_mask:0xf bank_mask:0xf
	v_add_f32_dpp v222, v222, v222 quad_perm:[2,3,0,1] row_mask:0xf bank_mask:0xf
	v_add_f32_dpp v224, v224, v224 quad_perm:[2,3,0,1] row_mask:0xf bank_mask:0xf
	v_add_f32_dpp v226, v226, v226 quad_perm:[2,3,0,1] row_mask:0xf bank_mask:0xf
	v_add_f32_dpp v220, v220, v220 row_half_mirror row_mask:0xf bank_mask:0xf
	v_add_f32_dpp v222, v222, v222 row_half_mirror row_mask:0xf bank_mask:0xf
	v_add_f32_dpp v224, v224, v224 row_half_mirror row_mask:0xf bank_mask:0xf
	v_add_f32_dpp v226, v226, v226 row_half_mirror row_mask:0xf bank_mask:0xf
	v_add_f32_dpp v220, v220, v220 row_mirror row_mask:0xf bank_mask:0xf
	v_add_f32_dpp v222, v222, v222 row_mirror row_mask:0xf bank_mask:0xf
	v_add_f32_dpp v224, v224, v224 row_mirror row_mask:0xf bank_mask:0xf
	v_add_f32_dpp v226, v226, v226 row_mirror row_mask:0xf bank_mask:0xf
	v_add_f32_dpp v220, v220, v220 row_bcast:15 row_mask:0xa bank_mask:0xf
	v_add_f32_dpp v222, v222, v222 row_bcast:15 row_mask:0xa bank_mask:0xf
	v_add_f32_dpp v224, v224, v224 row_bcast:15 row_mask:0xa bank_mask:0xf
	v_add_f32_dpp v226, v226, v226 row_bcast:15 row_mask:0xa bank_mask:0xf
	v_add_f32_dpp v220, v220, v220 row_bcast:31 row_mask:0xc bank_mask:0xf
	v_add_f32_dpp v222, v222, v222 row_bcast:31 row_mask:0xc bank_mask:0xf
	v_add_f32_dpp v224, v224, v224 row_bcast:31 row_mask:0xc bank_mask:0xf
	v_add_f32_dpp v226, v226, v226 row_bcast:31 row_mask:0xc bank_mask:0xf
	v_fma_f32 v220, v220, s88, v228
	v_fma_f32 v222, v222, s88, v228
	v_fma_f32 v224, v224, s88, v228
	v_fma_f32 v226, v226, s88, v228
	v_rsq_f32_e32 v220, v220
	v_rsq_f32_e32 v222, v222
	v_rsq_f32_e32 v224, v224
	v_rsq_f32_e32 v226, v226
	v_readlane_b32 s16, v220, 63
	v_readlane_b32 s17, v222, 63
	v_readlane_b32 s18, v224, 63
	v_readlane_b32 s19, v226, 63
	v_lshl_add_u64 v[230:231], v[84:85], 0, s[20:21]
	s_add_u32 s20, s20, 0x1000
	s_addc_u32 s21, s21, 0
	v_lshl_add_u64 v[232:233], v[84:85], 0, s[20:21]
	s_add_u32 s20, s20, 0x1000
	s_addc_u32 s21, s21, 0
	v_pk_mul_f32 v[136:137], v[136:137], s[16:17] op_sel_hi:[1,0]
	v_pk_mul_f32 v[138:139], v[138:139], s[16:17] op_sel_hi:[1,0]
	v_pk_mul_f32 v[140:141], v[140:141], s[16:17] op_sel_hi:[1,0]
	v_pk_mul_f32 v[142:143], v[142:143], s[16:17] op_sel_hi:[1,0]
	v_pk_mul_f32 v[144:145], v[144:145], s[16:17] op_sel_hi:[1,0]
	v_pk_mul_f32 v[146:147], v[146:147], s[16:17] op_sel_hi:[1,0]
	v_pk_mul_f32 v[148:149], v[148:149], s[16:17] op_sel_hi:[1,0]
	v_pk_mul_f32 v[150:151], v[150:151], s[16:17] op_sel_hi:[1,0]
	v_pk_mul_f32 v[152:153], v[152:153], s[16:17] op_sel:[0,1] op_sel_hi:[1,1]
	v_pk_mul_f32 v[154:155], v[154:155], s[16:17] op_sel:[0,1] op_sel_hi:[1,1]
	v_pk_mul_f32 v[156:157], v[156:157], s[16:17] op_sel:[0,1] op_sel_hi:[1,1]
	v_pk_mul_f32 v[158:159], v[158:159], s[16:17] op_sel:[0,1] op_sel_hi:[1,1]
	v_pk_mul_f32 v[160:161], v[160:161], s[16:17] op_sel:[0,1] op_sel_hi:[1,1]
	v_pk_mul_f32 v[162:163], v[162:163], s[16:17] op_sel:[0,1] op_sel_hi:[1,1]
	v_pk_mul_f32 v[164:165], v[164:165], s[16:17] op_sel:[0,1] op_sel_hi:[1,1]
	v_pk_mul_f32 v[166:167], v[166:167], s[16:17] op_sel:[0,1] op_sel_hi:[1,1]
	v_pk_mul_f32 v[168:169], v[168:169], s[18:19] op_sel_hi:[1,0]
	v_pk_mul_f32 v[170:171], v[170:171], s[18:19] op_sel_hi:[1,0]
	v_pk_mul_f32 v[184:185], v[184:185], s[18:19] op_sel_hi:[1,0]
	v_pk_mul_f32 v[186:187], v[186:187], s[18:19] op_sel_hi:[1,0]
	v_pk_mul_f32 v[188:189], v[188:189], s[18:19] op_sel_hi:[1,0]
	v_pk_mul_f32 v[190:191], v[190:191], s[18:19] op_sel_hi:[1,0]
	v_pk_mul_f32 v[192:193], v[192:193], s[18:19] op_sel_hi:[1,0]
	v_pk_mul_f32 v[194:195], v[194:195], s[18:19] op_sel_hi:[1,0]
	v_pk_mul_f32 v[196:197], v[196:197], s[18:19] op_sel:[0,1] op_sel_hi:[1,1]
	v_pk_mul_f32 v[198:199], v[198:199], s[18:19] op_sel:[0,1] op_sel_hi:[1,1]
	v_pk_mul_f32 v[200:201], v[200:201], s[18:19] op_sel:[0,1] op_sel_hi:[1,1]
	v_pk_mul_f32 v[202:203], v[202:203], s[18:19] op_sel:[0,1] op_sel_hi:[1,1]
	v_pk_mul_f32 v[212:213], v[212:213], s[18:19] op_sel:[0,1] op_sel_hi:[1,1]
	v_pk_mul_f32 v[214:215], v[214:215], s[18:19] op_sel:[0,1] op_sel_hi:[1,1]
	v_pk_mul_f32 v[216:217], v[216:217], s[18:19] op_sel:[0,1] op_sel_hi:[1,1]
	v_pk_mul_f32 v[218:219], v[218:219], s[18:19] op_sel:[0,1] op_sel_hi:[1,1]
	v_pk_fma_f32 v[136:137], v[64:65], v[136:137], v[116:117]
	v_pk_fma_f32 v[138:139], v[66:67], v[138:139], v[118:119]
	v_pk_fma_f32 v[140:141], v[68:69], v[140:141], v[120:121]
	v_pk_fma_f32 v[142:143], v[70:71], v[142:143], v[122:123]
	v_pk_fma_f32 v[144:145], v[72:73], v[144:145], v[124:125]
	v_pk_fma_f32 v[146:147], v[74:75], v[146:147], v[126:127]
	v_pk_fma_f32 v[148:149], v[76:77], v[148:149], v[128:129]
	v_pk_fma_f32 v[150:151], v[78:79], v[150:151], v[130:131]
	v_pk_fma_f32 v[152:153], v[64:65], v[152:153], v[116:117]
	v_pk_fma_f32 v[154:155], v[66:67], v[154:155], v[118:119]
	v_pk_fma_f32 v[156:157], v[68:69], v[156:157], v[120:121]
	v_pk_fma_f32 v[158:159], v[70:71], v[158:159], v[122:123]
	v_pk_fma_f32 v[160:161], v[72:73], v[160:161], v[124:125]
	v_pk_fma_f32 v[162:163], v[74:75], v[162:163], v[126:127]
	v_pk_fma_f32 v[164:165], v[76:77], v[164:165], v[128:129]
	v_pk_fma_f32 v[166:167], v[78:79], v[166:167], v[130:131]
	v_pk_fma_f32 v[168:169], v[64:65], v[168:169], v[116:117]
	v_pk_fma_f32 v[170:171], v[66:67], v[170:171], v[118:119]
	v_pk_fma_f32 v[184:185], v[68:69], v[184:185], v[120:121]
	v_pk_fma_f32 v[186:187], v[70:71], v[186:187], v[122:123]
	v_pk_fma_f32 v[188:189], v[72:73], v[188:189], v[124:125]
	v_pk_fma_f32 v[190:191], v[74:75], v[190:191], v[126:127]
	v_pk_fma_f32 v[192:193], v[76:77], v[192:193], v[128:129]
	v_pk_fma_f32 v[194:195], v[78:79], v[194:195], v[130:131]
	v_pk_fma_f32 v[196:197], v[64:65], v[196:197], v[116:117]
	v_pk_fma_f32 v[198:199], v[66:67], v[198:199], v[118:119]
	v_pk_fma_f32 v[200:201], v[68:69], v[200:201], v[120:121]
	v_pk_fma_f32 v[202:203], v[70:71], v[202:203], v[122:123]
	v_pk_fma_f32 v[212:213], v[72:73], v[212:213], v[124:125]
	v_pk_fma_f32 v[214:215], v[74:75], v[214:215], v[126:127]
	v_pk_fma_f32 v[216:217], v[76:77], v[216:217], v[128:129]
	v_pk_fma_f32 v[218:219], v[78:79], v[218:219], v[130:131]
	v_cvt_pk_bf16_f32 v136, v136, v137
	v_cvt_pk_bf16_f32 v137, v138, v139
	v_cvt_pk_bf16_f32 v140, v140, v141
	v_cvt_pk_bf16_f32 v141, v142, v143
	v_cvt_pk_bf16_f32 v144, v144, v145
	v_cvt_pk_bf16_f32 v145, v146, v147
	v_cvt_pk_bf16_f32 v148, v148, v149
	v_cvt_pk_bf16_f32 v149, v150, v151
	v_cvt_pk_bf16_f32 v152, v152, v153
	v_cvt_pk_bf16_f32 v153, v154, v155
	v_cvt_pk_bf16_f32 v156, v156, v157
	v_cvt_pk_bf16_f32 v157, v158, v159
	v_cvt_pk_bf16_f32 v160, v160, v161
	v_cvt_pk_bf16_f32 v161, v162, v163
	v_cvt_pk_bf16_f32 v164, v164, v165
	v_cvt_pk_bf16_f32 v165, v166, v167
	v_cvt_pk_bf16_f32 v168, v168, v169
	v_cvt_pk_bf16_f32 v169, v170, v171
	v_cvt_pk_bf16_f32 v184, v184, v185
	v_cvt_pk_bf16_f32 v185, v186, v187
	v_cvt_pk_bf16_f32 v188, v188, v189
	v_cvt_pk_bf16_f32 v189, v190, v191
	v_cvt_pk_bf16_f32 v192, v192, v193
	v_cvt_pk_bf16_f32 v193, v194, v195
	v_cvt_pk_bf16_f32 v196, v196, v197
	v_cvt_pk_bf16_f32 v197, v198, v199
	v_cvt_pk_bf16_f32 v200, v200, v201
	v_cvt_pk_bf16_f32 v201, v202, v203
	v_cvt_pk_bf16_f32 v212, v212, v213
	v_cvt_pk_bf16_f32 v213, v214, v215
	v_cvt_pk_bf16_f32 v216, v216, v217
	v_cvt_pk_bf16_f32 v217, v218, v219
	global_store_dwordx2 v[230:231], v[136:137], off sc1
	global_store_dwordx2 v[230:231], v[140:141], off offset:512 sc1
	global_store_dwordx2 v[230:231], v[144:145], off offset:1024 sc1
	global_store_dwordx2 v[230:231], v[148:149], off offset:1536 sc1
	global_store_dwordx2 v[230:231], v[152:153], off offset:2048 sc1
	global_store_dwordx2 v[230:231], v[156:157], off offset:2560 sc1
	global_store_dwordx2 v[230:231], v[160:161], off offset:3072 sc1
	global_store_dwordx2 v[230:231], v[164:165], off offset:3584 sc1
	global_store_dwordx2 v[232:233], v[168:169], off sc1
	global_store_dwordx2 v[232:233], v[184:185], off offset:512 sc1
	global_store_dwordx2 v[232:233], v[188:189], off offset:1024 sc1
	global_store_dwordx2 v[232:233], v[192:193], off offset:1536 sc1
	global_store_dwordx2 v[232:233], v[196:197], off offset:2048 sc1
	global_store_dwordx2 v[232:233], v[200:201], off offset:2560 sc1
	global_store_dwordx2 v[232:233], v[212:213], off offset:3072 sc1
	global_store_dwordx2 v[232:233], v[216:217], off offset:3584 sc1
	v_lshl_add_u64 v[230:231], s[14:15], 0, v[174:175]
	global_load_dwordx4 v[136:139], v[230:231], off
	global_load_dwordx4 v[140:143], v[230:231], off offset:1024
	global_load_dwordx4 v[144:147], v[230:231], off offset:2048
	global_load_dwordx4 v[148:151], v[230:231], off offset:3072
	s_add_u32 s14, s14, 0x1000
	s_addc_u32 s15, s15, 0
	v_lshl_add_u64 v[232:233], s[14:15], 0, v[174:175]
	global_load_dwordx4 v[152:155], v[232:233], off
	global_load_dwordx4 v[156:159], v[232:233], off offset:1024
	global_load_dwordx4 v[160:163], v[232:233], off offset:2048
	global_load_dwordx4 v[164:167], v[232:233], off offset:3072
	s_add_u32 s14, s14, 0x1000
	s_addc_u32 s15, s15, 0
	v_lshl_add_u64 v[230:231], s[14:15], 0, v[174:175]
	global_load_dwordx4 v[168:171], v[230:231], off
	global_load_dwordx4 v[184:187], v[230:231], off offset:1024
	global_load_dwordx4 v[188:191], v[230:231], off offset:2048
	global_load_dwordx4 v[192:195], v[230:231], off offset:3072
	s_add_u32 s14, s14, 0x1000
	s_addc_u32 s15, s15, 0
	v_lshl_add_u64 v[232:233], s[14:15], 0, v[174:175]
	global_load_dwordx4 v[196:199], v[232:233], off
	global_load_dwordx4 v[200:203], v[232:233], off offset:1024
	global_load_dwordx4 v[212:215], v[232:233], off offset:2048
	global_load_dwordx4 v[216:219], v[232:233], off offset:3072
	s_add_u32 s14, s14, 0x1000
	s_addc_u32 s15, s15, 0
	s_waitcnt vmcnt(32)
	v_pk_mul_f32 v[220:221], v[0:1], v[0:1]
	v_pk_mul_f32 v[222:223], v[16:17], v[16:17]
	v_pk_mul_f32 v[224:225], v[32:33], v[32:33]
	v_pk_mul_f32 v[226:227], v[48:49], v[48:49]
	v_pk_fma_f32 v[220:221], v[2:3], v[2:3], v[220:221]
	v_pk_fma_f32 v[222:223], v[18:19], v[18:19], v[222:223]
	v_pk_fma_f32 v[224:225], v[34:35], v[34:35], v[224:225]
	v_pk_fma_f32 v[226:227], v[50:51], v[50:51], v[226:227]
	v_pk_fma_f32 v[220:221], v[4:5], v[4:5], v[220:221]
	v_pk_fma_f32 v[222:223], v[20:21], v[20:21], v[222:223]
	v_pk_fma_f32 v[224:225], v[36:37], v[36:37], v[224:225]
	v_pk_fma_f32 v[226:227], v[52:53], v[52:53], v[226:227]
	v_pk_fma_f32 v[220:221], v[6:7], v[6:7], v[220:221]
	v_pk_fma_f32 v[222:223], v[22:23], v[22:23], v[222:223]
	v_pk_fma_f32 v[224:225], v[38:39], v[38:39], v[224:225]
	v_pk_fma_f32 v[226:227], v[54:55], v[54:55], v[226:227]
	v_pk_fma_f32 v[220:221], v[8:9], v[8:9], v[220:221]
	v_pk_fma_f32 v[222:223], v[24:25], v[24:25], v[222:223]
	v_pk_fma_f32 v[224:225], v[40:41], v[40:41], v[224:225]
	v_pk_fma_f32 v[226:227], v[56:57], v[56:57], v[226:227]
	v_pk_fma_f32 v[220:221], v[10:11], v[10:11], v[220:221]
	v_pk_fma_f32 v[222:223], v[26:27], v[26:27], v[222:223]
	v_pk_fma_f32 v[224:225], v[42:43], v[42:43], v[224:225]
	v_pk_fma_f32 v[226:227], v[58:59], v[58:59], v[226:227]
	v_pk_fma_f32 v[220:221], v[12:13], v[12:13], v[220:221]
	v_pk_fma_f32 v[222:223], v[28:29], v[28:29], v[222:223]
	v_pk_fma_f32 v[224:225], v[44:45], v[44:45], v[224:225]
	v_pk_fma_f32 v[226:227], v[60:61], v[60:61], v[226:227]
	v_pk_fma_f32 v[220:221], v[14:15], v[14:15], v[220:221]
	v_pk_fma_f32 v[222:223], v[30:31], v[30:31], v[222:223]
	v_pk_fma_f32 v[224:225], v[46:47], v[46:47], v[224:225]
	v_pk_fma_f32 v[226:227], v[62:63], v[62:63], v[226:227]
	v_add_f32_e32 v220, v220, v221
	v_add_f32_e32 v222, v222, v223
	v_add_f32_e32 v224, v224, v225
	v_add_f32_e32 v226, v226, v227
	v_add_f32_dpp v220, v220, v220 quad_perm:[1,0,3,2] row_mask:0xf bank_mask:0xf
	v_add_f32_dpp v222, v222, v222 quad_perm:[1,0,3,2] row_mask:0xf bank_mask:0xf
	v_add_f32_dpp v224, v224, v224 quad_perm:[1,0,3,2] row_mask:0xf bank_mask:0xf
	v_add_f32_dpp v226, v226, v226 quad_perm:[1,0,3,2] row_mask:0xf bank_mask:0xf
	v_add_f32_dpp v220, v220, v220 quad_perm:[2,3,0,1] row_mask:0xf bank_mask:0xf
	v_add_f32_dpp v222, v222, v222 quad_perm:[2,3,0,1] row_mask:0xf bank_mask:0xf
	v_add_f32_dpp v224, v224, v224 quad_perm:[2,3,0,1] row_mask:0xf bank_mask:0xf
	v_add_f32_dpp v226, v226, v226 quad_perm:[2,3,0,1] row_mask:0xf bank_mask:0xf
	v_add_f32_dpp v220, v220, v220 row_half_mirror row_mask:0xf bank_mask:0xf
	v_add_f32_dpp v222, v222, v222 row_half_mirror row_mask:0xf bank_mask:0xf
	v_add_f32_dpp v224, v224, v224 row_half_mirror row_mask:0xf bank_mask:0xf
	v_add_f32_dpp v226, v226, v226 row_half_mirror row_mask:0xf bank_mask:0xf
	v_add_f32_dpp v220, v220, v220 row_mirror row_mask:0xf bank_mask:0xf
	v_add_f32_dpp v222, v222, v222 row_mirror row_mask:0xf bank_mask:0xf
	v_add_f32_dpp v224, v224, v224 row_mirror row_mask:0xf bank_mask:0xf
	v_add_f32_dpp v226, v226, v226 row_mirror row_mask:0xf bank_mask:0xf
	v_add_f32_dpp v220, v220, v220 row_bcast:15 row_mask:0xa bank_mask:0xf
	v_add_f32_dpp v222, v222, v222 row_bcast:15 row_mask:0xa bank_mask:0xf
	v_add_f32_dpp v224, v224, v224 row_bcast:15 row_mask:0xa bank_mask:0xf
	v_add_f32_dpp v226, v226, v226 row_bcast:15 row_mask:0xa bank_mask:0xf
	v_add_f32_dpp v220, v220, v220 row_bcast:31 row_mask:0xc bank_mask:0xf
	v_add_f32_dpp v222, v222, v222 row_bcast:31 row_mask:0xc bank_mask:0xf
	v_add_f32_dpp v224, v224, v224 row_bcast:31 row_mask:0xc bank_mask:0xf
	v_add_f32_dpp v226, v226, v226 row_bcast:31 row_mask:0xc bank_mask:0xf
	v_fma_f32 v220, v220, s88, v228
	v_fma_f32 v222, v222, s88, v228
	v_fma_f32 v224, v224, s88, v228
	v_fma_f32 v226, v226, s88, v228
	v_rsq_f32_e32 v220, v220
	v_rsq_f32_e32 v222, v222
	v_rsq_f32_e32 v224, v224
	v_rsq_f32_e32 v226, v226
	v_readlane_b32 s16, v220, 63
	v_readlane_b32 s17, v222, 63
	v_readlane_b32 s18, v224, 63
	v_readlane_b32 s19, v226, 63
	v_lshl_add_u64 v[230:231], v[84:85], 0, s[20:21]
	s_add_u32 s20, s20, 0x1000
	s_addc_u32 s21, s21, 0
	v_lshl_add_u64 v[232:233], v[84:85], 0, s[20:21]
	s_add_u32 s20, s20, 0x1000
	s_addc_u32 s21, s21, 0
	v_pk_mul_f32 v[0:1], v[0:1], s[16:17] op_sel_hi:[1,0]
	v_pk_mul_f32 v[2:3], v[2:3], s[16:17] op_sel_hi:[1,0]
	v_pk_mul_f32 v[4:5], v[4:5], s[16:17] op_sel_hi:[1,0]
	v_pk_mul_f32 v[6:7], v[6:7], s[16:17] op_sel_hi:[1,0]
	v_pk_mul_f32 v[8:9], v[8:9], s[16:17] op_sel_hi:[1,0]
	v_pk_mul_f32 v[10:11], v[10:11], s[16:17] op_sel_hi:[1,0]
	v_pk_mul_f32 v[12:13], v[12:13], s[16:17] op_sel_hi:[1,0]
	v_pk_mul_f32 v[14:15], v[14:15], s[16:17] op_sel_hi:[1,0]
	v_pk_mul_f32 v[16:17], v[16:17], s[16:17] op_sel:[0,1] op_sel_hi:[1,1]
	v_pk_mul_f32 v[18:19], v[18:19], s[16:17] op_sel:[0,1] op_sel_hi:[1,1]
	v_pk_mul_f32 v[20:21], v[20:21], s[16:17] op_sel:[0,1] op_sel_hi:[1,1]
	v_pk_mul_f32 v[22:23], v[22:23], s[16:17] op_sel:[0,1] op_sel_hi:[1,1]
	v_pk_mul_f32 v[24:25], v[24:25], s[16:17] op_sel:[0,1] op_sel_hi:[1,1]
	v_pk_mul_f32 v[26:27], v[26:27], s[16:17] op_sel:[0,1] op_sel_hi:[1,1]
	v_pk_mul_f32 v[28:29], v[28:29], s[16:17] op_sel:[0,1] op_sel_hi:[1,1]
	v_pk_mul_f32 v[30:31], v[30:31], s[16:17] op_sel:[0,1] op_sel_hi:[1,1]
	v_pk_mul_f32 v[32:33], v[32:33], s[18:19] op_sel_hi:[1,0]
	v_pk_mul_f32 v[34:35], v[34:35], s[18:19] op_sel_hi:[1,0]
	v_pk_mul_f32 v[36:37], v[36:37], s[18:19] op_sel_hi:[1,0]
	v_pk_mul_f32 v[38:39], v[38:39], s[18:19] op_sel_hi:[1,0]
	v_pk_mul_f32 v[40:41], v[40:41], s[18:19] op_sel_hi:[1,0]
	v_pk_mul_f32 v[42:43], v[42:43], s[18:19] op_sel_hi:[1,0]
	v_pk_mul_f32 v[44:45], v[44:45], s[18:19] op_sel_hi:[1,0]
	v_pk_mul_f32 v[46:47], v[46:47], s[18:19] op_sel_hi:[1,0]
	v_pk_mul_f32 v[48:49], v[48:49], s[18:19] op_sel:[0,1] op_sel_hi:[1,1]
	v_pk_mul_f32 v[50:51], v[50:51], s[18:19] op_sel:[0,1] op_sel_hi:[1,1]
	v_pk_mul_f32 v[52:53], v[52:53], s[18:19] op_sel:[0,1] op_sel_hi:[1,1]
	v_pk_mul_f32 v[54:55], v[54:55], s[18:19] op_sel:[0,1] op_sel_hi:[1,1]
	v_pk_mul_f32 v[56:57], v[56:57], s[18:19] op_sel:[0,1] op_sel_hi:[1,1]
	v_pk_mul_f32 v[58:59], v[58:59], s[18:19] op_sel:[0,1] op_sel_hi:[1,1]
	v_pk_mul_f32 v[60:61], v[60:61], s[18:19] op_sel:[0,1] op_sel_hi:[1,1]
	v_pk_mul_f32 v[62:63], v[62:63], s[18:19] op_sel:[0,1] op_sel_hi:[1,1]
	v_pk_fma_f32 v[0:1], v[64:65], v[0:1], v[116:117]
	v_pk_fma_f32 v[2:3], v[66:67], v[2:3], v[118:119]
	v_pk_fma_f32 v[4:5], v[68:69], v[4:5], v[120:121]
	v_pk_fma_f32 v[6:7], v[70:71], v[6:7], v[122:123]
	v_pk_fma_f32 v[8:9], v[72:73], v[8:9], v[124:125]
	v_pk_fma_f32 v[10:11], v[74:75], v[10:11], v[126:127]
	v_pk_fma_f32 v[12:13], v[76:77], v[12:13], v[128:129]
	v_pk_fma_f32 v[14:15], v[78:79], v[14:15], v[130:131]
	v_pk_fma_f32 v[16:17], v[64:65], v[16:17], v[116:117]
	v_pk_fma_f32 v[18:19], v[66:67], v[18:19], v[118:119]
	v_pk_fma_f32 v[20:21], v[68:69], v[20:21], v[120:121]
	v_pk_fma_f32 v[22:23], v[70:71], v[22:23], v[122:123]
	v_pk_fma_f32 v[24:25], v[72:73], v[24:25], v[124:125]
	v_pk_fma_f32 v[26:27], v[74:75], v[26:27], v[126:127]
	v_pk_fma_f32 v[28:29], v[76:77], v[28:29], v[128:129]
	v_pk_fma_f32 v[30:31], v[78:79], v[30:31], v[130:131]
	v_pk_fma_f32 v[32:33], v[64:65], v[32:33], v[116:117]
	v_pk_fma_f32 v[34:35], v[66:67], v[34:35], v[118:119]
	v_pk_fma_f32 v[36:37], v[68:69], v[36:37], v[120:121]
	v_pk_fma_f32 v[38:39], v[70:71], v[38:39], v[122:123]
	v_pk_fma_f32 v[40:41], v[72:73], v[40:41], v[124:125]
	v_pk_fma_f32 v[42:43], v[74:75], v[42:43], v[126:127]
	v_pk_fma_f32 v[44:45], v[76:77], v[44:45], v[128:129]
	v_pk_fma_f32 v[46:47], v[78:79], v[46:47], v[130:131]
	v_pk_fma_f32 v[48:49], v[64:65], v[48:49], v[116:117]
	v_pk_fma_f32 v[50:51], v[66:67], v[50:51], v[118:119]
	v_pk_fma_f32 v[52:53], v[68:69], v[52:53], v[120:121]
	v_pk_fma_f32 v[54:55], v[70:71], v[54:55], v[122:123]
	v_pk_fma_f32 v[56:57], v[72:73], v[56:57], v[124:125]
	v_pk_fma_f32 v[58:59], v[74:75], v[58:59], v[126:127]
	v_pk_fma_f32 v[60:61], v[76:77], v[60:61], v[128:129]
	v_pk_fma_f32 v[62:63], v[78:79], v[62:63], v[130:131]
	v_cvt_pk_bf16_f32 v0, v0, v1
	v_cvt_pk_bf16_f32 v1, v2, v3
	v_cvt_pk_bf16_f32 v4, v4, v5
	v_cvt_pk_bf16_f32 v5, v6, v7
	v_cvt_pk_bf16_f32 v8, v8, v9
	v_cvt_pk_bf16_f32 v9, v10, v11
	v_cvt_pk_bf16_f32 v12, v12, v13
	v_cvt_pk_bf16_f32 v13, v14, v15
	v_cvt_pk_bf16_f32 v16, v16, v17
	v_cvt_pk_bf16_f32 v17, v18, v19
	v_cvt_pk_bf16_f32 v20, v20, v21
	v_cvt_pk_bf16_f32 v21, v22, v23
	v_cvt_pk_bf16_f32 v24, v24, v25
	v_cvt_pk_bf16_f32 v25, v26, v27
	v_cvt_pk_bf16_f32 v28, v28, v29
	v_cvt_pk_bf16_f32 v29, v30, v31
	v_cvt_pk_bf16_f32 v32, v32, v33
	v_cvt_pk_bf16_f32 v33, v34, v35
	v_cvt_pk_bf16_f32 v36, v36, v37
	v_cvt_pk_bf16_f32 v37, v38, v39
	v_cvt_pk_bf16_f32 v40, v40, v41
	v_cvt_pk_bf16_f32 v41, v42, v43
	v_cvt_pk_bf16_f32 v44, v44, v45
	v_cvt_pk_bf16_f32 v45, v46, v47
	v_cvt_pk_bf16_f32 v48, v48, v49
	v_cvt_pk_bf16_f32 v49, v50, v51
	v_cvt_pk_bf16_f32 v52, v52, v53
	v_cvt_pk_bf16_f32 v53, v54, v55
	v_cvt_pk_bf16_f32 v56, v56, v57
	v_cvt_pk_bf16_f32 v57, v58, v59
	v_cvt_pk_bf16_f32 v60, v60, v61
	v_cvt_pk_bf16_f32 v61, v62, v63
	global_store_dwordx2 v[230:231], v[0:1], off sc1
	global_store_dwordx2 v[230:231], v[4:5], off offset:512 sc1
	global_store_dwordx2 v[230:231], v[8:9], off offset:1024 sc1
	global_store_dwordx2 v[230:231], v[12:13], off offset:1536 sc1
	global_store_dwordx2 v[230:231], v[16:17], off offset:2048 sc1
	global_store_dwordx2 v[230:231], v[20:21], off offset:2560 sc1
	global_store_dwordx2 v[230:231], v[24:25], off offset:3072 sc1
	global_store_dwordx2 v[230:231], v[28:29], off offset:3584 sc1
	global_store_dwordx2 v[232:233], v[32:33], off sc1
	global_store_dwordx2 v[232:233], v[36:37], off offset:512 sc1
	global_store_dwordx2 v[232:233], v[40:41], off offset:1024 sc1
	global_store_dwordx2 v[232:233], v[44:45], off offset:1536 sc1
	global_store_dwordx2 v[232:233], v[48:49], off offset:2048 sc1
	global_store_dwordx2 v[232:233], v[52:53], off offset:2560 sc1
	global_store_dwordx2 v[232:233], v[56:57], off offset:3072 sc1
	global_store_dwordx2 v[232:233], v[60:61], off offset:3584 sc1
	s_waitcnt vmcnt(16)
	v_pk_mul_f32 v[220:221], v[136:137], v[136:137]
	v_pk_mul_f32 v[222:223], v[152:153], v[152:153]
	v_pk_mul_f32 v[224:225], v[168:169], v[168:169]
	v_pk_mul_f32 v[226:227], v[196:197], v[196:197]
	v_pk_fma_f32 v[220:221], v[138:139], v[138:139], v[220:221]
	v_pk_fma_f32 v[222:223], v[154:155], v[154:155], v[222:223]
	v_pk_fma_f32 v[224:225], v[170:171], v[170:171], v[224:225]
	v_pk_fma_f32 v[226:227], v[198:199], v[198:199], v[226:227]
	v_pk_fma_f32 v[220:221], v[140:141], v[140:141], v[220:221]
	v_pk_fma_f32 v[222:223], v[156:157], v[156:157], v[222:223]
	v_pk_fma_f32 v[224:225], v[184:185], v[184:185], v[224:225]
	v_pk_fma_f32 v[226:227], v[200:201], v[200:201], v[226:227]
	v_pk_fma_f32 v[220:221], v[142:143], v[142:143], v[220:221]
	v_pk_fma_f32 v[222:223], v[158:159], v[158:159], v[222:223]
	v_pk_fma_f32 v[224:225], v[186:187], v[186:187], v[224:225]
	v_pk_fma_f32 v[226:227], v[202:203], v[202:203], v[226:227]
	v_pk_fma_f32 v[220:221], v[144:145], v[144:145], v[220:221]
	v_pk_fma_f32 v[222:223], v[160:161], v[160:161], v[222:223]
	v_pk_fma_f32 v[224:225], v[188:189], v[188:189], v[224:225]
	v_pk_fma_f32 v[226:227], v[212:213], v[212:213], v[226:227]
	v_pk_fma_f32 v[220:221], v[146:147], v[146:147], v[220:221]
	v_pk_fma_f32 v[222:223], v[162:163], v[162:163], v[222:223]
	v_pk_fma_f32 v[224:225], v[190:191], v[190:191], v[224:225]
	v_pk_fma_f32 v[226:227], v[214:215], v[214:215], v[226:227]
	v_pk_fma_f32 v[220:221], v[148:149], v[148:149], v[220:221]
	v_pk_fma_f32 v[222:223], v[164:165], v[164:165], v[222:223]
	v_pk_fma_f32 v[224:225], v[192:193], v[192:193], v[224:225]
	v_pk_fma_f32 v[226:227], v[216:217], v[216:217], v[226:227]
	v_pk_fma_f32 v[220:221], v[150:151], v[150:151], v[220:221]
	v_pk_fma_f32 v[222:223], v[166:167], v[166:167], v[222:223]
	v_pk_fma_f32 v[224:225], v[194:195], v[194:195], v[224:225]
	v_pk_fma_f32 v[226:227], v[218:219], v[218:219], v[226:227]
	v_add_f32_e32 v220, v220, v221
	v_add_f32_e32 v222, v222, v223
	v_add_f32_e32 v224, v224, v225
	v_add_f32_e32 v226, v226, v227
	v_add_f32_dpp v220, v220, v220 quad_perm:[1,0,3,2] row_mask:0xf bank_mask:0xf
	v_add_f32_dpp v222, v222, v222 quad_perm:[1,0,3,2] row_mask:0xf bank_mask:0xf
	v_add_f32_dpp v224, v224, v224 quad_perm:[1,0,3,2] row_mask:0xf bank_mask:0xf
	v_add_f32_dpp v226, v226, v226 quad_perm:[1,0,3,2] row_mask:0xf bank_mask:0xf
	v_add_f32_dpp v220, v220, v220 quad_perm:[2,3,0,1] row_mask:0xf bank_mask:0xf
	v_add_f32_dpp v222, v222, v222 quad_perm:[2,3,0,1] row_mask:0xf bank_mask:0xf
	v_add_f32_dpp v224, v224, v224 quad_perm:[2,3,0,1] row_mask:0xf bank_mask:0xf
	v_add_f32_dpp v226, v226, v226 quad_perm:[2,3,0,1] row_mask:0xf bank_mask:0xf
	v_add_f32_dpp v220, v220, v220 row_half_mirror row_mask:0xf bank_mask:0xf
	v_add_f32_dpp v222, v222, v222 row_half_mirror row_mask:0xf bank_mask:0xf
	v_add_f32_dpp v224, v224, v224 row_half_mirror row_mask:0xf bank_mask:0xf
	v_add_f32_dpp v226, v226, v226 row_half_mirror row_mask:0xf bank_mask:0xf
	v_add_f32_dpp v220, v220, v220 row_mirror row_mask:0xf bank_mask:0xf
	v_add_f32_dpp v222, v222, v222 row_mirror row_mask:0xf bank_mask:0xf
	v_add_f32_dpp v224, v224, v224 row_mirror row_mask:0xf bank_mask:0xf
	v_add_f32_dpp v226, v226, v226 row_mirror row_mask:0xf bank_mask:0xf
	v_add_f32_dpp v220, v220, v220 row_bcast:15 row_mask:0xa bank_mask:0xf
	v_add_f32_dpp v222, v222, v222 row_bcast:15 row_mask:0xa bank_mask:0xf
	v_add_f32_dpp v224, v224, v224 row_bcast:15 row_mask:0xa bank_mask:0xf
	v_add_f32_dpp v226, v226, v226 row_bcast:15 row_mask:0xa bank_mask:0xf
	v_add_f32_dpp v220, v220, v220 row_bcast:31 row_mask:0xc bank_mask:0xf
	v_add_f32_dpp v222, v222, v222 row_bcast:31 row_mask:0xc bank_mask:0xf
	v_add_f32_dpp v224, v224, v224 row_bcast:31 row_mask:0xc bank_mask:0xf
	v_add_f32_dpp v226, v226, v226 row_bcast:31 row_mask:0xc bank_mask:0xf
	v_fma_f32 v220, v220, s88, v228
	v_fma_f32 v222, v222, s88, v228
	v_fma_f32 v224, v224, s88, v228
	v_fma_f32 v226, v226, s88, v228
	v_rsq_f32_e32 v220, v220
	v_rsq_f32_e32 v222, v222
	v_rsq_f32_e32 v224, v224
	v_rsq_f32_e32 v226, v226
	v_readlane_b32 s16, v220, 63
	v_readlane_b32 s17, v222, 63
	v_readlane_b32 s18, v224, 63
	v_readlane_b32 s19, v226, 63
	v_lshl_add_u64 v[230:231], v[84:85], 0, s[20:21]
	s_add_u32 s20, s20, 0x1000
	s_addc_u32 s21, s21, 0
	v_lshl_add_u64 v[232:233], v[84:85], 0, s[20:21]
	s_add_u32 s20, s20, 0x1000
	s_addc_u32 s21, s21, 0
	v_pk_mul_f32 v[136:137], v[136:137], s[16:17] op_sel_hi:[1,0]
	v_pk_mul_f32 v[138:139], v[138:139], s[16:17] op_sel_hi:[1,0]
	v_pk_mul_f32 v[140:141], v[140:141], s[16:17] op_sel_hi:[1,0]
	v_pk_mul_f32 v[142:143], v[142:143], s[16:17] op_sel_hi:[1,0]
	v_pk_mul_f32 v[144:145], v[144:145], s[16:17] op_sel_hi:[1,0]
	v_pk_mul_f32 v[146:147], v[146:147], s[16:17] op_sel_hi:[1,0]
	v_pk_mul_f32 v[148:149], v[148:149], s[16:17] op_sel_hi:[1,0]
	v_pk_mul_f32 v[150:151], v[150:151], s[16:17] op_sel_hi:[1,0]
	v_pk_mul_f32 v[152:153], v[152:153], s[16:17] op_sel:[0,1] op_sel_hi:[1,1]
	v_pk_mul_f32 v[154:155], v[154:155], s[16:17] op_sel:[0,1] op_sel_hi:[1,1]
	v_pk_mul_f32 v[156:157], v[156:157], s[16:17] op_sel:[0,1] op_sel_hi:[1,1]
	v_pk_mul_f32 v[158:159], v[158:159], s[16:17] op_sel:[0,1] op_sel_hi:[1,1]
	v_pk_mul_f32 v[160:161], v[160:161], s[16:17] op_sel:[0,1] op_sel_hi:[1,1]
	v_pk_mul_f32 v[162:163], v[162:163], s[16:17] op_sel:[0,1] op_sel_hi:[1,1]
	v_pk_mul_f32 v[164:165], v[164:165], s[16:17] op_sel:[0,1] op_sel_hi:[1,1]
	v_pk_mul_f32 v[166:167], v[166:167], s[16:17] op_sel:[0,1] op_sel_hi:[1,1]
	v_pk_mul_f32 v[168:169], v[168:169], s[18:19] op_sel_hi:[1,0]
	v_pk_mul_f32 v[170:171], v[170:171], s[18:19] op_sel_hi:[1,0]
	v_pk_mul_f32 v[184:185], v[184:185], s[18:19] op_sel_hi:[1,0]
	v_pk_mul_f32 v[186:187], v[186:187], s[18:19] op_sel_hi:[1,0]
	v_pk_mul_f32 v[188:189], v[188:189], s[18:19] op_sel_hi:[1,0]
	v_pk_mul_f32 v[190:191], v[190:191], s[18:19] op_sel_hi:[1,0]
	v_pk_mul_f32 v[192:193], v[192:193], s[18:19] op_sel_hi:[1,0]
	v_pk_mul_f32 v[194:195], v[194:195], s[18:19] op_sel_hi:[1,0]
	v_pk_mul_f32 v[196:197], v[196:197], s[18:19] op_sel:[0,1] op_sel_hi:[1,1]
	v_pk_mul_f32 v[198:199], v[198:199], s[18:19] op_sel:[0,1] op_sel_hi:[1,1]
	v_pk_mul_f32 v[200:201], v[200:201], s[18:19] op_sel:[0,1] op_sel_hi:[1,1]
	v_pk_mul_f32 v[202:203], v[202:203], s[18:19] op_sel:[0,1] op_sel_hi:[1,1]
	v_pk_mul_f32 v[212:213], v[212:213], s[18:19] op_sel:[0,1] op_sel_hi:[1,1]
	v_pk_mul_f32 v[214:215], v[214:215], s[18:19] op_sel:[0,1] op_sel_hi:[1,1]
	v_pk_mul_f32 v[216:217], v[216:217], s[18:19] op_sel:[0,1] op_sel_hi:[1,1]
	v_pk_mul_f32 v[218:219], v[218:219], s[18:19] op_sel:[0,1] op_sel_hi:[1,1]
	v_pk_fma_f32 v[136:137], v[64:65], v[136:137], v[116:117]
	v_pk_fma_f32 v[138:139], v[66:67], v[138:139], v[118:119]
	v_pk_fma_f32 v[140:141], v[68:69], v[140:141], v[120:121]
	v_pk_fma_f32 v[142:143], v[70:71], v[142:143], v[122:123]
	v_pk_fma_f32 v[144:145], v[72:73], v[144:145], v[124:125]
	v_pk_fma_f32 v[146:147], v[74:75], v[146:147], v[126:127]
	v_pk_fma_f32 v[148:149], v[76:77], v[148:149], v[128:129]
	v_pk_fma_f32 v[150:151], v[78:79], v[150:151], v[130:131]
	v_pk_fma_f32 v[152:153], v[64:65], v[152:153], v[116:117]
	v_pk_fma_f32 v[154:155], v[66:67], v[154:155], v[118:119]
	v_pk_fma_f32 v[156:157], v[68:69], v[156:157], v[120:121]
	v_pk_fma_f32 v[158:159], v[70:71], v[158:159], v[122:123]
	v_pk_fma_f32 v[160:161], v[72:73], v[160:161], v[124:125]
	v_pk_fma_f32 v[162:163], v[74:75], v[162:163], v[126:127]
	v_pk_fma_f32 v[164:165], v[76:77], v[164:165], v[128:129]
	v_pk_fma_f32 v[166:167], v[78:79], v[166:167], v[130:131]
	v_pk_fma_f32 v[168:169], v[64:65], v[168:169], v[116:117]
	v_pk_fma_f32 v[170:171], v[66:67], v[170:171], v[118:119]
	v_pk_fma_f32 v[184:185], v[68:69], v[184:185], v[120:121]
	v_pk_fma_f32 v[186:187], v[70:71], v[186:187], v[122:123]
	v_pk_fma_f32 v[188:189], v[72:73], v[188:189], v[124:125]
	v_pk_fma_f32 v[190:191], v[74:75], v[190:191], v[126:127]
	v_pk_fma_f32 v[192:193], v[76:77], v[192:193], v[128:129]
	v_pk_fma_f32 v[194:195], v[78:79], v[194:195], v[130:131]
	v_pk_fma_f32 v[196:197], v[64:65], v[196:197], v[116:117]
	v_pk_fma_f32 v[198:199], v[66:67], v[198:199], v[118:119]
	v_pk_fma_f32 v[200:201], v[68:69], v[200:201], v[120:121]
	v_pk_fma_f32 v[202:203], v[70:71], v[202:203], v[122:123]
	v_pk_fma_f32 v[212:213], v[72:73], v[212:213], v[124:125]
	v_pk_fma_f32 v[214:215], v[74:75], v[214:215], v[126:127]
	v_pk_fma_f32 v[216:217], v[76:77], v[216:217], v[128:129]
	v_pk_fma_f32 v[218:219], v[78:79], v[218:219], v[130:131]
	v_cvt_pk_bf16_f32 v136, v136, v137
	v_cvt_pk_bf16_f32 v137, v138, v139
	v_cvt_pk_bf16_f32 v140, v140, v141
	v_cvt_pk_bf16_f32 v141, v142, v143
	v_cvt_pk_bf16_f32 v144, v144, v145
	v_cvt_pk_bf16_f32 v145, v146, v147
	v_cvt_pk_bf16_f32 v148, v148, v149
	v_cvt_pk_bf16_f32 v149, v150, v151
	v_cvt_pk_bf16_f32 v152, v152, v153
	v_cvt_pk_bf16_f32 v153, v154, v155
	v_cvt_pk_bf16_f32 v156, v156, v157
	v_cvt_pk_bf16_f32 v157, v158, v159
	v_cvt_pk_bf16_f32 v160, v160, v161
	v_cvt_pk_bf16_f32 v161, v162, v163
	v_cvt_pk_bf16_f32 v164, v164, v165
	v_cvt_pk_bf16_f32 v165, v166, v167
	v_cvt_pk_bf16_f32 v168, v168, v169
	v_cvt_pk_bf16_f32 v169, v170, v171
	v_cvt_pk_bf16_f32 v184, v184, v185
	v_cvt_pk_bf16_f32 v185, v186, v187
	v_cvt_pk_bf16_f32 v188, v188, v189
	v_cvt_pk_bf16_f32 v189, v190, v191
	v_cvt_pk_bf16_f32 v192, v192, v193
	v_cvt_pk_bf16_f32 v193, v194, v195
	v_cvt_pk_bf16_f32 v196, v196, v197
	v_cvt_pk_bf16_f32 v197, v198, v199
	v_cvt_pk_bf16_f32 v200, v200, v201
	v_cvt_pk_bf16_f32 v201, v202, v203
	v_cvt_pk_bf16_f32 v212, v212, v213
	v_cvt_pk_bf16_f32 v213, v214, v215
	v_cvt_pk_bf16_f32 v216, v216, v217
	v_cvt_pk_bf16_f32 v217, v218, v219
	global_store_dwordx2 v[230:231], v[136:137], off sc1
	global_store_dwordx2 v[230:231], v[140:141], off offset:512 sc1
	global_store_dwordx2 v[230:231], v[144:145], off offset:1024 sc1
	global_store_dwordx2 v[230:231], v[148:149], off offset:1536 sc1
	global_store_dwordx2 v[230:231], v[152:153], off offset:2048 sc1
	global_store_dwordx2 v[230:231], v[156:157], off offset:2560 sc1
	global_store_dwordx2 v[230:231], v[160:161], off offset:3072 sc1
	global_store_dwordx2 v[230:231], v[164:165], off offset:3584 sc1
	global_store_dwordx2 v[232:233], v[168:169], off sc1
	global_store_dwordx2 v[232:233], v[184:185], off offset:512 sc1
	global_store_dwordx2 v[232:233], v[188:189], off offset:1024 sc1
	global_store_dwordx2 v[232:233], v[192:193], off offset:1536 sc1
	global_store_dwordx2 v[232:233], v[196:197], off offset:2048 sc1
	global_store_dwordx2 v[232:233], v[200:201], off offset:2560 sc1
	global_store_dwordx2 v[232:233], v[212:213], off offset:3072 sc1
	global_store_dwordx2 v[232:233], v[216:217], off offset:3584 sc1
	s_mov_b32 s22, 0x8000
	s_mov_b32 s23, 0
	s_add_i32 s24, s24, s58
	s_add_i32 s6, s6, s27
	s_add_i32 s8, s8, s27
	s_add_i32 s10, s10, s27
	s_add_i32 s12, s12, s27
	s_cmpk_gt_i32 s24, 0x7ff
	s_cbranch_scc0 .LBB0_533

.LBB0_541:
	v_lshl_add_u64 v[32:33], s[12:13], 0, v[174:175]
	global_load_dwordx4 v[92:95], v[32:33], off
	global_load_dwordx4 v[88:91], v[32:33], off offset:1024
	global_load_dwordx4 v[84:87], v[32:33], off offset:2048
	global_load_dwordx4 v[80:83], v[32:33], off offset:3072
	v_lshl_add_u64 v[32:33], s[16:17], 0, v[174:175]
	global_load_dwordx4 v[76:79], v[32:33], off
	global_load_dwordx4 v[72:75], v[32:33], off offset:1024
	global_load_dwordx4 v[68:71], v[32:33], off offset:2048
	global_load_dwordx4 v[64:67], v[32:33], off offset:3072
	v_lshl_add_u64 v[32:33], s[18:19], 0, v[174:175]
	global_load_dwordx4 v[60:63], v[32:33], off
	global_load_dwordx4 v[56:59], v[32:33], off offset:1024
	global_load_dwordx4 v[52:55], v[32:33], off offset:2048
	global_load_dwordx4 v[48:51], v[32:33], off offset:3072
	v_lshl_add_u64 v[32:33], s[14:15], 0, v[174:175]
	global_load_dwordx4 v[44:47], v[32:33], off
	global_load_dwordx4 v[40:43], v[32:33], off offset:1024
	global_load_dwordx4 v[36:39], v[32:33], off offset:2048
	s_nop 0
	global_load_dwordx4 v[32:35], v[32:33], off offset:3072
	s_waitcnt vmcnt(15)
	v_pk_mul_f32 v[170:171], v[94:95], v[94:95]
	v_pk_mul_f32 v[182:183], v[92:93], v[92:93]
	s_waitcnt vmcnt(12)
	v_mul_f32_e32 v160, v80, v80
	v_pk_mov_b32 v[184:185], v[182:183], v[170:171] op_sel:[1,0]
	v_mov_b32_e32 v183, v171
	v_pk_add_f32 v[170:171], v[184:185], v[182:183]
	v_pk_mul_f32 v[182:183], v[90:91], v[90:91]
	v_pk_mul_f32 v[184:185], v[88:89], v[88:89]
	v_mul_f32_e32 v162, v81, v81
	v_pk_mov_b32 v[186:187], v[184:185], v[182:183] op_sel:[1,0]
	v_mov_b32_e32 v185, v183
	v_pk_add_f32 v[182:183], v[186:187], v[184:185]
	v_pk_add_f32 v[170:171], v[170:171], v[170:171] op_sel:[0,1] op_sel_hi:[1,0]
	v_pk_add_f32 v[182:183], v[182:183], v[182:183] op_sel:[0,1] op_sel_hi:[1,0]
	v_mov_b32_e32 v171, v160
	v_mov_b32_e32 v183, v162
	v_mul_f32_e32 v160, v85, v85
	v_pk_add_f32 v[170:171], v[170:171], v[182:183]
	v_pk_fma_f32 v[182:183], v[84:85], v[84:85], v[160:161] op_sel_hi:[1,1,0]
	v_mul_f32_e32 v160, v87, v87
	v_mul_f32_e32 v164, v82, v82
	v_mul_f32_e32 v166, v83, v83
	v_pk_fma_f32 v[184:185], v[86:87], v[86:87], v[160:161] op_sel_hi:[1,1,0]
	v_mov_b32_e32 v183, v164
	v_mov_b32_e32 v185, v166
	v_pk_add_f32 v[182:183], v[182:183], v[184:185]
	s_waitcnt vmcnt(11)
	v_pk_mul_f32 v[184:185], v[76:77], v[76:77]
	v_pk_add_f32 v[170:171], v[170:171], v[182:183]
	v_pk_mul_f32 v[182:183], v[78:79], v[78:79]
	s_waitcnt vmcnt(8)
	v_mul_f32_e32 v160, v64, v64
	v_pk_mov_b32 v[186:187], v[184:185], v[182:183] op_sel:[1,0]
	v_mov_b32_e32 v185, v183
	v_pk_add_f32 v[182:183], v[186:187], v[184:185]
	v_pk_mul_f32 v[184:185], v[74:75], v[74:75]
	v_pk_mul_f32 v[186:187], v[72:73], v[72:73]
	v_mul_f32_e32 v162, v65, v65
	v_pk_mov_b32 v[188:189], v[186:187], v[184:185] op_sel:[1,0]
	v_mov_b32_e32 v187, v185
	v_pk_add_f32 v[184:185], v[188:189], v[186:187]
	v_pk_add_f32 v[182:183], v[182:183], v[182:183] op_sel:[0,1] op_sel_hi:[1,0]
	v_pk_add_f32 v[184:185], v[184:185], v[184:185] op_sel:[0,1] op_sel_hi:[1,0]
	v_mov_b32_e32 v183, v160
	v_mov_b32_e32 v185, v162
	v_mul_f32_e32 v160, v69, v69
	v_pk_add_f32 v[182:183], v[182:183], v[184:185]
	v_pk_fma_f32 v[184:185], v[68:69], v[68:69], v[160:161] op_sel_hi:[1,1,0]
	v_mul_f32_e32 v160, v71, v71
	v_mul_f32_e32 v164, v66, v66
	v_mul_f32_e32 v166, v67, v67
	v_pk_fma_f32 v[186:187], v[70:71], v[70:71], v[160:161] op_sel_hi:[1,1,0]
	v_mov_b32_e32 v185, v164
	v_mov_b32_e32 v187, v166
	v_pk_add_f32 v[184:185], v[184:185], v[186:187]
	s_nop 0
	v_pk_add_f32 v[182:183], v[182:183], v[184:185]
	v_mov_b32_e32 v185, v170
	v_mov_b32_e32 v184, v182
	v_mov_b32_e32 v170, v183
	v_pk_add_f32 v[170:171], v[184:185], v[170:171]
	ds_bpermute_b32 v183, v161, v171
	ds_bpermute_b32 v182, v161, v170
	s_waitcnt vmcnt(7)
	v_pk_mul_f32 v[184:185], v[60:61], v[60:61]
	s_waitcnt lgkmcnt(0)
	v_pk_add_f32 v[170:171], v[170:171], v[182:183]
	ds_bpermute_b32 v183, v163, v171
	ds_bpermute_b32 v182, v163, v170
	s_waitcnt lgkmcnt(0)
	v_pk_add_f32 v[170:171], v[170:171], v[182:183]
	ds_bpermute_b32 v183, v165, v171
	ds_bpermute_b32 v182, v165, v170
	s_waitcnt lgkmcnt(0)
	v_pk_add_f32 v[170:171], v[170:171], v[182:183]
	ds_bpermute_b32 v183, v167, v171
	ds_bpermute_b32 v182, v167, v170
	s_waitcnt lgkmcnt(0)
	v_pk_add_f32 v[170:171], v[170:171], v[182:183]
	ds_bpermute_b32 v183, v168, v171
	ds_bpermute_b32 v182, v168, v170
	s_waitcnt lgkmcnt(0)
	v_pk_add_f32 v[170:171], v[170:171], v[182:183]
	ds_bpermute_b32 v183, v169, v171
	ds_bpermute_b32 v182, v169, v170
	s_waitcnt lgkmcnt(0)
	v_pk_add_f32 v[170:171], v[170:171], v[182:183]
	v_mov_b64_e32 v[182:183], s[70:71]
	v_pk_fma_f32 v[170:171], v[170:171], s[88:89], v[182:183] op_sel_hi:[1,0,0]
	s_nop 0
	v_mul_f32_e32 v160, 0x4b800000, v171
	v_cmp_gt_f32_e64 s[0:1], s91, v171
	v_cmp_gt_f32_e32 vcc, s91, v170
	s_nop 0
	v_cndmask_b32_e64 v160, v171, v160, s[0:1]
	v_rsq_f32_e32 v160, v160
	s_nop 0
	v_mul_f32_e32 v162, 0x45800000, v160
	v_cndmask_b32_e64 v166, v160, v162, s[0:1]
	v_mul_f32_e32 v160, 0x4b800000, v170
	v_cndmask_b32_e32 v160, v170, v160, vcc
	v_rsq_f32_e32 v160, v160
	v_pk_mul_f32 v[170:171], v[62:63], v[62:63]
	v_pk_mul_f32 v[92:93], v[92:93], v[166:167] op_sel_hi:[1,0]
	v_pk_mov_b32 v[186:187], v[184:185], v[170:171] op_sel:[1,0]
	v_mov_b32_e32 v185, v171
	v_pk_add_f32 v[170:171], v[186:187], v[184:185]
	s_waitcnt vmcnt(6)
	v_pk_mul_f32 v[184:185], v[58:59], v[58:59]
	v_pk_mul_f32 v[186:187], v[56:57], v[56:57]
	v_mul_f32_e32 v162, 0x45800000, v160
	v_pk_mov_b32 v[188:189], v[186:187], v[184:185] op_sel:[1,0]
	v_mov_b32_e32 v187, v185
	v_pk_add_f32 v[184:185], v[188:189], v[186:187]
	v_cndmask_b32_e32 v164, v160, v162, vcc
	s_waitcnt vmcnt(4)
	v_mul_f32_e32 v160, v48, v48
	v_mul_f32_e32 v162, v49, v49
	v_pk_add_f32 v[170:171], v[170:171], v[170:171] op_sel:[0,1] op_sel_hi:[1,0]
	v_pk_add_f32 v[184:185], v[184:185], v[184:185] op_sel:[0,1] op_sel_hi:[1,0]
	v_mov_b32_e32 v171, v160
	v_mov_b32_e32 v185, v162
	v_mul_f32_e32 v160, v53, v53
	v_mul_f32_e32 v186, v50, v50
	v_pk_add_f32 v[170:171], v[170:171], v[184:185]
	v_pk_fma_f32 v[184:185], v[52:53], v[52:53], v[160:161] op_sel_hi:[1,1,0]
	v_mul_f32_e32 v160, v55, v55
	v_mul_f32_e32 v188, v51, v51
	v_mov_b32_e32 v185, v186
	v_pk_fma_f32 v[186:187], v[54:55], v[54:55], v[160:161] op_sel_hi:[1,1,0]
	s_waitcnt vmcnt(0)
	v_mul_f32_e32 v160, v32, v32
	v_mov_b32_e32 v187, v188
	v_pk_add_f32 v[184:185], v[184:185], v[186:187]
	v_pk_mul_f32 v[186:187], v[44:45], v[44:45]
	v_pk_add_f32 v[170:171], v[170:171], v[184:185]
	v_pk_mul_f32 v[184:185], v[46:47], v[46:47]
	v_mul_f32_e32 v162, v33, v33
	v_pk_mov_b32 v[188:189], v[186:187], v[184:185] op_sel:[1,0]
	v_mov_b32_e32 v187, v185
	v_pk_add_f32 v[184:185], v[188:189], v[186:187]
	v_pk_mul_f32 v[186:187], v[42:43], v[42:43]
	v_pk_mul_f32 v[188:189], v[40:41], v[40:41]
	v_pk_add_f32 v[184:185], v[184:185], v[184:185] op_sel:[0,1] op_sel_hi:[1,0]
	v_pk_mov_b32 v[190:191], v[188:189], v[186:187] op_sel:[1,0]
	v_mov_b32_e32 v189, v187
	v_pk_add_f32 v[186:187], v[190:191], v[188:189]
	v_mov_b32_e32 v185, v160
	v_pk_add_f32 v[186:187], v[186:187], v[186:187] op_sel:[0,1] op_sel_hi:[1,0]
	v_mul_f32_e32 v160, v37, v37
	v_mov_b32_e32 v187, v162
	v_mul_f32_e32 v188, v34, v34
	v_pk_add_f32 v[184:185], v[184:185], v[186:187]
	v_pk_fma_f32 v[186:187], v[36:37], v[36:37], v[160:161] op_sel_hi:[1,1,0]
	v_mul_f32_e32 v160, v39, v39
	v_mul_f32_e32 v190, v35, v35
	v_mov_b32_e32 v187, v188
	v_pk_fma_f32 v[188:189], v[38:39], v[38:39], v[160:161] op_sel_hi:[1,1,0]
	v_pk_mul_f32 v[94:95], v[94:95], v[166:167] op_sel_hi:[1,0]
	v_mov_b32_e32 v189, v190
	v_pk_add_f32 v[186:187], v[186:187], v[188:189]
	v_pk_mul_f32 v[88:89], v[88:89], v[166:167] op_sel_hi:[1,0]
	v_pk_add_f32 v[184:185], v[184:185], v[186:187]
	v_mov_b32_e32 v187, v170
	v_mov_b32_e32 v186, v184
	v_mov_b32_e32 v170, v185
	v_pk_add_f32 v[170:171], v[186:187], v[170:171]
	ds_bpermute_b32 v185, v161, v171
	ds_bpermute_b32 v184, v161, v170
	v_pk_mul_f32 v[90:91], v[90:91], v[166:167] op_sel_hi:[1,0]
	v_pk_mul_f32 v[84:85], v[84:85], v[166:167] op_sel_hi:[1,0]
	v_pk_mul_f32 v[86:87], v[86:87], v[166:167] op_sel_hi:[1,0]
	v_pk_mul_f32 v[80:81], v[80:81], v[166:167] op_sel_hi:[1,0]
	s_waitcnt lgkmcnt(0)
	v_pk_add_f32 v[170:171], v[170:171], v[184:185]
	ds_bpermute_b32 v185, v163, v171
	ds_bpermute_b32 v184, v163, v170
	v_pk_mul_f32 v[82:83], v[82:83], v[166:167] op_sel_hi:[1,0]
	v_pk_mul_f32 v[76:77], v[76:77], v[164:165] op_sel_hi:[1,0]
	v_pk_mul_f32 v[78:79], v[78:79], v[164:165] op_sel_hi:[1,0]
	v_pk_mul_f32 v[72:73], v[72:73], v[164:165] op_sel_hi:[1,0]
	s_waitcnt lgkmcnt(0)
	v_pk_add_f32 v[170:171], v[170:171], v[184:185]
	ds_bpermute_b32 v185, v165, v171
	ds_bpermute_b32 v184, v165, v170
	v_pk_mul_f32 v[74:75], v[74:75], v[164:165] op_sel_hi:[1,0]
	v_pk_mul_f32 v[68:69], v[68:69], v[164:165] op_sel_hi:[1,0]
	v_pk_mul_f32 v[70:71], v[70:71], v[164:165] op_sel_hi:[1,0]
	v_pk_mul_f32 v[64:65], v[64:65], v[164:165] op_sel_hi:[1,0]
	s_waitcnt lgkmcnt(0)
	v_pk_add_f32 v[170:171], v[170:171], v[184:185]
	ds_bpermute_b32 v185, v167, v171
	ds_bpermute_b32 v184, v167, v170
	v_pk_mul_f32 v[66:67], v[66:67], v[164:165] op_sel_hi:[1,0]
	s_waitcnt lgkmcnt(0)
	v_pk_add_f32 v[170:171], v[170:171], v[184:185]
	ds_bpermute_b32 v185, v168, v171
	ds_bpermute_b32 v184, v168, v170
	s_waitcnt lgkmcnt(0)
	v_pk_add_f32 v[170:171], v[170:171], v[184:185]
	ds_bpermute_b32 v185, v169, v171
	ds_bpermute_b32 v184, v169, v170
	s_waitcnt lgkmcnt(0)
	v_pk_add_f32 v[170:171], v[170:171], v[184:185]
	s_nop 0
	v_pk_fma_f32 v[170:171], v[170:171], s[88:89], v[182:183] op_sel_hi:[1,0,0]
	v_pk_fma_f32 v[182:183], v[128:129], v[94:95], v[2:3]
	v_mul_f32_e32 v160, 0x4b800000, v171
	v_cmp_gt_f32_e64 s[0:1], s91, v171
	v_cmp_gt_f32_e32 vcc, s91, v170
	v_pk_fma_f32 v[184:185], v[130:131], v[92:93], v[0:1]
	v_cndmask_b32_e64 v160, v171, v160, s[0:1]
	v_rsq_f32_e32 v160, v160
	v_cvt_pk_bf16_f32 v184, v184, v185
	v_cvt_pk_bf16_f32 v185, v182, v183
	v_pk_fma_f32 v[182:183], v[136:137], v[90:91], v[6:7]
	v_mul_f32_e32 v162, 0x45800000, v160
	v_cndmask_b32_e64 v162, v160, v162, s[0:1]
	v_mul_f32_e32 v160, 0x4b800000, v170
	v_cndmask_b32_e32 v160, v170, v160, vcc
	v_rsq_f32_e32 v160, v160
	v_pk_fma_f32 v[94:95], v[132:133], v[94:95], v[10:11]
	v_pk_fma_f32 v[92:93], v[134:135], v[92:93], v[8:9]
	v_pk_fma_f32 v[90:91], v[140:141], v[90:91], v[14:15]
	v_mul_f32_e32 v170, 0x45800000, v160
	v_cndmask_b32_e32 v160, v160, v170, vcc
	v_lshl_add_u64 v[170:171], v[112:113], 0, s[20:21]
	global_store_dwordx2 v[170:171], v[184:185], off sc1
	v_pk_fma_f32 v[184:185], v[138:139], v[88:89], v[4:5]
	v_pk_fma_f32 v[88:89], v[142:143], v[88:89], v[12:13]
	v_cvt_pk_bf16_f32 v184, v184, v185
	v_cvt_pk_bf16_f32 v185, v182, v183
	global_store_dwordx2 v[170:171], v[184:185], off offset:512 sc1
	v_pk_fma_f32 v[182:183], v[144:145], v[86:87], v[18:19]
	v_pk_fma_f32 v[184:185], v[146:147], v[84:85], v[16:17]
	v_pk_fma_f32 v[86:87], v[148:149], v[86:87], v[26:27]
	v_cvt_pk_bf16_f32 v184, v184, v185
	v_cvt_pk_bf16_f32 v185, v182, v183
	global_store_dwordx2 v[170:171], v[184:185], off offset:1024 sc1
	v_pk_fma_f32 v[182:183], v[152:153], v[82:83], v[22:23]
	v_pk_fma_f32 v[184:185], v[154:155], v[80:81], v[20:21]
	v_pk_fma_f32 v[84:85], v[150:151], v[84:85], v[24:25]
	v_cvt_pk_bf16_f32 v184, v184, v185
	v_cvt_pk_bf16_f32 v185, v182, v183
	global_store_dwordx2 v[170:171], v[184:185], off offset:1536 sc1
	v_lshl_add_u64 v[170:171], v[114:115], 0, s[20:21]
	v_cvt_pk_bf16_f32 v84, v84, v85
	v_cvt_pk_bf16_f32 v85, v86, v87
	v_pk_fma_f32 v[82:83], v[156:157], v[82:83], v[30:31]
	v_pk_fma_f32 v[80:81], v[158:159], v[80:81], v[28:29]
	global_store_dwordx2 v[170:171], v[84:85], off offset:1024 sc1
	v_cvt_pk_bf16_f32 v80, v80, v81
	v_cvt_pk_bf16_f32 v81, v82, v83
	v_pk_fma_f32 v[82:83], v[128:129], v[78:79], v[2:3]
	v_pk_fma_f32 v[84:85], v[130:131], v[76:77], v[0:1]
	v_cvt_pk_bf16_f32 v92, v92, v93
	v_cvt_pk_bf16_f32 v93, v94, v95
	v_cvt_pk_bf16_f32 v88, v88, v89
	v_cvt_pk_bf16_f32 v89, v90, v91
	global_store_dwordx2 v[170:171], v[80:81], off offset:1536 sc1
	v_lshl_add_u64 v[80:81], v[120:121], 0, s[20:21]
	v_cvt_pk_bf16_f32 v84, v84, v85
	v_cvt_pk_bf16_f32 v85, v82, v83
	global_store_dwordx2 v[170:171], v[92:93], off sc1
	global_store_dwordx2 v[170:171], v[88:89], off offset:512 sc1
	global_store_dwordx2 v[80:81], v[84:85], off sc1
	v_pk_fma_f32 v[82:83], v[136:137], v[74:75], v[6:7]
	v_pk_fma_f32 v[84:85], v[138:139], v[72:73], v[4:5]
	v_pk_mul_f32 v[60:61], v[60:61], v[162:163] op_sel_hi:[1,0]
	v_cvt_pk_bf16_f32 v84, v84, v85
	v_cvt_pk_bf16_f32 v85, v82, v83
	global_store_dwordx2 v[80:81], v[84:85], off offset:512 sc1
	v_pk_fma_f32 v[82:83], v[144:145], v[70:71], v[18:19]
	v_pk_fma_f32 v[84:85], v[146:147], v[68:69], v[16:17]
	v_pk_fma_f32 v[70:71], v[148:149], v[70:71], v[26:27]
	v_cvt_pk_bf16_f32 v84, v84, v85
	v_cvt_pk_bf16_f32 v85, v82, v83
	global_store_dwordx2 v[80:81], v[84:85], off offset:1024 sc1
	v_pk_fma_f32 v[82:83], v[152:153], v[66:67], v[22:23]
	v_pk_fma_f32 v[84:85], v[154:155], v[64:65], v[20:21]
	v_pk_fma_f32 v[68:69], v[150:151], v[68:69], v[24:25]
	v_cvt_pk_bf16_f32 v84, v84, v85
	v_cvt_pk_bf16_f32 v85, v82, v83
	global_store_dwordx2 v[80:81], v[84:85], off offset:1536 sc1
	v_lshl_add_u64 v[80:81], v[122:123], 0, s[20:21]
	v_cvt_pk_bf16_f32 v68, v68, v69
	v_cvt_pk_bf16_f32 v69, v70, v71
	v_pk_fma_f32 v[66:67], v[156:157], v[66:67], v[30:31]
	v_pk_fma_f32 v[64:65], v[158:159], v[64:65], v[28:29]
	v_pk_mul_f32 v[62:63], v[62:63], v[162:163] op_sel_hi:[1,0]
	v_pk_fma_f32 v[78:79], v[132:133], v[78:79], v[10:11]
	v_pk_fma_f32 v[76:77], v[134:135], v[76:77], v[8:9]
	v_pk_fma_f32 v[74:75], v[140:141], v[74:75], v[14:15]
	v_pk_fma_f32 v[72:73], v[142:143], v[72:73], v[12:13]
	global_store_dwordx2 v[80:81], v[68:69], off offset:1024 sc1
	v_cvt_pk_bf16_f32 v64, v64, v65
	v_cvt_pk_bf16_f32 v65, v66, v67
	v_pk_fma_f32 v[66:67], v[128:129], v[62:63], v[2:3]
	v_pk_fma_f32 v[68:69], v[130:131], v[60:61], v[0:1]
	v_cvt_pk_bf16_f32 v76, v76, v77
	v_cvt_pk_bf16_f32 v77, v78, v79
	v_cvt_pk_bf16_f32 v72, v72, v73
	v_cvt_pk_bf16_f32 v73, v74, v75
	global_store_dwordx2 v[80:81], v[64:65], off offset:1536 sc1
	v_lshl_add_u64 v[64:65], v[126:127], 0, s[20:21]
	v_cvt_pk_bf16_f32 v68, v68, v69
	v_cvt_pk_bf16_f32 v69, v66, v67
	v_pk_mul_f32 v[56:57], v[56:57], v[162:163] op_sel_hi:[1,0]
	v_pk_mul_f32 v[58:59], v[58:59], v[162:163] op_sel_hi:[1,0]
	global_store_dwordx2 v[80:81], v[76:77], off sc1
	global_store_dwordx2 v[80:81], v[72:73], off offset:512 sc1
	global_store_dwordx2 v[64:65], v[68:69], off sc1
	v_pk_fma_f32 v[66:67], v[136:137], v[58:59], v[6:7]
	v_pk_fma_f32 v[68:69], v[138:139], v[56:57], v[4:5]
	v_pk_mul_f32 v[52:53], v[52:53], v[162:163] op_sel_hi:[1,0]
	v_cvt_pk_bf16_f32 v68, v68, v69
	v_cvt_pk_bf16_f32 v69, v66, v67
	v_pk_mul_f32 v[54:55], v[54:55], v[162:163] op_sel_hi:[1,0]
	global_store_dwordx2 v[64:65], v[68:69], off offset:512 sc1
	v_pk_fma_f32 v[66:67], v[144:145], v[54:55], v[18:19]
	v_pk_fma_f32 v[68:69], v[146:147], v[52:53], v[16:17]
	v_pk_mul_f32 v[48:49], v[48:49], v[162:163] op_sel_hi:[1,0]
	v_cvt_pk_bf16_f32 v68, v68, v69
	v_cvt_pk_bf16_f32 v69, v66, v67
	v_pk_mul_f32 v[50:51], v[50:51], v[162:163] op_sel_hi:[1,0]
	global_store_dwordx2 v[64:65], v[68:69], off offset:1024 sc1
	v_pk_fma_f32 v[66:67], v[152:153], v[50:51], v[22:23]
	v_pk_fma_f32 v[68:69], v[154:155], v[48:49], v[20:21]
	v_pk_fma_f32 v[54:55], v[148:149], v[54:55], v[26:27]
	v_cvt_pk_bf16_f32 v68, v68, v69
	v_cvt_pk_bf16_f32 v69, v66, v67
	v_pk_fma_f32 v[52:53], v[150:151], v[52:53], v[24:25]
	global_store_dwordx2 v[64:65], v[68:69], off offset:1536 sc1
	v_lshl_add_u64 v[64:65], v[124:125], 0, s[20:21]
	v_cvt_pk_bf16_f32 v52, v52, v53
	v_cvt_pk_bf16_f32 v53, v54, v55
	v_pk_fma_f32 v[50:51], v[156:157], v[50:51], v[30:31]
	v_pk_fma_f32 v[48:49], v[158:159], v[48:49], v[28:29]
	v_pk_mul_f32 v[44:45], v[44:45], v[160:161] op_sel_hi:[1,0]
	v_pk_mul_f32 v[46:47], v[46:47], v[160:161] op_sel_hi:[1,0]
	v_pk_fma_f32 v[62:63], v[132:133], v[62:63], v[10:11]
	v_pk_fma_f32 v[60:61], v[134:135], v[60:61], v[8:9]
	v_pk_fma_f32 v[58:59], v[140:141], v[58:59], v[14:15]
	v_pk_fma_f32 v[56:57], v[142:143], v[56:57], v[12:13]
	global_store_dwordx2 v[64:65], v[52:53], off offset:1024 sc1
	v_cvt_pk_bf16_f32 v48, v48, v49
	v_cvt_pk_bf16_f32 v49, v50, v51
	v_pk_fma_f32 v[50:51], v[128:129], v[46:47], v[2:3]
	v_pk_fma_f32 v[52:53], v[130:131], v[44:45], v[0:1]
	v_cvt_pk_bf16_f32 v60, v60, v61
	v_cvt_pk_bf16_f32 v61, v62, v63
	v_cvt_pk_bf16_f32 v56, v56, v57
	v_cvt_pk_bf16_f32 v57, v58, v59
	global_store_dwordx2 v[64:65], v[48:49], off offset:1536 sc1
	v_lshl_add_u64 v[48:49], v[118:119], 0, s[20:21]
	v_cvt_pk_bf16_f32 v52, v52, v53
	v_cvt_pk_bf16_f32 v53, v50, v51
	v_pk_mul_f32 v[40:41], v[40:41], v[160:161] op_sel_hi:[1,0]
	v_pk_mul_f32 v[42:43], v[42:43], v[160:161] op_sel_hi:[1,0]
	global_store_dwordx2 v[64:65], v[60:61], off sc1
	global_store_dwordx2 v[64:65], v[56:57], off offset:512 sc1
	global_store_dwordx2 v[48:49], v[52:53], off sc1
	v_pk_fma_f32 v[50:51], v[136:137], v[42:43], v[6:7]
	v_pk_fma_f32 v[52:53], v[138:139], v[40:41], v[4:5]
	v_pk_mul_f32 v[36:37], v[36:37], v[160:161] op_sel_hi:[1,0]
	v_cvt_pk_bf16_f32 v52, v52, v53
	v_cvt_pk_bf16_f32 v53, v50, v51
	v_pk_mul_f32 v[38:39], v[38:39], v[160:161] op_sel_hi:[1,0]
	global_store_dwordx2 v[48:49], v[52:53], off offset:512 sc1
	v_pk_fma_f32 v[50:51], v[144:145], v[38:39], v[18:19]
	v_pk_fma_f32 v[52:53], v[146:147], v[36:37], v[16:17]
	v_pk_mul_f32 v[32:33], v[32:33], v[160:161] op_sel_hi:[1,0]
	v_cvt_pk_bf16_f32 v52, v52, v53
	v_cvt_pk_bf16_f32 v53, v50, v51
	v_pk_mul_f32 v[34:35], v[34:35], v[160:161] op_sel_hi:[1,0]
	global_store_dwordx2 v[48:49], v[52:53], off offset:1024 sc1
	v_pk_fma_f32 v[50:51], v[152:153], v[34:35], v[22:23]
	v_pk_fma_f32 v[52:53], v[154:155], v[32:33], v[20:21]
	v_pk_fma_f32 v[46:47], v[132:133], v[46:47], v[10:11]
	v_cvt_pk_bf16_f32 v52, v52, v53
	v_cvt_pk_bf16_f32 v53, v50, v51
	global_store_dwordx2 v[48:49], v[52:53], off offset:1536 sc1
	v_lshl_add_u64 v[48:49], v[116:117], 0, s[20:21]
	s_add_u32 s20, s20, 0x2000
	s_addc_u32 s21, s21, 0
	s_add_u32 s12, s12, 0x4000
	s_addc_u32 s13, s13, 0
	s_add_u32 s14, s14, 0x4000
	s_addc_u32 s15, s15, 0
	s_add_u32 s16, s16, 0x4000
	s_addc_u32 s17, s17, 0
	s_add_u32 s18, s18, 0x4000
	v_pk_fma_f32 v[44:45], v[134:135], v[44:45], v[8:9]
	v_pk_fma_f32 v[42:43], v[140:141], v[42:43], v[14:15]
	v_pk_fma_f32 v[40:41], v[142:143], v[40:41], v[12:13]
	v_pk_fma_f32 v[38:39], v[148:149], v[38:39], v[26:27]
	v_pk_fma_f32 v[36:37], v[150:151], v[36:37], v[24:25]
	v_pk_fma_f32 v[34:35], v[156:157], v[34:35], v[30:31]
	v_pk_fma_f32 v[32:33], v[158:159], v[32:33], v[28:29]
	s_addc_u32 s19, s19, 0
	v_cvt_pk_bf16_f32 v44, v44, v45
	v_cvt_pk_bf16_f32 v45, v46, v47
	v_cvt_pk_bf16_f32 v40, v40, v41
	v_cvt_pk_bf16_f32 v41, v42, v43
	v_cvt_pk_bf16_f32 v36, v36, v37
	v_cvt_pk_bf16_f32 v37, v38, v39
	v_cvt_pk_bf16_f32 v32, v32, v33
	v_cvt_pk_bf16_f32 v33, v34, v35
	s_cmpk_eq_u32 s20, 0x8000
	global_store_dwordx2 v[48:49], v[44:45], off sc1
	global_store_dwordx2 v[48:49], v[40:41], off offset:512 sc1
	global_store_dwordx2 v[48:49], v[36:37], off offset:1024 sc1
	global_store_dwordx2 v[48:49], v[32:33], off offset:1536 sc1
	s_cbranch_scc0 .LBB0_541
	s_add_i32 s26, s26, s58
	s_add_i32 s4, s4, s27
	s_add_i32 s6, s6, s27
	s_add_i32 s8, s8, s27
	s_add_i32 s10, s10, s27
	s_cmpk_gt_i32 s26, 0x7ff
	s_cbranch_scc0 .LBB0_540

.LBB0_572:
	s_andn2_saveexec_b64 s[4:5], s[4:5]
	s_cbranch_execz .LBB0_588
	v_mov_b32_e32 v1, s40
	v_add_co_u32_e32 v2, vcc, 0x3000, v1
	v_mov_b32_e32 v1, s41
	s_waitcnt vmcnt(0)
	v_addc_co_u32_e32 v3, vcc, 0, v1, vcc
	flat_atomic_add v1, v[2:3], v173 offset:1024 sc0
	v_cvt_f32_u32_e32 v2, v0
	v_sub_u32_e32 v3, 0, v0
	s_add_u32 s4, s40, 0x3500
	s_addc_u32 s5, s41, 0
	v_rcp_iflag_f32_e32 v2, v2
	s_mov_b64 s[8:9], -1
	v_mul_f32_e32 v2, 0x4f7ffffe, v2
	v_cvt_u32_f32_e32 v2, v2
	v_mul_lo_u32 v3, v3, v2
	v_mul_hi_u32 v3, v2, v3
	v_add_u32_e32 v2, v2, v3
	s_waitcnt vmcnt(0) lgkmcnt(0)
	v_mul_hi_u32 v2, v1, v2
	v_mul_lo_u32 v3, v2, v0
	v_sub_u32_e32 v3, v1, v3
	v_cmp_ge_u32_e32 vcc, v3, v0
	v_add_u32_e32 v4, 1, v2
	s_nop 0
	v_cndmask_b32_e32 v2, v2, v4, vcc
	v_sub_u32_e32 v4, v3, v0
	v_cndmask_b32_e32 v3, v3, v4, vcc
	v_cmp_ge_u32_e32 vcc, v3, v0
	v_add_u32_e32 v3, 1, v2
	s_nop 0
	v_cndmask_b32_e32 v2, v2, v3, vcc
	v_add_u32_e32 v3, 1, v1
	v_mad_u64_u32 v[0:1], s[6:7], v0, v2, v[0:1]
	v_cmp_ne_u32_e32 vcc, v3, v0
	v_mov_b64_e32 v[0:1], s[4:5]
	s_and_saveexec_b64 s[6:7], vcc
	s_cbranch_execz .LBB0_585
	v_mov_b64_e32 v[0:1], s[4:5]
	flat_load_dword v0, v[0:1] sc1
	s_mov_b64 s[10:11], 0
	s_waitcnt vmcnt(0) lgkmcnt(0)
	v_cmp_eq_u32_e32 vcc, v0, v2
	s_and_saveexec_b64 s[8:9], vcc
	s_cbranch_execz .LBB0_584
	s_mov_b32 s22, 1
	s_branch .LBB0_577
